# GEMM k-loops: 4-stage LDS-DMA ring, both B DMAs of a step pair issued together, one s_barrier per two k-steps
# speedup vs baseline: 1.0064x; 1.0014x over previous
.LBB0_215:
	s_mul_hi_i32 s0, s8, 0x2aaaaaab
	s_lshr_b32 s1, s0, 31
	s_ashr_i32 s0, s0, 5
	s_add_i32 s0, s0, s1
	s_lshl_b32 s1, s0, 3
	s_sub_i32 s2, 17, s1
	s_min_u32 s2, s2, 8
	v_cvt_f32_ubyte0_e32 v0, s2
	v_rcp_iflag_f32_e32 v0, v0
	s_sub_i32 s5, 0, s2
	s_mulk_i32 s0, 0xff40
	s_add_i32 s3, s0, s8
	v_mul_f32_e32 v0, 0x4f7ffffe, v0
	v_cvt_u32_f32_e32 v0, v0
	s_abs_i32 s4, s3
	s_ashr_i32 s0, s3, 31
	v_mov_b32_e32 v181, v179
	v_readfirstlane_b32 s6, v0
	s_mul_i32 s5, s5, s6
	s_mul_hi_u32 s5, s6, s5
	s_add_i32 s6, s6, s5
	s_mul_hi_u32 s5, s4, s6
	s_mul_i32 s6, s5, s2
	s_sub_i32 s4, s4, s6
	s_add_i32 s6, s5, 1
	s_sub_i32 s7, s4, s2
	s_cmp_ge_u32 s4, s2
	s_cselect_b32 s5, s6, s5
	s_cselect_b32 s4, s7, s4
	s_add_i32 s6, s5, 1
	s_cmp_ge_u32 s4, s2
	s_cselect_b32 s4, s6, s5
	s_xor_b32 s4, s4, s0
	s_sub_i32 s0, s4, s0
	s_mul_i32 s2, s2, s0
	s_sub_i32 s2, s3, s2
	s_add_i32 s1, s1, s11
	s_add_i32 s2, s1, s2
	v_ashrrev_i32_e32 v233, 6, v181
	v_lshlrev_b32_e32 v0, 1, v233
	v_lshl_add_u32 v0, s2, 3, v0
	v_ashrrev_i32_e32 v1, 31, v0
	v_bfe_u32 v183, v181, 5, 1
	v_lshlrev_b64 v[0:1], 16, v[0:1]
	v_and_b32_e32 v231, 31, v181
	v_lshl_add_u64 v[0:1], s[64:65], 0, v[0:1]
	v_lshlrev_b32_e32 v176, 9, v183
	s_ashr_i32 s1, s0, 31
	v_lshl_add_u64 v[0:1], v[0:1], 0, v[176:177]
	v_lshlrev_b32_e32 v176, 4, v231
	v_ashrrev_i32_e32 v12, 2, v181
	s_lshl_b64 s[4:5], s[0:1], 18
	v_lshl_add_u64 v[184:185], v[0:1], 0, v[176:177]
	s_add_u32 s4, s9, s4
	v_lshlrev_b32_e32 v0, 5, v12
	s_addc_u32 s5, s10, s5
	v_ashrrev_i32_e32 v1, 31, v0
	v_lshlrev_b32_e32 v2, 4, v181
	v_lshl_add_u64 v[0:1], v[0:1], 1, s[4:5]
	v_and_b32_e32 v176, 48, v2
	v_lshl_add_u64 v[186:187], v[0:1], 0, v[176:177]
	s_movk_i32 s1, 0x2000
	v_add_co_u32_e32 v8, vcc, s1, v186
	v_mul_u32_u24_e32 v10, 40, v231
	s_nop 0
	v_addc_co_u32_e32 v9, vcc, 0, v187, vcc
	v_lshlrev_b32_e32 v11, 4, v183
	v_lshl_add_u32 v235, v10, 1, v11
	v_add_co_u32_e32 v10, vcc, s41, v184
	s_movk_i32 s3, 0x50
	s_nop 0
	v_addc_co_u32_e32 v11, vcc, 0, v185, vcc
	v_and_b32_e32 v232, 63, v181
	v_lshlrev_b32_e32 v234, 3, v181
	v_bfe_u32 v197, v181, 4, 2
	v_lshlrev_b32_e32 v197, 1, v197
	v_mov_b32_e32 v176, 0x78
	v_lshrrev_b32_e32 v197, v197, v176
	v_and_b32_e32 v197, 3, v197
	v_and_b32_e32 v196, 3, v181
	v_xor_b32_e32 v197, v197, v196
	v_lshlrev_b32_e32 v197, 4, v197
	v_and_b32_e32 v188, 0xffffffcf, v186
	v_or_b32_e32 v188, v188, v197
	v_mov_b32_e32 v189, v187
	v_lshrrev_b32_e32 v176, 6, v181
	v_lshlrev_b32_e32 v197, 11, v176
	v_lshlrev_b32_e32 v176, 10, v176
	v_lshl_add_u64 v[188:189], v[188:189], 0, v[176:177]
	v_readfirstlane_b32 vcc_lo, v197
	v_bfe_u32 v197, v181, 4, 1
	v_lshlrev_b32_e32 v176, 9, v183
	v_lshl_add_u32 v176, v197, 8, v176
	v_lshl_add_u64 v[184:185], v[184:185], 0, v[176:177]
	v_mov_b32_e32 v176, s41
	v_lshl_add_u64 v[186:187], v[184:185], 0, v[176:177]
	v_mov_b32_e32 v176, 0x78
	v_bfe_u32 v197, v181, 2, 2
	v_lshlrev_b32_e32 v197, 1, v197
	v_lshrrev_b32_e32 v197, v197, v176
	v_and_b32_e32 v197, 3, v197
	v_bfe_u32 v196, v181, 4, 2
	v_xor_b32_e32 v197, v197, v196
	v_lshlrev_b32_e32 v197, 4, v197
	v_and_b32_e32 v196, 15, v181
	v_lshl_add_u32 v196, v196, 6, v197
	s_mov_b32 s96, 0
	s_mov_b32 m0, vcc_lo
	v_lshl_add_u64 v[160:161], v[188:189], 0, s[96:97]
	global_load_lds_dwordx4 v[160:161], off
	global_load_lds_dwordx4 v[160:161], off offset:1024
	s_movk_i32 s96, 0x2000
	s_add_i32 m0, vcc_lo, 8192
	v_lshl_add_u64 v[160:161], v[188:189], 0, s[96:97]
	global_load_lds_dwordx4 v[160:161], off
	global_load_lds_dwordx4 v[160:161], off offset:1024
	s_mov_b32 s96, 0
	v_lshl_add_u64 v[198:199], v[184:185], 0, s[96:97]
	v_lshl_add_u64 v[200:201], v[186:187], 0, s[96:97]
	global_load_dwordx4 v[128:131], v[198:199], off
	global_load_dwordx4 v[132:135], v[198:199], off offset:256
	global_load_dwordx4 v[136:139], v[200:201], off
	global_load_dwordx4 v[140:143], v[200:201], off offset:256
	s_movk_i32 s96, 0x800
	v_lshl_add_u64 v[198:199], v[184:185], 0, s[96:97]
	v_lshl_add_u64 v[200:201], v[186:187], 0, s[96:97]
	global_load_dwordx4 v[144:147], v[198:199], off
	global_load_dwordx4 v[148:151], v[198:199], off offset:256
	global_load_dwordx4 v[152:155], v[200:201], off
	global_load_dwordx4 v[156:159], v[200:201], off offset:256
	v_mov_b32_e32 v0, 0
	v_mov_b32_e32 v1, 0
	v_mov_b32_e32 v2, 0
	v_mov_b32_e32 v3, 0
	v_mov_b32_e32 v4, 0
	v_mov_b32_e32 v5, 0
	v_mov_b32_e32 v6, 0
	v_mov_b32_e32 v7, 0
	v_mov_b32_e32 v8, 0
	v_mov_b32_e32 v9, 0
	v_mov_b32_e32 v10, 0
	v_mov_b32_e32 v11, 0
	v_mov_b32_e32 v12, 0
	v_mov_b32_e32 v13, 0
	v_mov_b32_e32 v14, 0
	v_mov_b32_e32 v15, 0
	v_mov_b32_e32 v16, 0
	v_mov_b32_e32 v17, 0
	v_mov_b32_e32 v18, 0
	v_mov_b32_e32 v19, 0
	v_mov_b32_e32 v20, 0
	v_mov_b32_e32 v21, 0
	v_mov_b32_e32 v22, 0
	v_mov_b32_e32 v23, 0
	v_mov_b32_e32 v24, 0
	v_mov_b32_e32 v25, 0
	v_mov_b32_e32 v26, 0
	v_mov_b32_e32 v27, 0
	v_mov_b32_e32 v28, 0
	v_mov_b32_e32 v29, 0
	v_mov_b32_e32 v30, 0
	v_mov_b32_e32 v31, 0
	v_mov_b32_e32 v32, 0
	v_mov_b32_e32 v33, 0
	v_mov_b32_e32 v34, 0
	v_mov_b32_e32 v35, 0
	v_mov_b32_e32 v36, 0
	v_mov_b32_e32 v37, 0
	v_mov_b32_e32 v38, 0
	v_mov_b32_e32 v39, 0
	v_mov_b32_e32 v40, 0
	v_mov_b32_e32 v41, 0
	v_mov_b32_e32 v42, 0
	v_mov_b32_e32 v43, 0
	v_mov_b32_e32 v44, 0
	v_mov_b32_e32 v45, 0
	v_mov_b32_e32 v46, 0
	v_mov_b32_e32 v47, 0
	v_mov_b32_e32 v48, 0
	v_mov_b32_e32 v49, 0
	v_mov_b32_e32 v50, 0
	v_mov_b32_e32 v51, 0
	v_mov_b32_e32 v52, 0
	v_mov_b32_e32 v53, 0
	v_mov_b32_e32 v54, 0
	v_mov_b32_e32 v55, 0
	v_mov_b32_e32 v56, 0
	v_mov_b32_e32 v57, 0
	v_mov_b32_e32 v58, 0
	v_mov_b32_e32 v59, 0
	v_mov_b32_e32 v60, 0
	v_mov_b32_e32 v61, 0
	v_mov_b32_e32 v62, 0
	v_mov_b32_e32 v63, 0
	v_mov_b32_e32 v64, 0
	v_mov_b32_e32 v65, 0
	v_mov_b32_e32 v66, 0
	v_mov_b32_e32 v67, 0
	v_mov_b32_e32 v68, 0
	v_mov_b32_e32 v69, 0
	v_mov_b32_e32 v70, 0
	v_mov_b32_e32 v71, 0
	v_mov_b32_e32 v72, 0
	v_mov_b32_e32 v73, 0
	v_mov_b32_e32 v74, 0
	v_mov_b32_e32 v75, 0
	v_mov_b32_e32 v76, 0
	v_mov_b32_e32 v77, 0
	v_mov_b32_e32 v78, 0
	v_mov_b32_e32 v79, 0
	v_mov_b32_e32 v80, 0
	v_mov_b32_e32 v81, 0
	v_mov_b32_e32 v82, 0
	v_mov_b32_e32 v83, 0
	v_mov_b32_e32 v84, 0
	v_mov_b32_e32 v85, 0
	v_mov_b32_e32 v86, 0
	v_mov_b32_e32 v87, 0
	v_mov_b32_e32 v88, 0
	v_mov_b32_e32 v89, 0
	v_mov_b32_e32 v90, 0
	v_mov_b32_e32 v91, 0
	v_mov_b32_e32 v92, 0
	v_mov_b32_e32 v93, 0
	v_mov_b32_e32 v94, 0
	v_mov_b32_e32 v95, 0
	v_mov_b32_e32 v96, 0
	v_mov_b32_e32 v97, 0
	v_mov_b32_e32 v98, 0
	v_mov_b32_e32 v99, 0
	v_mov_b32_e32 v100, 0
	v_mov_b32_e32 v101, 0
	v_mov_b32_e32 v102, 0
	v_mov_b32_e32 v103, 0
	v_mov_b32_e32 v104, 0
	v_mov_b32_e32 v105, 0
	v_mov_b32_e32 v106, 0
	v_mov_b32_e32 v107, 0
	v_mov_b32_e32 v108, 0
	v_mov_b32_e32 v109, 0
	v_mov_b32_e32 v110, 0
	v_mov_b32_e32 v111, 0
	v_mov_b32_e32 v112, 0
	v_mov_b32_e32 v113, 0
	v_mov_b32_e32 v114, 0
	v_mov_b32_e32 v115, 0
	v_mov_b32_e32 v116, 0
	v_mov_b32_e32 v117, 0
	v_mov_b32_e32 v118, 0
	v_mov_b32_e32 v119, 0
	v_mov_b32_e32 v120, 0
	v_mov_b32_e32 v121, 0
	v_mov_b32_e32 v122, 0
	v_mov_b32_e32 v123, 0
	v_mov_b32_e32 v124, 0
	v_mov_b32_e32 v125, 0
	v_mov_b32_e32 v126, 0
	v_mov_b32_e32 v127, 0
	s_mov_b32 s1, 0
	s_waitcnt vmcnt(4)
	s_barrier
.Lg16_proj_k:
	s_add_i32 s3, s1, 2
	s_lshl_b32 s96, s3, 13
	s_add_i32 m0, vcc_lo, 16384
	v_lshl_add_u64 v[160:161], v[188:189], 0, s[96:97]
	global_load_lds_dwordx4 v[160:161], off
	global_load_lds_dwordx4 v[160:161], off offset:1024
	s_add_i32 s3, s1, 3
	s_lshl_b32 s96, s3, 13
	s_add_i32 m0, vcc_lo, 24576
	v_lshl_add_u64 v[160:161], v[188:189], 0, s[96:97]
	global_load_lds_dwordx4 v[160:161], off
	global_load_lds_dwordx4 v[160:161], off offset:1024
	ds_read_b128 v[236:239], v196 offset:0
	ds_read_b128 v[240:243], v196 offset:1024
	ds_read_b128 v[244:247], v196 offset:2048
	ds_read_b128 v[248:251], v196 offset:3072
	s_add_i32 s3, s1, 2
	s_lshl_b32 s96, s3, 11
	v_lshl_add_u64 v[198:199], v[184:185], 0, s[96:97]
	v_lshl_add_u64 v[200:201], v[186:187], 0, s[96:97]
	s_waitcnt vmcnt(8) lgkmcnt(3)
	v_mfma_f32_16x16x32_bf16 v[16:19], v[128:131], v[236:239], v[16:19]
	v_mfma_f32_16x16x32_bf16 v[24:27], v[132:135], v[236:239], v[24:27]
	v_mfma_f32_16x16x32_bf16 v[0:3], v[136:139], v[236:239], v[0:3]
	v_mfma_f32_16x16x32_bf16 v[8:11], v[140:143], v[236:239], v[8:11]
	ds_read_b128 v[236:239], v196 offset:4096
	s_waitcnt lgkmcnt(3)
	v_mfma_f32_16x16x32_bf16 v[20:23], v[128:131], v[240:243], v[20:23]
	v_mfma_f32_16x16x32_bf16 v[28:31], v[132:135], v[240:243], v[28:31]
	v_mfma_f32_16x16x32_bf16 v[4:7], v[136:139], v[240:243], v[4:7]
	v_mfma_f32_16x16x32_bf16 v[12:15], v[140:143], v[240:243], v[12:15]
	ds_read_b128 v[240:243], v196 offset:5120
	s_waitcnt lgkmcnt(3)
	v_mfma_f32_16x16x32_bf16 v[112:115], v[128:131], v[244:247], v[112:115]
	v_mfma_f32_16x16x32_bf16 v[120:123], v[132:135], v[244:247], v[120:123]
	v_mfma_f32_16x16x32_bf16 v[96:99], v[136:139], v[244:247], v[96:99]
	v_mfma_f32_16x16x32_bf16 v[104:107], v[140:143], v[244:247], v[104:107]
	ds_read_b128 v[244:247], v196 offset:6144
	s_waitcnt lgkmcnt(3)
	v_mfma_f32_16x16x32_bf16 v[116:119], v[128:131], v[248:251], v[116:119]
	v_mfma_f32_16x16x32_bf16 v[124:127], v[132:135], v[248:251], v[124:127]
	v_mfma_f32_16x16x32_bf16 v[100:103], v[136:139], v[248:251], v[100:103]
	v_mfma_f32_16x16x32_bf16 v[108:111], v[140:143], v[248:251], v[108:111]
	ds_read_b128 v[248:251], v196 offset:7168
	s_waitcnt lgkmcnt(3)
	v_mfma_f32_16x16x32_bf16 v[80:83], v[128:131], v[236:239], v[80:83]
	v_mfma_f32_16x16x32_bf16 v[88:91], v[132:135], v[236:239], v[88:91]
	v_mfma_f32_16x16x32_bf16 v[48:51], v[136:139], v[236:239], v[48:51]
	v_mfma_f32_16x16x32_bf16 v[56:59], v[140:143], v[236:239], v[56:59]
	s_waitcnt lgkmcnt(2)
	v_mfma_f32_16x16x32_bf16 v[84:87], v[128:131], v[240:243], v[84:87]
	v_mfma_f32_16x16x32_bf16 v[92:95], v[132:135], v[240:243], v[92:95]
	v_mfma_f32_16x16x32_bf16 v[52:55], v[136:139], v[240:243], v[52:55]
	v_mfma_f32_16x16x32_bf16 v[60:63], v[140:143], v[240:243], v[60:63]
	s_waitcnt lgkmcnt(1)
	v_mfma_f32_16x16x32_bf16 v[64:67], v[128:131], v[244:247], v[64:67]
	v_mfma_f32_16x16x32_bf16 v[72:75], v[132:135], v[244:247], v[72:75]
	v_mfma_f32_16x16x32_bf16 v[32:35], v[136:139], v[244:247], v[32:35]
	v_mfma_f32_16x16x32_bf16 v[40:43], v[140:143], v[244:247], v[40:43]
	s_waitcnt lgkmcnt(0)
	v_mfma_f32_16x16x32_bf16 v[68:71], v[128:131], v[248:251], v[68:71]
	v_mfma_f32_16x16x32_bf16 v[76:79], v[132:135], v[248:251], v[76:79]
	v_mfma_f32_16x16x32_bf16 v[36:39], v[136:139], v[248:251], v[36:39]
	v_mfma_f32_16x16x32_bf16 v[44:47], v[140:143], v[248:251], v[44:47]
	global_load_dwordx4 v[128:131], v[198:199], off
	global_load_dwordx4 v[132:135], v[198:199], off offset:256
	global_load_dwordx4 v[136:139], v[200:201], off
	global_load_dwordx4 v[140:143], v[200:201], off offset:256
	ds_read_b128 v[236:239], v196 offset:8192
	ds_read_b128 v[240:243], v196 offset:9216
	ds_read_b128 v[244:247], v196 offset:10240
	ds_read_b128 v[248:251], v196 offset:11264
	s_add_i32 s3, s1, 3
	s_lshl_b32 s96, s3, 11
	v_lshl_add_u64 v[198:199], v[184:185], 0, s[96:97]
	v_lshl_add_u64 v[200:201], v[186:187], 0, s[96:97]
	s_waitcnt vmcnt(8) lgkmcnt(3)
	v_mfma_f32_16x16x32_bf16 v[16:19], v[144:147], v[236:239], v[16:19]
	v_mfma_f32_16x16x32_bf16 v[24:27], v[148:151], v[236:239], v[24:27]
	v_mfma_f32_16x16x32_bf16 v[0:3], v[152:155], v[236:239], v[0:3]
	v_mfma_f32_16x16x32_bf16 v[8:11], v[156:159], v[236:239], v[8:11]
	ds_read_b128 v[236:239], v196 offset:12288
	s_waitcnt lgkmcnt(3)
	v_mfma_f32_16x16x32_bf16 v[20:23], v[144:147], v[240:243], v[20:23]
	v_mfma_f32_16x16x32_bf16 v[28:31], v[148:151], v[240:243], v[28:31]
	v_mfma_f32_16x16x32_bf16 v[4:7], v[152:155], v[240:243], v[4:7]
	v_mfma_f32_16x16x32_bf16 v[12:15], v[156:159], v[240:243], v[12:15]
	ds_read_b128 v[240:243], v196 offset:13312
	s_waitcnt lgkmcnt(3)
	v_mfma_f32_16x16x32_bf16 v[112:115], v[144:147], v[244:247], v[112:115]
	v_mfma_f32_16x16x32_bf16 v[120:123], v[148:151], v[244:247], v[120:123]
	v_mfma_f32_16x16x32_bf16 v[96:99], v[152:155], v[244:247], v[96:99]
	v_mfma_f32_16x16x32_bf16 v[104:107], v[156:159], v[244:247], v[104:107]
	ds_read_b128 v[244:247], v196 offset:14336
	s_waitcnt lgkmcnt(3)
	v_mfma_f32_16x16x32_bf16 v[116:119], v[144:147], v[248:251], v[116:119]
	v_mfma_f32_16x16x32_bf16 v[124:127], v[148:151], v[248:251], v[124:127]
	v_mfma_f32_16x16x32_bf16 v[100:103], v[152:155], v[248:251], v[100:103]
	v_mfma_f32_16x16x32_bf16 v[108:111], v[156:159], v[248:251], v[108:111]
	ds_read_b128 v[248:251], v196 offset:15360
	s_waitcnt lgkmcnt(3)
	v_mfma_f32_16x16x32_bf16 v[80:83], v[144:147], v[236:239], v[80:83]
	v_mfma_f32_16x16x32_bf16 v[88:91], v[148:151], v[236:239], v[88:91]
	v_mfma_f32_16x16x32_bf16 v[48:51], v[152:155], v[236:239], v[48:51]
	v_mfma_f32_16x16x32_bf16 v[56:59], v[156:159], v[236:239], v[56:59]
	s_waitcnt lgkmcnt(2)
	v_mfma_f32_16x16x32_bf16 v[84:87], v[144:147], v[240:243], v[84:87]
	v_mfma_f32_16x16x32_bf16 v[92:95], v[148:151], v[240:243], v[92:95]
	v_mfma_f32_16x16x32_bf16 v[52:55], v[152:155], v[240:243], v[52:55]
	v_mfma_f32_16x16x32_bf16 v[60:63], v[156:159], v[240:243], v[60:63]
	s_waitcnt lgkmcnt(1)
	v_mfma_f32_16x16x32_bf16 v[64:67], v[144:147], v[244:247], v[64:67]
	v_mfma_f32_16x16x32_bf16 v[72:75], v[148:151], v[244:247], v[72:75]
	v_mfma_f32_16x16x32_bf16 v[32:35], v[152:155], v[244:247], v[32:35]
	v_mfma_f32_16x16x32_bf16 v[40:43], v[156:159], v[244:247], v[40:43]
	s_waitcnt lgkmcnt(0)
	v_mfma_f32_16x16x32_bf16 v[68:71], v[144:147], v[248:251], v[68:71]
	v_mfma_f32_16x16x32_bf16 v[76:79], v[148:151], v[248:251], v[76:79]
	v_mfma_f32_16x16x32_bf16 v[36:39], v[152:155], v[248:251], v[36:39]
	v_mfma_f32_16x16x32_bf16 v[44:47], v[156:159], v[248:251], v[44:47]
	global_load_dwordx4 v[144:147], v[198:199], off
	global_load_dwordx4 v[148:151], v[198:199], off offset:256
	global_load_dwordx4 v[152:155], v[200:201], off
	global_load_dwordx4 v[156:159], v[200:201], off offset:256
	s_waitcnt vmcnt(8)
	s_barrier
	s_add_i32 s3, s1, 4
	s_lshl_b32 s96, s3, 13
	s_mov_b32 m0, vcc_lo
	v_lshl_add_u64 v[160:161], v[188:189], 0, s[96:97]
	global_load_lds_dwordx4 v[160:161], off
	global_load_lds_dwordx4 v[160:161], off offset:1024
	s_add_i32 s3, s1, 5
	s_lshl_b32 s96, s3, 13
	s_add_i32 m0, vcc_lo, 8192
	v_lshl_add_u64 v[160:161], v[188:189], 0, s[96:97]
	global_load_lds_dwordx4 v[160:161], off
	global_load_lds_dwordx4 v[160:161], off offset:1024
	ds_read_b128 v[236:239], v196 offset:16384
	ds_read_b128 v[240:243], v196 offset:17408
	ds_read_b128 v[244:247], v196 offset:18432
	ds_read_b128 v[248:251], v196 offset:19456
	s_add_i32 s3, s1, 4
	s_lshl_b32 s96, s3, 11
	v_lshl_add_u64 v[198:199], v[184:185], 0, s[96:97]
	v_lshl_add_u64 v[200:201], v[186:187], 0, s[96:97]
	s_waitcnt vmcnt(8) lgkmcnt(3)
	v_mfma_f32_16x16x32_bf16 v[16:19], v[128:131], v[236:239], v[16:19]
	v_mfma_f32_16x16x32_bf16 v[24:27], v[132:135], v[236:239], v[24:27]
	v_mfma_f32_16x16x32_bf16 v[0:3], v[136:139], v[236:239], v[0:3]
	v_mfma_f32_16x16x32_bf16 v[8:11], v[140:143], v[236:239], v[8:11]
	ds_read_b128 v[236:239], v196 offset:20480
	s_waitcnt lgkmcnt(3)
	v_mfma_f32_16x16x32_bf16 v[20:23], v[128:131], v[240:243], v[20:23]
	v_mfma_f32_16x16x32_bf16 v[28:31], v[132:135], v[240:243], v[28:31]
	v_mfma_f32_16x16x32_bf16 v[4:7], v[136:139], v[240:243], v[4:7]
	v_mfma_f32_16x16x32_bf16 v[12:15], v[140:143], v[240:243], v[12:15]
	ds_read_b128 v[240:243], v196 offset:21504
	s_waitcnt lgkmcnt(3)
	v_mfma_f32_16x16x32_bf16 v[112:115], v[128:131], v[244:247], v[112:115]
	v_mfma_f32_16x16x32_bf16 v[120:123], v[132:135], v[244:247], v[120:123]
	v_mfma_f32_16x16x32_bf16 v[96:99], v[136:139], v[244:247], v[96:99]
	v_mfma_f32_16x16x32_bf16 v[104:107], v[140:143], v[244:247], v[104:107]
	ds_read_b128 v[244:247], v196 offset:22528
	s_waitcnt lgkmcnt(3)
	v_mfma_f32_16x16x32_bf16 v[116:119], v[128:131], v[248:251], v[116:119]
	v_mfma_f32_16x16x32_bf16 v[124:127], v[132:135], v[248:251], v[124:127]
	v_mfma_f32_16x16x32_bf16 v[100:103], v[136:139], v[248:251], v[100:103]
	v_mfma_f32_16x16x32_bf16 v[108:111], v[140:143], v[248:251], v[108:111]
	ds_read_b128 v[248:251], v196 offset:23552
	s_waitcnt lgkmcnt(3)
	v_mfma_f32_16x16x32_bf16 v[80:83], v[128:131], v[236:239], v[80:83]
	v_mfma_f32_16x16x32_bf16 v[88:91], v[132:135], v[236:239], v[88:91]
	v_mfma_f32_16x16x32_bf16 v[48:51], v[136:139], v[236:239], v[48:51]
	v_mfma_f32_16x16x32_bf16 v[56:59], v[140:143], v[236:239], v[56:59]
	s_waitcnt lgkmcnt(2)
	v_mfma_f32_16x16x32_bf16 v[84:87], v[128:131], v[240:243], v[84:87]
	v_mfma_f32_16x16x32_bf16 v[92:95], v[132:135], v[240:243], v[92:95]
	v_mfma_f32_16x16x32_bf16 v[52:55], v[136:139], v[240:243], v[52:55]
	v_mfma_f32_16x16x32_bf16 v[60:63], v[140:143], v[240:243], v[60:63]
	s_waitcnt lgkmcnt(1)
	v_mfma_f32_16x16x32_bf16 v[64:67], v[128:131], v[244:247], v[64:67]
	v_mfma_f32_16x16x32_bf16 v[72:75], v[132:135], v[244:247], v[72:75]
	v_mfma_f32_16x16x32_bf16 v[32:35], v[136:139], v[244:247], v[32:35]
	v_mfma_f32_16x16x32_bf16 v[40:43], v[140:143], v[244:247], v[40:43]
	s_waitcnt lgkmcnt(0)
	v_mfma_f32_16x16x32_bf16 v[68:71], v[128:131], v[248:251], v[68:71]
	v_mfma_f32_16x16x32_bf16 v[76:79], v[132:135], v[248:251], v[76:79]
	v_mfma_f32_16x16x32_bf16 v[36:39], v[136:139], v[248:251], v[36:39]
	v_mfma_f32_16x16x32_bf16 v[44:47], v[140:143], v[248:251], v[44:47]
	global_load_dwordx4 v[128:131], v[198:199], off
	global_load_dwordx4 v[132:135], v[198:199], off offset:256
	global_load_dwordx4 v[136:139], v[200:201], off
	global_load_dwordx4 v[140:143], v[200:201], off offset:256
	ds_read_b128 v[236:239], v196 offset:24576
	ds_read_b128 v[240:243], v196 offset:25600
	ds_read_b128 v[244:247], v196 offset:26624
	ds_read_b128 v[248:251], v196 offset:27648
	s_add_i32 s3, s1, 5
	s_lshl_b32 s96, s3, 11
	v_lshl_add_u64 v[198:199], v[184:185], 0, s[96:97]
	v_lshl_add_u64 v[200:201], v[186:187], 0, s[96:97]
	s_waitcnt vmcnt(8) lgkmcnt(3)
	v_mfma_f32_16x16x32_bf16 v[16:19], v[144:147], v[236:239], v[16:19]
	v_mfma_f32_16x16x32_bf16 v[24:27], v[148:151], v[236:239], v[24:27]
	v_mfma_f32_16x16x32_bf16 v[0:3], v[152:155], v[236:239], v[0:3]
	v_mfma_f32_16x16x32_bf16 v[8:11], v[156:159], v[236:239], v[8:11]
	ds_read_b128 v[236:239], v196 offset:28672
	s_waitcnt lgkmcnt(3)
	v_mfma_f32_16x16x32_bf16 v[20:23], v[144:147], v[240:243], v[20:23]
	v_mfma_f32_16x16x32_bf16 v[28:31], v[148:151], v[240:243], v[28:31]
	v_mfma_f32_16x16x32_bf16 v[4:7], v[152:155], v[240:243], v[4:7]
	v_mfma_f32_16x16x32_bf16 v[12:15], v[156:159], v[240:243], v[12:15]
	ds_read_b128 v[240:243], v196 offset:29696
	s_waitcnt lgkmcnt(3)
	v_mfma_f32_16x16x32_bf16 v[112:115], v[144:147], v[244:247], v[112:115]
	v_mfma_f32_16x16x32_bf16 v[120:123], v[148:151], v[244:247], v[120:123]
	v_mfma_f32_16x16x32_bf16 v[96:99], v[152:155], v[244:247], v[96:99]
	v_mfma_f32_16x16x32_bf16 v[104:107], v[156:159], v[244:247], v[104:107]
	ds_read_b128 v[244:247], v196 offset:30720
	s_waitcnt lgkmcnt(3)
	v_mfma_f32_16x16x32_bf16 v[116:119], v[144:147], v[248:251], v[116:119]
	v_mfma_f32_16x16x32_bf16 v[124:127], v[148:151], v[248:251], v[124:127]
	v_mfma_f32_16x16x32_bf16 v[100:103], v[152:155], v[248:251], v[100:103]
	v_mfma_f32_16x16x32_bf16 v[108:111], v[156:159], v[248:251], v[108:111]
	ds_read_b128 v[248:251], v196 offset:31744
	s_waitcnt lgkmcnt(3)
	v_mfma_f32_16x16x32_bf16 v[80:83], v[144:147], v[236:239], v[80:83]
	v_mfma_f32_16x16x32_bf16 v[88:91], v[148:151], v[236:239], v[88:91]
	v_mfma_f32_16x16x32_bf16 v[48:51], v[152:155], v[236:239], v[48:51]
	v_mfma_f32_16x16x32_bf16 v[56:59], v[156:159], v[236:239], v[56:59]
	s_waitcnt lgkmcnt(2)
	v_mfma_f32_16x16x32_bf16 v[84:87], v[144:147], v[240:243], v[84:87]
	v_mfma_f32_16x16x32_bf16 v[92:95], v[148:151], v[240:243], v[92:95]
	v_mfma_f32_16x16x32_bf16 v[52:55], v[152:155], v[240:243], v[52:55]
	v_mfma_f32_16x16x32_bf16 v[60:63], v[156:159], v[240:243], v[60:63]
	s_waitcnt lgkmcnt(1)
	v_mfma_f32_16x16x32_bf16 v[64:67], v[144:147], v[244:247], v[64:67]
	v_mfma_f32_16x16x32_bf16 v[72:75], v[148:151], v[244:247], v[72:75]
	v_mfma_f32_16x16x32_bf16 v[32:35], v[152:155], v[244:247], v[32:35]
	v_mfma_f32_16x16x32_bf16 v[40:43], v[156:159], v[244:247], v[40:43]
	s_waitcnt lgkmcnt(0)
	v_mfma_f32_16x16x32_bf16 v[68:71], v[144:147], v[248:251], v[68:71]
	v_mfma_f32_16x16x32_bf16 v[76:79], v[148:151], v[248:251], v[76:79]
	v_mfma_f32_16x16x32_bf16 v[36:39], v[152:155], v[248:251], v[36:39]
	v_mfma_f32_16x16x32_bf16 v[44:47], v[156:159], v[248:251], v[44:47]
	global_load_dwordx4 v[144:147], v[198:199], off
	global_load_dwordx4 v[148:151], v[198:199], off offset:256
	global_load_dwordx4 v[152:155], v[200:201], off
	global_load_dwordx4 v[156:159], v[200:201], off offset:256
	s_waitcnt vmcnt(8)
	s_barrier
	s_add_i32 s1, s1, 4
	s_cmp_lt_u32 s1, 28
	s_cbranch_scc1 .Lg16_proj_k
	s_mov_b32 s96, 0x3c000
	s_add_i32 m0, vcc_lo, 16384
	v_lshl_add_u64 v[160:161], v[188:189], 0, s[96:97]
	global_load_lds_dwordx4 v[160:161], off
	global_load_lds_dwordx4 v[160:161], off offset:1024
	s_mov_b32 s96, 0x3e000
	s_add_i32 m0, vcc_lo, 24576
	v_lshl_add_u64 v[160:161], v[188:189], 0, s[96:97]
	global_load_lds_dwordx4 v[160:161], off
	global_load_lds_dwordx4 v[160:161], off offset:1024
	ds_read_b128 v[236:239], v196 offset:0
	ds_read_b128 v[240:243], v196 offset:1024
	ds_read_b128 v[244:247], v196 offset:2048
	ds_read_b128 v[248:251], v196 offset:3072
	s_mov_b32 s96, 0xf000
	v_lshl_add_u64 v[198:199], v[184:185], 0, s[96:97]
	v_lshl_add_u64 v[200:201], v[186:187], 0, s[96:97]
	s_waitcnt vmcnt(8) lgkmcnt(3)
	v_mfma_f32_16x16x32_bf16 v[16:19], v[128:131], v[236:239], v[16:19]
	v_mfma_f32_16x16x32_bf16 v[24:27], v[132:135], v[236:239], v[24:27]
	v_mfma_f32_16x16x32_bf16 v[0:3], v[136:139], v[236:239], v[0:3]
	v_mfma_f32_16x16x32_bf16 v[8:11], v[140:143], v[236:239], v[8:11]
	ds_read_b128 v[236:239], v196 offset:4096
	s_waitcnt lgkmcnt(3)
	v_mfma_f32_16x16x32_bf16 v[20:23], v[128:131], v[240:243], v[20:23]
	v_mfma_f32_16x16x32_bf16 v[28:31], v[132:135], v[240:243], v[28:31]
	v_mfma_f32_16x16x32_bf16 v[4:7], v[136:139], v[240:243], v[4:7]
	v_mfma_f32_16x16x32_bf16 v[12:15], v[140:143], v[240:243], v[12:15]
	ds_read_b128 v[240:243], v196 offset:5120
	s_waitcnt lgkmcnt(3)
	v_mfma_f32_16x16x32_bf16 v[112:115], v[128:131], v[244:247], v[112:115]
	v_mfma_f32_16x16x32_bf16 v[120:123], v[132:135], v[244:247], v[120:123]
	v_mfma_f32_16x16x32_bf16 v[96:99], v[136:139], v[244:247], v[96:99]
	v_mfma_f32_16x16x32_bf16 v[104:107], v[140:143], v[244:247], v[104:107]
	ds_read_b128 v[244:247], v196 offset:6144
	s_waitcnt lgkmcnt(3)
	v_mfma_f32_16x16x32_bf16 v[116:119], v[128:131], v[248:251], v[116:119]
	v_mfma_f32_16x16x32_bf16 v[124:127], v[132:135], v[248:251], v[124:127]
	v_mfma_f32_16x16x32_bf16 v[100:103], v[136:139], v[248:251], v[100:103]
	v_mfma_f32_16x16x32_bf16 v[108:111], v[140:143], v[248:251], v[108:111]
	ds_read_b128 v[248:251], v196 offset:7168
	s_waitcnt lgkmcnt(3)
	v_mfma_f32_16x16x32_bf16 v[80:83], v[128:131], v[236:239], v[80:83]
	v_mfma_f32_16x16x32_bf16 v[88:91], v[132:135], v[236:239], v[88:91]
	v_mfma_f32_16x16x32_bf16 v[48:51], v[136:139], v[236:239], v[48:51]
	v_mfma_f32_16x16x32_bf16 v[56:59], v[140:143], v[236:239], v[56:59]
	s_waitcnt lgkmcnt(2)
	v_mfma_f32_16x16x32_bf16 v[84:87], v[128:131], v[240:243], v[84:87]
	v_mfma_f32_16x16x32_bf16 v[92:95], v[132:135], v[240:243], v[92:95]
	v_mfma_f32_16x16x32_bf16 v[52:55], v[136:139], v[240:243], v[52:55]
	v_mfma_f32_16x16x32_bf16 v[60:63], v[140:143], v[240:243], v[60:63]
	s_waitcnt lgkmcnt(1)
	v_mfma_f32_16x16x32_bf16 v[64:67], v[128:131], v[244:247], v[64:67]
	v_mfma_f32_16x16x32_bf16 v[72:75], v[132:135], v[244:247], v[72:75]
	v_mfma_f32_16x16x32_bf16 v[32:35], v[136:139], v[244:247], v[32:35]
	v_mfma_f32_16x16x32_bf16 v[40:43], v[140:143], v[244:247], v[40:43]
	s_waitcnt lgkmcnt(0)
	v_mfma_f32_16x16x32_bf16 v[68:71], v[128:131], v[248:251], v[68:71]
	v_mfma_f32_16x16x32_bf16 v[76:79], v[132:135], v[248:251], v[76:79]
	v_mfma_f32_16x16x32_bf16 v[36:39], v[136:139], v[248:251], v[36:39]
	v_mfma_f32_16x16x32_bf16 v[44:47], v[140:143], v[248:251], v[44:47]
	global_load_dwordx4 v[128:131], v[198:199], off
	global_load_dwordx4 v[132:135], v[198:199], off offset:256
	global_load_dwordx4 v[136:139], v[200:201], off
	global_load_dwordx4 v[140:143], v[200:201], off offset:256
	ds_read_b128 v[236:239], v196 offset:8192
	ds_read_b128 v[240:243], v196 offset:9216
	ds_read_b128 v[244:247], v196 offset:10240
	ds_read_b128 v[248:251], v196 offset:11264
	s_mov_b32 s96, 0xf800
	v_lshl_add_u64 v[198:199], v[184:185], 0, s[96:97]
	v_lshl_add_u64 v[200:201], v[186:187], 0, s[96:97]
	s_waitcnt vmcnt(8) lgkmcnt(3)
	v_mfma_f32_16x16x32_bf16 v[16:19], v[144:147], v[236:239], v[16:19]
	v_mfma_f32_16x16x32_bf16 v[24:27], v[148:151], v[236:239], v[24:27]
	v_mfma_f32_16x16x32_bf16 v[0:3], v[152:155], v[236:239], v[0:3]
	v_mfma_f32_16x16x32_bf16 v[8:11], v[156:159], v[236:239], v[8:11]
	ds_read_b128 v[236:239], v196 offset:12288
	s_waitcnt lgkmcnt(3)
	v_mfma_f32_16x16x32_bf16 v[20:23], v[144:147], v[240:243], v[20:23]
	v_mfma_f32_16x16x32_bf16 v[28:31], v[148:151], v[240:243], v[28:31]
	v_mfma_f32_16x16x32_bf16 v[4:7], v[152:155], v[240:243], v[4:7]
	v_mfma_f32_16x16x32_bf16 v[12:15], v[156:159], v[240:243], v[12:15]
	ds_read_b128 v[240:243], v196 offset:13312
	s_waitcnt lgkmcnt(3)
	v_mfma_f32_16x16x32_bf16 v[112:115], v[144:147], v[244:247], v[112:115]
	v_mfma_f32_16x16x32_bf16 v[120:123], v[148:151], v[244:247], v[120:123]
	v_mfma_f32_16x16x32_bf16 v[96:99], v[152:155], v[244:247], v[96:99]
	v_mfma_f32_16x16x32_bf16 v[104:107], v[156:159], v[244:247], v[104:107]
	ds_read_b128 v[244:247], v196 offset:14336
	s_waitcnt lgkmcnt(3)
	v_mfma_f32_16x16x32_bf16 v[116:119], v[144:147], v[248:251], v[116:119]
	v_mfma_f32_16x16x32_bf16 v[124:127], v[148:151], v[248:251], v[124:127]
	v_mfma_f32_16x16x32_bf16 v[100:103], v[152:155], v[248:251], v[100:103]
	v_mfma_f32_16x16x32_bf16 v[108:111], v[156:159], v[248:251], v[108:111]
	ds_read_b128 v[248:251], v196 offset:15360
	s_waitcnt lgkmcnt(3)
	v_mfma_f32_16x16x32_bf16 v[80:83], v[144:147], v[236:239], v[80:83]
	v_mfma_f32_16x16x32_bf16 v[88:91], v[148:151], v[236:239], v[88:91]
	v_mfma_f32_16x16x32_bf16 v[48:51], v[152:155], v[236:239], v[48:51]
	v_mfma_f32_16x16x32_bf16 v[56:59], v[156:159], v[236:239], v[56:59]
	s_waitcnt lgkmcnt(2)
	v_mfma_f32_16x16x32_bf16 v[84:87], v[144:147], v[240:243], v[84:87]
	v_mfma_f32_16x16x32_bf16 v[92:95], v[148:151], v[240:243], v[92:95]
	v_mfma_f32_16x16x32_bf16 v[52:55], v[152:155], v[240:243], v[52:55]
	v_mfma_f32_16x16x32_bf16 v[60:63], v[156:159], v[240:243], v[60:63]
	s_waitcnt lgkmcnt(1)
	v_mfma_f32_16x16x32_bf16 v[64:67], v[144:147], v[244:247], v[64:67]
	v_mfma_f32_16x16x32_bf16 v[72:75], v[148:151], v[244:247], v[72:75]
	v_mfma_f32_16x16x32_bf16 v[32:35], v[152:155], v[244:247], v[32:35]
	v_mfma_f32_16x16x32_bf16 v[40:43], v[156:159], v[244:247], v[40:43]
	s_waitcnt lgkmcnt(0)
	v_mfma_f32_16x16x32_bf16 v[68:71], v[144:147], v[248:251], v[68:71]
	v_mfma_f32_16x16x32_bf16 v[76:79], v[148:151], v[248:251], v[76:79]
	v_mfma_f32_16x16x32_bf16 v[36:39], v[152:155], v[248:251], v[36:39]
	v_mfma_f32_16x16x32_bf16 v[44:47], v[156:159], v[248:251], v[44:47]
	global_load_dwordx4 v[144:147], v[198:199], off
	global_load_dwordx4 v[148:151], v[198:199], off offset:256
	global_load_dwordx4 v[152:155], v[200:201], off
	global_load_dwordx4 v[156:159], v[200:201], off offset:256
	s_waitcnt vmcnt(8)
	s_barrier
	ds_read_b128 v[236:239], v196 offset:16384
	ds_read_b128 v[240:243], v196 offset:17408
	ds_read_b128 v[244:247], v196 offset:18432
	ds_read_b128 v[248:251], v196 offset:19456
	s_waitcnt vmcnt(4) lgkmcnt(3)
	v_mfma_f32_16x16x32_bf16 v[16:19], v[128:131], v[236:239], v[16:19]
	v_mfma_f32_16x16x32_bf16 v[24:27], v[132:135], v[236:239], v[24:27]
	v_mfma_f32_16x16x32_bf16 v[0:3], v[136:139], v[236:239], v[0:3]
	v_mfma_f32_16x16x32_bf16 v[8:11], v[140:143], v[236:239], v[8:11]
	ds_read_b128 v[236:239], v196 offset:20480
	s_waitcnt lgkmcnt(3)
	v_mfma_f32_16x16x32_bf16 v[20:23], v[128:131], v[240:243], v[20:23]
	v_mfma_f32_16x16x32_bf16 v[28:31], v[132:135], v[240:243], v[28:31]
	v_mfma_f32_16x16x32_bf16 v[4:7], v[136:139], v[240:243], v[4:7]
	v_mfma_f32_16x16x32_bf16 v[12:15], v[140:143], v[240:243], v[12:15]
	ds_read_b128 v[240:243], v196 offset:21504
	s_waitcnt lgkmcnt(3)
	v_mfma_f32_16x16x32_bf16 v[112:115], v[128:131], v[244:247], v[112:115]
	v_mfma_f32_16x16x32_bf16 v[120:123], v[132:135], v[244:247], v[120:123]
	v_mfma_f32_16x16x32_bf16 v[96:99], v[136:139], v[244:247], v[96:99]
	v_mfma_f32_16x16x32_bf16 v[104:107], v[140:143], v[244:247], v[104:107]
	ds_read_b128 v[244:247], v196 offset:22528
	s_waitcnt lgkmcnt(3)
	v_mfma_f32_16x16x32_bf16 v[116:119], v[128:131], v[248:251], v[116:119]
	v_mfma_f32_16x16x32_bf16 v[124:127], v[132:135], v[248:251], v[124:127]
	v_mfma_f32_16x16x32_bf16 v[100:103], v[136:139], v[248:251], v[100:103]
	v_mfma_f32_16x16x32_bf16 v[108:111], v[140:143], v[248:251], v[108:111]
	ds_read_b128 v[248:251], v196 offset:23552
	s_waitcnt lgkmcnt(3)
	v_mfma_f32_16x16x32_bf16 v[80:83], v[128:131], v[236:239], v[80:83]
	v_mfma_f32_16x16x32_bf16 v[88:91], v[132:135], v[236:239], v[88:91]
	v_mfma_f32_16x16x32_bf16 v[48:51], v[136:139], v[236:239], v[48:51]
	v_mfma_f32_16x16x32_bf16 v[56:59], v[140:143], v[236:239], v[56:59]
	s_waitcnt lgkmcnt(2)
	v_mfma_f32_16x16x32_bf16 v[84:87], v[128:131], v[240:243], v[84:87]
	v_mfma_f32_16x16x32_bf16 v[92:95], v[132:135], v[240:243], v[92:95]
	v_mfma_f32_16x16x32_bf16 v[52:55], v[136:139], v[240:243], v[52:55]
	v_mfma_f32_16x16x32_bf16 v[60:63], v[140:143], v[240:243], v[60:63]
	s_waitcnt lgkmcnt(1)
	v_mfma_f32_16x16x32_bf16 v[64:67], v[128:131], v[244:247], v[64:67]
	v_mfma_f32_16x16x32_bf16 v[72:75], v[132:135], v[244:247], v[72:75]
	v_mfma_f32_16x16x32_bf16 v[32:35], v[136:139], v[244:247], v[32:35]
	v_mfma_f32_16x16x32_bf16 v[40:43], v[140:143], v[244:247], v[40:43]
	s_waitcnt lgkmcnt(0)
	v_mfma_f32_16x16x32_bf16 v[68:71], v[128:131], v[248:251], v[68:71]
	v_mfma_f32_16x16x32_bf16 v[76:79], v[132:135], v[248:251], v[76:79]
	v_mfma_f32_16x16x32_bf16 v[36:39], v[136:139], v[248:251], v[36:39]
	v_mfma_f32_16x16x32_bf16 v[44:47], v[140:143], v[248:251], v[44:47]
	ds_read_b128 v[236:239], v196 offset:24576
	ds_read_b128 v[240:243], v196 offset:25600
	ds_read_b128 v[244:247], v196 offset:26624
	ds_read_b128 v[248:251], v196 offset:27648
	s_waitcnt vmcnt(0) lgkmcnt(3)
	v_mfma_f32_16x16x32_bf16 v[16:19], v[144:147], v[236:239], v[16:19]
	v_mfma_f32_16x16x32_bf16 v[24:27], v[148:151], v[236:239], v[24:27]
	v_mfma_f32_16x16x32_bf16 v[0:3], v[152:155], v[236:239], v[0:3]
	v_mfma_f32_16x16x32_bf16 v[8:11], v[156:159], v[236:239], v[8:11]
	ds_read_b128 v[236:239], v196 offset:28672
	s_waitcnt lgkmcnt(3)
	v_mfma_f32_16x16x32_bf16 v[20:23], v[144:147], v[240:243], v[20:23]
	v_mfma_f32_16x16x32_bf16 v[28:31], v[148:151], v[240:243], v[28:31]
	v_mfma_f32_16x16x32_bf16 v[4:7], v[152:155], v[240:243], v[4:7]
	v_mfma_f32_16x16x32_bf16 v[12:15], v[156:159], v[240:243], v[12:15]
	ds_read_b128 v[240:243], v196 offset:29696
	s_waitcnt lgkmcnt(3)
	v_mfma_f32_16x16x32_bf16 v[112:115], v[144:147], v[244:247], v[112:115]
	v_mfma_f32_16x16x32_bf16 v[120:123], v[148:151], v[244:247], v[120:123]
	v_mfma_f32_16x16x32_bf16 v[96:99], v[152:155], v[244:247], v[96:99]
	v_mfma_f32_16x16x32_bf16 v[104:107], v[156:159], v[244:247], v[104:107]
	ds_read_b128 v[244:247], v196 offset:30720
	s_waitcnt lgkmcnt(3)
	v_mfma_f32_16x16x32_bf16 v[116:119], v[144:147], v[248:251], v[116:119]
	v_mfma_f32_16x16x32_bf16 v[124:127], v[148:151], v[248:251], v[124:127]
	v_mfma_f32_16x16x32_bf16 v[100:103], v[152:155], v[248:251], v[100:103]
	v_mfma_f32_16x16x32_bf16 v[108:111], v[156:159], v[248:251], v[108:111]
	ds_read_b128 v[248:251], v196 offset:31744
	v_permlane16_swap_b32_e32 v16, v20
	v_permlane16_swap_b32_e32 v17, v21
	v_permlane16_swap_b32_e32 v18, v22
	v_permlane16_swap_b32_e32 v19, v23
	v_permlane16_swap_b32_e32 v24, v28
	v_permlane16_swap_b32_e32 v25, v29
	v_permlane16_swap_b32_e32 v26, v30
	v_permlane16_swap_b32_e32 v27, v31
	v_permlane16_swap_b32_e32 v0, v4
	v_permlane16_swap_b32_e32 v1, v5
	v_permlane16_swap_b32_e32 v2, v6
	v_permlane16_swap_b32_e32 v3, v7
	v_permlane16_swap_b32_e32 v8, v12
	v_permlane16_swap_b32_e32 v9, v13
	v_permlane16_swap_b32_e32 v10, v14
	v_permlane16_swap_b32_e32 v11, v15
	v_permlane32_swap_b32_e32 v16, v20
	v_permlane32_swap_b32_e32 v17, v21
	v_permlane32_swap_b32_e32 v18, v22
	v_permlane32_swap_b32_e32 v19, v23
	v_permlane32_swap_b32_e32 v24, v28
	v_permlane32_swap_b32_e32 v25, v29
	v_permlane32_swap_b32_e32 v26, v30
	v_permlane32_swap_b32_e32 v27, v31
	v_permlane32_swap_b32_e32 v0, v4
	v_permlane32_swap_b32_e32 v1, v5
	v_permlane32_swap_b32_e32 v2, v6
	v_permlane32_swap_b32_e32 v3, v7
	v_permlane32_swap_b32_e32 v8, v12
	v_permlane32_swap_b32_e32 v9, v13
	v_permlane32_swap_b32_e32 v10, v14
	v_permlane32_swap_b32_e32 v11, v15
	s_waitcnt lgkmcnt(3)
	v_mfma_f32_16x16x32_bf16 v[80:83], v[144:147], v[236:239], v[80:83]
	v_mfma_f32_16x16x32_bf16 v[88:91], v[148:151], v[236:239], v[88:91]
	v_mfma_f32_16x16x32_bf16 v[48:51], v[152:155], v[236:239], v[48:51]
	v_mfma_f32_16x16x32_bf16 v[56:59], v[156:159], v[236:239], v[56:59]
	s_waitcnt lgkmcnt(2)
	v_mfma_f32_16x16x32_bf16 v[84:87], v[144:147], v[240:243], v[84:87]
	v_mfma_f32_16x16x32_bf16 v[92:95], v[148:151], v[240:243], v[92:95]
	v_mfma_f32_16x16x32_bf16 v[52:55], v[152:155], v[240:243], v[52:55]
	v_mfma_f32_16x16x32_bf16 v[60:63], v[156:159], v[240:243], v[60:63]
	v_permlane16_swap_b32_e32 v112, v116
	v_permlane16_swap_b32_e32 v113, v117
	v_permlane16_swap_b32_e32 v114, v118
	v_permlane16_swap_b32_e32 v115, v119
	v_permlane16_swap_b32_e32 v120, v124
	v_permlane16_swap_b32_e32 v121, v125
	v_permlane16_swap_b32_e32 v122, v126
	v_permlane16_swap_b32_e32 v123, v127
	v_permlane16_swap_b32_e32 v96, v100
	v_permlane16_swap_b32_e32 v97, v101
	v_permlane16_swap_b32_e32 v98, v102
	v_permlane16_swap_b32_e32 v99, v103
	v_permlane16_swap_b32_e32 v104, v108
	v_permlane16_swap_b32_e32 v105, v109
	v_permlane16_swap_b32_e32 v106, v110
	v_permlane16_swap_b32_e32 v107, v111
	v_permlane32_swap_b32_e32 v112, v116
	v_permlane32_swap_b32_e32 v113, v117
	v_permlane32_swap_b32_e32 v114, v118
	v_permlane32_swap_b32_e32 v115, v119
	v_permlane32_swap_b32_e32 v120, v124
	v_permlane32_swap_b32_e32 v121, v125
	v_permlane32_swap_b32_e32 v122, v126
	v_permlane32_swap_b32_e32 v123, v127
	v_permlane32_swap_b32_e32 v96, v100
	v_permlane32_swap_b32_e32 v97, v101
	v_permlane32_swap_b32_e32 v98, v102
	v_permlane32_swap_b32_e32 v99, v103
	v_permlane32_swap_b32_e32 v104, v108
	v_permlane32_swap_b32_e32 v105, v109
	v_permlane32_swap_b32_e32 v106, v110
	v_permlane32_swap_b32_e32 v107, v111
	s_waitcnt lgkmcnt(1)
	v_mfma_f32_16x16x32_bf16 v[64:67], v[144:147], v[244:247], v[64:67]
	v_mfma_f32_16x16x32_bf16 v[72:75], v[148:151], v[244:247], v[72:75]
	v_mfma_f32_16x16x32_bf16 v[32:35], v[152:155], v[244:247], v[32:35]
	v_mfma_f32_16x16x32_bf16 v[40:43], v[156:159], v[244:247], v[40:43]
	s_waitcnt lgkmcnt(0)
	v_mfma_f32_16x16x32_bf16 v[68:71], v[144:147], v[248:251], v[68:71]
	v_mfma_f32_16x16x32_bf16 v[76:79], v[148:151], v[248:251], v[76:79]
	v_mfma_f32_16x16x32_bf16 v[36:39], v[152:155], v[248:251], v[36:39]
	v_mfma_f32_16x16x32_bf16 v[44:47], v[156:159], v[248:251], v[44:47]
	v_permlane16_swap_b32_e32 v80, v84
	v_permlane16_swap_b32_e32 v81, v85
	v_permlane16_swap_b32_e32 v82, v86
	v_permlane16_swap_b32_e32 v83, v87
	v_permlane16_swap_b32_e32 v88, v92
	v_permlane16_swap_b32_e32 v89, v93
	v_permlane16_swap_b32_e32 v90, v94
	v_permlane16_swap_b32_e32 v91, v95
	v_permlane16_swap_b32_e32 v48, v52
	v_permlane16_swap_b32_e32 v49, v53
	v_permlane16_swap_b32_e32 v50, v54
	v_permlane16_swap_b32_e32 v51, v55
	v_permlane16_swap_b32_e32 v56, v60
	v_permlane16_swap_b32_e32 v57, v61
	v_permlane16_swap_b32_e32 v58, v62
	v_permlane16_swap_b32_e32 v59, v63
	v_permlane32_swap_b32_e32 v80, v84
	v_permlane32_swap_b32_e32 v81, v85
	v_permlane32_swap_b32_e32 v82, v86
	v_permlane32_swap_b32_e32 v83, v87
	v_permlane32_swap_b32_e32 v88, v92
	v_permlane32_swap_b32_e32 v89, v93
	v_permlane32_swap_b32_e32 v90, v94
	v_permlane32_swap_b32_e32 v91, v95
	v_permlane32_swap_b32_e32 v48, v52
	v_permlane32_swap_b32_e32 v49, v53
	v_permlane32_swap_b32_e32 v50, v54
	v_permlane32_swap_b32_e32 v51, v55
	v_permlane32_swap_b32_e32 v56, v60
	v_permlane32_swap_b32_e32 v57, v61
	v_permlane32_swap_b32_e32 v58, v62
	v_permlane32_swap_b32_e32 v59, v63
	s_barrier
	s_nop 7
	v_permlane16_swap_b32_e32 v64, v68
	v_permlane16_swap_b32_e32 v65, v69
	v_permlane16_swap_b32_e32 v66, v70
	v_permlane16_swap_b32_e32 v67, v71
	v_permlane16_swap_b32_e32 v72, v76
	v_permlane16_swap_b32_e32 v73, v77
	v_permlane16_swap_b32_e32 v74, v78
	v_permlane16_swap_b32_e32 v75, v79
	v_permlane16_swap_b32_e32 v32, v36
	v_permlane16_swap_b32_e32 v33, v37
	v_permlane16_swap_b32_e32 v34, v38
	v_permlane16_swap_b32_e32 v35, v39
	v_permlane16_swap_b32_e32 v40, v44
	v_permlane16_swap_b32_e32 v41, v45
	v_permlane16_swap_b32_e32 v42, v46
	v_permlane16_swap_b32_e32 v43, v47
	v_permlane32_swap_b32_e32 v64, v68
	v_permlane32_swap_b32_e32 v65, v69
	v_permlane32_swap_b32_e32 v66, v70
	v_permlane32_swap_b32_e32 v67, v71
	v_permlane32_swap_b32_e32 v72, v76
	v_permlane32_swap_b32_e32 v73, v77
	v_permlane32_swap_b32_e32 v74, v78
	v_permlane32_swap_b32_e32 v75, v79
	v_permlane32_swap_b32_e32 v32, v36
	v_permlane32_swap_b32_e32 v33, v37
	v_permlane32_swap_b32_e32 v34, v38
	v_permlane32_swap_b32_e32 v35, v39
	v_permlane32_swap_b32_e32 v40, v44
	v_permlane32_swap_b32_e32 v41, v45
	v_permlane32_swap_b32_e32 v42, v46
	v_permlane32_swap_b32_e32 v43, v47
	s_waitcnt vmcnt(0)
	s_lshl_b32 s12, s2, 8
	s_cmp_eq_u32 s0, 23
	s_mov_b64 s[2:3], -1
	s_cbranch_scc1 .LBB0_347
	s_movk_i32 s1, 0x2400
	s_waitcnt vmcnt(6)
	v_and_b32_e32 v130, 0xffffffc0, v181
	s_cmp_gt_i32 s0, 10
	v_mul_lo_u32 v129, v233, s1
	v_and_b32_e32 v128, 56, v234
	v_add_u32_e32 v131, s12, v130
	s_cselect_b64 s[2:3], -1, 0
	s_cmp_gt_u32 s0, 19
	v_mul_u32_u24_e32 v130, 0x120, v183
	s_waitcnt vmcnt(0)
	v_lshl_or_b32 v132, v128, 1, v129
	v_lshl_or_b32 v128, s0, 7, v128
	s_cselect_b64 s[0:1], -1, 0
	v_lshl_add_u32 v129, v130, 1, v129
	v_lshl_or_b32 v130, v231, 1, v129
	v_cvt_pk_bf16_f32 v112, v112, s0
	ds_write_b16 v130, v112 offset:64
	v_cvt_pk_bf16_f32 v112, v17, s0
	v_cvt_pk_bf16_f32 v96, v96, s0
	ds_write_b16 v130, v112 offset:144
	v_cvt_pk_bf16_f32 v112, v113, s0
	ds_write_b16 v130, v96 offset:4672
	v_cvt_pk_bf16_f32 v96, v1, s0
	ds_write_b16 v130, v112 offset:208
	v_cvt_pk_bf16_f32 v112, v18, s0
	ds_write_b16 v130, v96 offset:4752
	v_cvt_pk_bf16_f32 v96, v97, s0
	ds_write_b16 v130, v112 offset:288
	v_cvt_pk_bf16_f32 v112, v114, s0
	ds_write_b16 v130, v96 offset:4816
	v_cvt_pk_bf16_f32 v96, v2, s0
	ds_write_b16 v130, v112 offset:352
	v_cvt_pk_bf16_f32 v112, v19, s0
	ds_write_b16 v130, v96 offset:4896
	v_cvt_pk_bf16_f32 v96, v98, s0
	ds_write_b16 v130, v112 offset:432
	v_cvt_pk_bf16_f32 v112, v115, s0
	ds_write_b16 v130, v96 offset:4960
	v_cvt_pk_bf16_f32 v96, v3, s0
	ds_write_b16 v130, v112 offset:496
	v_cvt_pk_bf16_f32 v112, v20, s0
	ds_write_b16 v130, v96 offset:5040
	v_cvt_pk_bf16_f32 v96, v99, s0
	ds_write_b16 v130, v112 offset:1152
	v_cvt_pk_bf16_f32 v112, v116, s0
	ds_write_b16 v130, v96 offset:5104
	v_cvt_pk_bf16_f32 v96, v4, s0
	ds_write_b16 v130, v112 offset:1216
	v_cvt_pk_bf16_f32 v112, v21, s0
	ds_write_b16 v130, v96 offset:5760
	v_cvt_pk_bf16_f32 v96, v100, s0
	ds_write_b16 v130, v112 offset:1296
	v_cvt_pk_bf16_f32 v112, v117, s0
	ds_write_b16 v130, v96 offset:5824
	v_cvt_pk_bf16_f32 v96, v5, s0
	ds_write_b16 v130, v112 offset:1360
	v_cvt_pk_bf16_f32 v112, v22, s0
	ds_write_b16 v130, v96 offset:5904
	v_cvt_pk_bf16_f32 v96, v101, s0
	ds_write_b16 v130, v112 offset:1440
	v_cvt_pk_bf16_f32 v112, v118, s0
	ds_write_b16 v130, v96 offset:5968
	v_cvt_pk_bf16_f32 v96, v6, s0
	ds_write_b16 v130, v112 offset:1504
	v_cvt_pk_bf16_f32 v112, v23, s0
	ds_write_b16 v130, v96 offset:6048
	v_cvt_pk_bf16_f32 v96, v102, s0
	ds_write_b16 v130, v112 offset:1584
	v_cvt_pk_bf16_f32 v112, v119, s0
	ds_write_b16 v130, v96 offset:6112
	v_cvt_pk_bf16_f32 v96, v7, s0
	ds_write_b16 v130, v112 offset:1648
	v_cvt_pk_bf16_f32 v112, v24, s0
	ds_write_b16 v130, v96 offset:6192
	v_cvt_pk_bf16_f32 v96, v103, s0
	ds_write_b16 v130, v112 offset:2304
	v_cvt_pk_bf16_f32 v112, v120, s0
	ds_write_b16 v130, v96 offset:6256
	v_cvt_pk_bf16_f32 v96, v8, s0
	ds_write_b16 v130, v112 offset:2368
	v_cvt_pk_bf16_f32 v112, v25, s0
	ds_write_b16 v130, v96 offset:6912
	v_cvt_pk_bf16_f32 v96, v104, s0
	ds_write_b16 v130, v112 offset:2448
	v_cvt_pk_bf16_f32 v112, v121, s0
	ds_write_b16 v130, v96 offset:6976
	v_cvt_pk_bf16_f32 v96, v9, s0
	ds_write_b16 v130, v112 offset:2512
	v_cvt_pk_bf16_f32 v112, v26, s0
	ds_write_b16 v130, v96 offset:7056
	v_cvt_pk_bf16_f32 v96, v105, s0
	ds_write_b16 v130, v112 offset:2592
	v_cvt_pk_bf16_f32 v112, v122, s0
	ds_write_b16 v130, v96 offset:7120
	v_cvt_pk_bf16_f32 v96, v10, s0
	ds_write_b16 v130, v112 offset:2656
	v_cvt_pk_bf16_f32 v112, v27, s0
	ds_write_b16 v130, v96 offset:7200
	v_cvt_pk_bf16_f32 v96, v106, s0
	ds_write_b16 v130, v112 offset:2736
	v_cvt_pk_bf16_f32 v112, v123, s0
	ds_write_b16 v130, v96 offset:7264
	v_cvt_pk_bf16_f32 v96, v11, s0
	ds_write_b16 v130, v112 offset:2800
	v_cvt_pk_bf16_f32 v112, v28, s0
	ds_write_b16 v130, v96 offset:7344
	v_cvt_pk_bf16_f32 v96, v107, s0
	ds_write_b16 v130, v112 offset:3456
	v_cvt_pk_bf16_f32 v112, v124, s0
	ds_write_b16 v130, v96 offset:7408
	v_cvt_pk_bf16_f32 v96, v12, s0
	ds_write_b16 v130, v112 offset:3520
	v_cvt_pk_bf16_f32 v112, v29, s0
	ds_write_b16 v130, v96 offset:8064
	v_cvt_pk_bf16_f32 v96, v108, s0
	ds_write_b16 v130, v112 offset:3600
	v_cvt_pk_bf16_f32 v112, v125, s0
	ds_write_b16 v130, v96 offset:8128
	v_cvt_pk_bf16_f32 v96, v13, s0
	ds_write_b16 v130, v112 offset:3664
	v_cvt_pk_bf16_f32 v112, v30, s0
	ds_write_b16 v130, v96 offset:8208
	v_cvt_pk_bf16_f32 v96, v109, s0
	ds_write_b16 v130, v112 offset:3744
	v_cvt_pk_bf16_f32 v112, v126, s0
	ds_write_b16 v130, v96 offset:8272
	v_cvt_pk_bf16_f32 v96, v14, s0
	ds_write_b16 v130, v112 offset:3808
	v_cvt_pk_bf16_f32 v112, v31, s0
	ds_write_b16 v130, v96 offset:8352
	v_cvt_pk_bf16_f32 v96, v110, s0
	ds_write_b16 v130, v112 offset:3888
	v_cvt_pk_bf16_f32 v112, v127, s0
	ds_write_b16 v130, v96 offset:8416
	v_cvt_pk_bf16_f32 v96, v15, s0
	v_cvt_pk_bf16_f32 v133, v16, s0
	ds_write_b16 v130, v112 offset:3952
	v_cvt_pk_bf16_f32 v112, v0, s0
	ds_write_b16 v130, v96 offset:8496
	v_cvt_pk_bf16_f32 v96, v111, s0
	ds_write_b16 v130, v133
	ds_write_b16 v130, v112 offset:4608
	ds_write_b16 v130, v96 offset:8560
	v_lshrrev_b32_e32 v109, 3, v232
	s_waitcnt lgkmcnt(0)
	v_mad_u32_u24 v96, v109, s42, v132
	ds_read_b128 v[96:99], v96
	v_mov_b32_e32 v176, v128
	v_or_b32_e32 v110, v131, v109
	s_mov_b64 s[4:5], -1
	s_and_b64 vcc, exec, s[2:3]
	s_cbranch_vccz .LBB0_224
	s_and_b64 vcc, exec, s[0:1]
	s_cbranch_vccz .LBB0_221
	v_readlane_b32 s16, v254, 15
	v_readlane_b32 s18, v254, 17
	v_readlane_b32 s19, v254, 18
	v_readlane_b32 s17, v254, 16
	v_readlane_b32 s20, v254, 19
	v_mov_b64_e32 v[100:101], s[18:19]
	v_mad_i64_i32 v[100:101], s[4:5], v110, s89, v[100:101]
	s_movk_i32 s4, 0xec00
	v_lshl_add_u64 v[100:101], v[176:177], 1, v[100:101]
	s_mov_b32 s5, -1
	v_readlane_b32 s21, v254, 20
	v_readlane_b32 s22, v254, 21
	v_readlane_b32 s23, v254, 22
	v_readlane_b32 s24, v254, 23
	v_readlane_b32 s25, v254, 24
	v_readlane_b32 s26, v254, 25
	v_readlane_b32 s27, v254, 26
	v_readlane_b32 s28, v254, 27
	v_readlane_b32 s29, v254, 28
	v_readlane_b32 s30, v254, 29
	v_readlane_b32 s31, v254, 30
	v_lshl_add_u64 v[100:101], v[100:101], 0, s[4:5]
	s_mov_b64 s[4:5], 0

.LBB0_923:
	s_ashr_i32 s2, s4, 31
	s_lshr_b32 s2, s2, 26
	s_add_i32 s2, s4, s2
	s_ashr_i32 s3, s2, 6
	s_lshl_b32 s3, s3, 3
	s_sub_i32 s8, s25, s3
	s_min_i32 s8, s8, 8
	s_abs_i32 s9, s8
	v_cvt_f32_u32_e32 v0, s9
	s_sub_i32 s12, 0, s9
	s_andn2_b32 s2, s2, 63
	s_sub_i32 s10, s4, s2
	v_rcp_iflag_f32_e32 v0, v0
	s_abs_i32 s2, s10
	s_xor_b32 s11, s10, s8
	s_ashr_i32 s11, s11, 31
	v_mul_f32_e32 v0, 0x4f7ffffe, v0
	v_cvt_u32_f32_e32 v0, v0
	v_mov_b32_e32 v181, v179
	v_readfirstlane_b32 s13, v0
	s_mul_i32 s12, s12, s13
	s_mul_hi_u32 s12, s13, s12
	s_add_i32 s13, s13, s12
	s_mul_hi_u32 s12, s2, s13
	s_mul_i32 s13, s12, s9
	s_sub_i32 s2, s2, s13
	s_add_i32 s14, s12, 1
	s_sub_i32 s13, s2, s9
	s_cmp_ge_u32 s2, s9
	s_cselect_b32 s12, s14, s12
	s_cselect_b32 s2, s13, s2
	s_add_i32 s13, s12, 1
	s_cmp_ge_u32 s2, s9
	s_cselect_b32 s2, s13, s12
	s_xor_b32 s2, s2, s11
	s_sub_i32 s2, s2, s11
	s_mul_i32 s8, s8, s2
	s_add_i32 s3, s3, s7
	s_sub_i32 s8, s10, s8
	v_ashrrev_i32_e32 v237, 6, v181
	s_add_i32 s8, s3, s8
	v_lshlrev_b32_e32 v0, 1, v237
	v_lshl_add_u32 v0, s8, 3, v0
	v_ashrrev_i32_e32 v1, 31, v0
	v_bfe_u32 v183, v181, 5, 1
	v_lshlrev_b64 v[0:1], 16, v[0:1]
	v_and_b32_e32 v238, 31, v181
	v_lshl_add_u64 v[0:1], s[64:65], 0, v[0:1]
	v_lshlrev_b32_e32 v176, 9, v183
	s_ashr_i32 s3, s2, 31
	v_lshl_add_u64 v[0:1], v[0:1], 0, v[176:177]
	v_lshlrev_b32_e32 v176, 4, v238
	v_ashrrev_i32_e32 v40, 2, v181
	s_lshl_b64 s[10:11], s[2:3], 18
	v_lshl_add_u64 v[184:185], v[0:1], 0, v[176:177]
	s_add_u32 s10, s5, s10
	v_lshlrev_b32_e32 v0, 5, v40
	s_addc_u32 s11, s6, s11
	v_ashrrev_i32_e32 v1, 31, v0
	v_lshlrev_b32_e32 v2, 4, v181
	v_lshl_add_u64 v[0:1], v[0:1], 1, s[10:11]
	v_and_b32_e32 v176, 48, v2
	v_lshl_add_u64 v[186:187], v[0:1], 0, v[176:177]
	s_movk_i32 s3, 0x2000
	v_add_co_u32_e32 v36, vcc, s3, v186
	v_mul_u32_u24_e32 v38, 40, v238
	s_nop 0
	v_addc_co_u32_e32 v37, vcc, 0, v187, vcc
	v_lshlrev_b32_e32 v39, 4, v183
	v_lshl_add_u32 v240, v38, 1, v39
	v_add_co_u32_e32 v38, vcc, s41, v184
	s_movk_i32 s9, 0x50
	s_nop 0
	v_addc_co_u32_e32 v39, vcc, 0, v185, vcc
	v_and_b32_e32 v239, 63, v181
	v_bfe_u32 v247, v181, 4, 2
	v_lshlrev_b32_e32 v247, 1, v247
	v_mov_b32_e32 v176, 0x78
	v_lshrrev_b32_e32 v247, v247, v176
	v_and_b32_e32 v247, 3, v247
	v_and_b32_e32 v246, 3, v181
	v_xor_b32_e32 v247, v247, v246
	v_lshlrev_b32_e32 v247, 4, v247
	v_and_b32_e32 v188, 0xffffffcf, v186
	v_or_b32_e32 v188, v188, v247
	v_mov_b32_e32 v189, v187
	v_lshrrev_b32_e32 v176, 6, v181
	v_lshlrev_b32_e32 v247, 11, v176
	v_lshlrev_b32_e32 v176, 10, v176
	v_lshl_add_u64 v[188:189], v[188:189], 0, v[176:177]
	v_readfirstlane_b32 vcc_lo, v247
	v_bfe_u32 v247, v181, 4, 1
	v_lshlrev_b32_e32 v176, 9, v183
	v_lshl_add_u32 v176, v247, 8, v176
	v_lshl_add_u64 v[184:185], v[184:185], 0, v[176:177]
	v_mov_b32_e32 v176, s41
	v_lshl_add_u64 v[186:187], v[184:185], 0, v[176:177]
	v_mov_b32_e32 v176, 0x78
	v_bfe_u32 v247, v181, 2, 2
	v_lshlrev_b32_e32 v247, 1, v247
	v_lshrrev_b32_e32 v247, v247, v176
	v_and_b32_e32 v247, 3, v247
	v_bfe_u32 v246, v181, 4, 2
	v_xor_b32_e32 v247, v247, v246
	v_lshlrev_b32_e32 v247, 4, v247
	v_and_b32_e32 v246, 15, v181
	v_lshl_add_u32 v246, v246, 6, v247
	s_mov_b32 s96, 0
	s_mov_b32 m0, vcc_lo
	v_lshl_add_u64 v[160:161], v[188:189], 0, s[96:97]
	global_load_lds_dwordx4 v[160:161], off
	global_load_lds_dwordx4 v[160:161], off offset:1024
	s_movk_i32 s96, 0x2000
	s_add_i32 m0, vcc_lo, 8192
	v_lshl_add_u64 v[160:161], v[188:189], 0, s[96:97]
	global_load_lds_dwordx4 v[160:161], off
	global_load_lds_dwordx4 v[160:161], off offset:1024
	s_mov_b32 s96, 0
	v_lshl_add_u64 v[248:249], v[184:185], 0, s[96:97]
	v_lshl_add_u64 v[250:251], v[186:187], 0, s[96:97]
	global_load_dwordx4 v[128:131], v[248:249], off
	global_load_dwordx4 v[132:135], v[248:249], off offset:256
	global_load_dwordx4 v[136:139], v[250:251], off
	global_load_dwordx4 v[140:143], v[250:251], off offset:256
	s_movk_i32 s96, 0x800
	v_lshl_add_u64 v[248:249], v[184:185], 0, s[96:97]
	v_lshl_add_u64 v[250:251], v[186:187], 0, s[96:97]
	global_load_dwordx4 v[144:147], v[248:249], off
	global_load_dwordx4 v[148:151], v[248:249], off offset:256
	global_load_dwordx4 v[152:155], v[250:251], off
	global_load_dwordx4 v[156:159], v[250:251], off offset:256
	v_mov_b32_e32 v0, 0
	v_mov_b32_e32 v1, 0
	v_mov_b32_e32 v2, 0
	v_mov_b32_e32 v3, 0
	v_mov_b32_e32 v4, 0
	v_mov_b32_e32 v5, 0
	v_mov_b32_e32 v6, 0
	v_mov_b32_e32 v7, 0
	v_mov_b32_e32 v8, 0
	v_mov_b32_e32 v9, 0
	v_mov_b32_e32 v10, 0
	v_mov_b32_e32 v11, 0
	v_mov_b32_e32 v12, 0
	v_mov_b32_e32 v13, 0
	v_mov_b32_e32 v14, 0
	v_mov_b32_e32 v15, 0
	v_mov_b32_e32 v16, 0
	v_mov_b32_e32 v17, 0
	v_mov_b32_e32 v18, 0
	v_mov_b32_e32 v19, 0
	v_mov_b32_e32 v20, 0
	v_mov_b32_e32 v21, 0
	v_mov_b32_e32 v22, 0
	v_mov_b32_e32 v23, 0
	v_mov_b32_e32 v24, 0
	v_mov_b32_e32 v25, 0
	v_mov_b32_e32 v26, 0
	v_mov_b32_e32 v27, 0
	v_mov_b32_e32 v28, 0
	v_mov_b32_e32 v29, 0
	v_mov_b32_e32 v30, 0
	v_mov_b32_e32 v31, 0
	v_mov_b32_e32 v32, 0
	v_mov_b32_e32 v33, 0
	v_mov_b32_e32 v34, 0
	v_mov_b32_e32 v35, 0
	v_mov_b32_e32 v36, 0
	v_mov_b32_e32 v37, 0
	v_mov_b32_e32 v38, 0
	v_mov_b32_e32 v39, 0
	v_mov_b32_e32 v40, 0
	v_mov_b32_e32 v41, 0
	v_mov_b32_e32 v42, 0
	v_mov_b32_e32 v43, 0
	v_mov_b32_e32 v44, 0
	v_mov_b32_e32 v45, 0
	v_mov_b32_e32 v46, 0
	v_mov_b32_e32 v47, 0
	v_mov_b32_e32 v48, 0
	v_mov_b32_e32 v49, 0
	v_mov_b32_e32 v50, 0
	v_mov_b32_e32 v51, 0
	v_mov_b32_e32 v52, 0
	v_mov_b32_e32 v53, 0
	v_mov_b32_e32 v54, 0
	v_mov_b32_e32 v55, 0
	v_mov_b32_e32 v56, 0
	v_mov_b32_e32 v57, 0
	v_mov_b32_e32 v58, 0
	v_mov_b32_e32 v59, 0
	v_mov_b32_e32 v60, 0
	v_mov_b32_e32 v61, 0
	v_mov_b32_e32 v62, 0
	v_mov_b32_e32 v63, 0
	v_mov_b32_e32 v64, 0
	v_mov_b32_e32 v65, 0
	v_mov_b32_e32 v66, 0
	v_mov_b32_e32 v67, 0
	v_mov_b32_e32 v68, 0
	v_mov_b32_e32 v69, 0
	v_mov_b32_e32 v70, 0
	v_mov_b32_e32 v71, 0
	v_mov_b32_e32 v72, 0
	v_mov_b32_e32 v73, 0
	v_mov_b32_e32 v74, 0
	v_mov_b32_e32 v75, 0
	v_mov_b32_e32 v76, 0
	v_mov_b32_e32 v77, 0
	v_mov_b32_e32 v78, 0
	v_mov_b32_e32 v79, 0
	v_mov_b32_e32 v80, 0
	v_mov_b32_e32 v81, 0
	v_mov_b32_e32 v82, 0
	v_mov_b32_e32 v83, 0
	v_mov_b32_e32 v84, 0
	v_mov_b32_e32 v85, 0
	v_mov_b32_e32 v86, 0
	v_mov_b32_e32 v87, 0
	v_mov_b32_e32 v88, 0
	v_mov_b32_e32 v89, 0
	v_mov_b32_e32 v90, 0
	v_mov_b32_e32 v91, 0
	v_mov_b32_e32 v92, 0
	v_mov_b32_e32 v93, 0
	v_mov_b32_e32 v94, 0
	v_mov_b32_e32 v95, 0
	v_mov_b32_e32 v96, 0
	v_mov_b32_e32 v97, 0
	v_mov_b32_e32 v98, 0
	v_mov_b32_e32 v99, 0
	v_mov_b32_e32 v100, 0
	v_mov_b32_e32 v101, 0
	v_mov_b32_e32 v102, 0
	v_mov_b32_e32 v103, 0
	v_mov_b32_e32 v104, 0
	v_mov_b32_e32 v105, 0
	v_mov_b32_e32 v106, 0
	v_mov_b32_e32 v107, 0
	v_mov_b32_e32 v108, 0
	v_mov_b32_e32 v109, 0
	v_mov_b32_e32 v110, 0
	v_mov_b32_e32 v111, 0
	v_mov_b32_e32 v112, 0
	v_mov_b32_e32 v113, 0
	v_mov_b32_e32 v114, 0
	v_mov_b32_e32 v115, 0
	v_mov_b32_e32 v116, 0
	v_mov_b32_e32 v117, 0
	v_mov_b32_e32 v118, 0
	v_mov_b32_e32 v119, 0
	v_mov_b32_e32 v120, 0
	v_mov_b32_e32 v121, 0
	v_mov_b32_e32 v122, 0
	v_mov_b32_e32 v123, 0
	v_mov_b32_e32 v124, 0
	v_mov_b32_e32 v125, 0
	v_mov_b32_e32 v126, 0
	v_mov_b32_e32 v127, 0
	s_mov_b32 s3, 0
	s_waitcnt vmcnt(4)
	s_barrier
.Lg16_out_k:
	s_add_i32 s9, s3, 2
	s_lshl_b32 s96, s9, 13
	s_add_i32 m0, vcc_lo, 16384
	v_lshl_add_u64 v[160:161], v[188:189], 0, s[96:97]
	global_load_lds_dwordx4 v[160:161], off
	global_load_lds_dwordx4 v[160:161], off offset:1024
	s_add_i32 s9, s3, 3
	s_lshl_b32 s96, s9, 13
	s_add_i32 m0, vcc_lo, 24576
	v_lshl_add_u64 v[160:161], v[188:189], 0, s[96:97]
	global_load_lds_dwordx4 v[160:161], off
	global_load_lds_dwordx4 v[160:161], off offset:1024
	ds_read_b128 v[196:199], v246 offset:0
	ds_read_b128 v[200:203], v246 offset:1024
	ds_read_b128 v[204:207], v246 offset:2048
	ds_read_b128 v[242:245], v246 offset:3072
	s_add_i32 s9, s3, 2
	s_lshl_b32 s96, s9, 11
	v_lshl_add_u64 v[248:249], v[184:185], 0, s[96:97]
	v_lshl_add_u64 v[250:251], v[186:187], 0, s[96:97]
	s_waitcnt vmcnt(8) lgkmcnt(3)
	v_mfma_f32_16x16x32_bf16 v[112:115], v[128:131], v[196:199], v[112:115]
	v_mfma_f32_16x16x32_bf16 v[120:123], v[132:135], v[196:199], v[120:123]
	v_mfma_f32_16x16x32_bf16 v[48:51], v[136:139], v[196:199], v[48:51]
	v_mfma_f32_16x16x32_bf16 v[56:59], v[140:143], v[196:199], v[56:59]
	ds_read_b128 v[196:199], v246 offset:4096
	s_waitcnt lgkmcnt(3)
	v_mfma_f32_16x16x32_bf16 v[116:119], v[128:131], v[200:203], v[116:119]
	v_mfma_f32_16x16x32_bf16 v[124:127], v[132:135], v[200:203], v[124:127]
	v_mfma_f32_16x16x32_bf16 v[52:55], v[136:139], v[200:203], v[52:55]
	v_mfma_f32_16x16x32_bf16 v[60:63], v[140:143], v[200:203], v[60:63]
	ds_read_b128 v[200:203], v246 offset:5120
	s_waitcnt lgkmcnt(3)
	v_mfma_f32_16x16x32_bf16 v[96:99], v[128:131], v[204:207], v[96:99]
	v_mfma_f32_16x16x32_bf16 v[104:107], v[132:135], v[204:207], v[104:107]
	v_mfma_f32_16x16x32_bf16 v[32:35], v[136:139], v[204:207], v[32:35]
	v_mfma_f32_16x16x32_bf16 v[40:43], v[140:143], v[204:207], v[40:43]
	ds_read_b128 v[204:207], v246 offset:6144
	s_waitcnt lgkmcnt(3)
	v_mfma_f32_16x16x32_bf16 v[100:103], v[128:131], v[242:245], v[100:103]
	v_mfma_f32_16x16x32_bf16 v[108:111], v[132:135], v[242:245], v[108:111]
	v_mfma_f32_16x16x32_bf16 v[36:39], v[136:139], v[242:245], v[36:39]
	v_mfma_f32_16x16x32_bf16 v[44:47], v[140:143], v[242:245], v[44:47]
	ds_read_b128 v[242:245], v246 offset:7168
	s_waitcnt lgkmcnt(3)
	v_mfma_f32_16x16x32_bf16 v[80:83], v[128:131], v[196:199], v[80:83]
	v_mfma_f32_16x16x32_bf16 v[88:91], v[132:135], v[196:199], v[88:91]
	v_mfma_f32_16x16x32_bf16 v[16:19], v[136:139], v[196:199], v[16:19]
	v_mfma_f32_16x16x32_bf16 v[24:27], v[140:143], v[196:199], v[24:27]
	s_waitcnt lgkmcnt(2)
	v_mfma_f32_16x16x32_bf16 v[84:87], v[128:131], v[200:203], v[84:87]
	v_mfma_f32_16x16x32_bf16 v[92:95], v[132:135], v[200:203], v[92:95]
	v_mfma_f32_16x16x32_bf16 v[20:23], v[136:139], v[200:203], v[20:23]
	v_mfma_f32_16x16x32_bf16 v[28:31], v[140:143], v[200:203], v[28:31]
	s_waitcnt lgkmcnt(1)
	v_mfma_f32_16x16x32_bf16 v[64:67], v[128:131], v[204:207], v[64:67]
	v_mfma_f32_16x16x32_bf16 v[72:75], v[132:135], v[204:207], v[72:75]
	v_mfma_f32_16x16x32_bf16 v[0:3], v[136:139], v[204:207], v[0:3]
	v_mfma_f32_16x16x32_bf16 v[8:11], v[140:143], v[204:207], v[8:11]
	s_waitcnt lgkmcnt(0)
	v_mfma_f32_16x16x32_bf16 v[68:71], v[128:131], v[242:245], v[68:71]
	v_mfma_f32_16x16x32_bf16 v[76:79], v[132:135], v[242:245], v[76:79]
	v_mfma_f32_16x16x32_bf16 v[4:7], v[136:139], v[242:245], v[4:7]
	v_mfma_f32_16x16x32_bf16 v[12:15], v[140:143], v[242:245], v[12:15]
	global_load_dwordx4 v[128:131], v[248:249], off
	global_load_dwordx4 v[132:135], v[248:249], off offset:256
	global_load_dwordx4 v[136:139], v[250:251], off
	global_load_dwordx4 v[140:143], v[250:251], off offset:256
	ds_read_b128 v[196:199], v246 offset:8192
	ds_read_b128 v[200:203], v246 offset:9216
	ds_read_b128 v[204:207], v246 offset:10240
	ds_read_b128 v[242:245], v246 offset:11264
	s_add_i32 s9, s3, 3
	s_lshl_b32 s96, s9, 11
	v_lshl_add_u64 v[248:249], v[184:185], 0, s[96:97]
	v_lshl_add_u64 v[250:251], v[186:187], 0, s[96:97]
	s_waitcnt vmcnt(8) lgkmcnt(3)
	v_mfma_f32_16x16x32_bf16 v[112:115], v[144:147], v[196:199], v[112:115]
	v_mfma_f32_16x16x32_bf16 v[120:123], v[148:151], v[196:199], v[120:123]
	v_mfma_f32_16x16x32_bf16 v[48:51], v[152:155], v[196:199], v[48:51]
	v_mfma_f32_16x16x32_bf16 v[56:59], v[156:159], v[196:199], v[56:59]
	ds_read_b128 v[196:199], v246 offset:12288
	s_waitcnt lgkmcnt(3)
	v_mfma_f32_16x16x32_bf16 v[116:119], v[144:147], v[200:203], v[116:119]
	v_mfma_f32_16x16x32_bf16 v[124:127], v[148:151], v[200:203], v[124:127]
	v_mfma_f32_16x16x32_bf16 v[52:55], v[152:155], v[200:203], v[52:55]
	v_mfma_f32_16x16x32_bf16 v[60:63], v[156:159], v[200:203], v[60:63]
	ds_read_b128 v[200:203], v246 offset:13312
	s_waitcnt lgkmcnt(3)
	v_mfma_f32_16x16x32_bf16 v[96:99], v[144:147], v[204:207], v[96:99]
	v_mfma_f32_16x16x32_bf16 v[104:107], v[148:151], v[204:207], v[104:107]
	v_mfma_f32_16x16x32_bf16 v[32:35], v[152:155], v[204:207], v[32:35]
	v_mfma_f32_16x16x32_bf16 v[40:43], v[156:159], v[204:207], v[40:43]
	ds_read_b128 v[204:207], v246 offset:14336
	s_waitcnt lgkmcnt(3)
	v_mfma_f32_16x16x32_bf16 v[100:103], v[144:147], v[242:245], v[100:103]
	v_mfma_f32_16x16x32_bf16 v[108:111], v[148:151], v[242:245], v[108:111]
	v_mfma_f32_16x16x32_bf16 v[36:39], v[152:155], v[242:245], v[36:39]
	v_mfma_f32_16x16x32_bf16 v[44:47], v[156:159], v[242:245], v[44:47]
	ds_read_b128 v[242:245], v246 offset:15360
	s_waitcnt lgkmcnt(3)
	v_mfma_f32_16x16x32_bf16 v[80:83], v[144:147], v[196:199], v[80:83]
	v_mfma_f32_16x16x32_bf16 v[88:91], v[148:151], v[196:199], v[88:91]
	v_mfma_f32_16x16x32_bf16 v[16:19], v[152:155], v[196:199], v[16:19]
	v_mfma_f32_16x16x32_bf16 v[24:27], v[156:159], v[196:199], v[24:27]
	s_waitcnt lgkmcnt(2)
	v_mfma_f32_16x16x32_bf16 v[84:87], v[144:147], v[200:203], v[84:87]
	v_mfma_f32_16x16x32_bf16 v[92:95], v[148:151], v[200:203], v[92:95]
	v_mfma_f32_16x16x32_bf16 v[20:23], v[152:155], v[200:203], v[20:23]
	v_mfma_f32_16x16x32_bf16 v[28:31], v[156:159], v[200:203], v[28:31]
	s_waitcnt lgkmcnt(1)
	v_mfma_f32_16x16x32_bf16 v[64:67], v[144:147], v[204:207], v[64:67]
	v_mfma_f32_16x16x32_bf16 v[72:75], v[148:151], v[204:207], v[72:75]
	v_mfma_f32_16x16x32_bf16 v[0:3], v[152:155], v[204:207], v[0:3]
	v_mfma_f32_16x16x32_bf16 v[8:11], v[156:159], v[204:207], v[8:11]
	s_waitcnt lgkmcnt(0)
	v_mfma_f32_16x16x32_bf16 v[68:71], v[144:147], v[242:245], v[68:71]
	v_mfma_f32_16x16x32_bf16 v[76:79], v[148:151], v[242:245], v[76:79]
	v_mfma_f32_16x16x32_bf16 v[4:7], v[152:155], v[242:245], v[4:7]
	v_mfma_f32_16x16x32_bf16 v[12:15], v[156:159], v[242:245], v[12:15]
	global_load_dwordx4 v[144:147], v[248:249], off
	global_load_dwordx4 v[148:151], v[248:249], off offset:256
	global_load_dwordx4 v[152:155], v[250:251], off
	global_load_dwordx4 v[156:159], v[250:251], off offset:256
	s_waitcnt vmcnt(8)
	s_barrier
	s_add_i32 s9, s3, 4
	s_lshl_b32 s96, s9, 13
	s_mov_b32 m0, vcc_lo
	v_lshl_add_u64 v[160:161], v[188:189], 0, s[96:97]
	global_load_lds_dwordx4 v[160:161], off
	global_load_lds_dwordx4 v[160:161], off offset:1024
	s_add_i32 s9, s3, 5
	s_lshl_b32 s96, s9, 13
	s_add_i32 m0, vcc_lo, 8192
	v_lshl_add_u64 v[160:161], v[188:189], 0, s[96:97]
	global_load_lds_dwordx4 v[160:161], off
	global_load_lds_dwordx4 v[160:161], off offset:1024
	ds_read_b128 v[196:199], v246 offset:16384
	ds_read_b128 v[200:203], v246 offset:17408
	ds_read_b128 v[204:207], v246 offset:18432
	ds_read_b128 v[242:245], v246 offset:19456
	s_add_i32 s9, s3, 4
	s_lshl_b32 s96, s9, 11
	v_lshl_add_u64 v[248:249], v[184:185], 0, s[96:97]
	v_lshl_add_u64 v[250:251], v[186:187], 0, s[96:97]
	s_waitcnt vmcnt(8) lgkmcnt(3)
	v_mfma_f32_16x16x32_bf16 v[112:115], v[128:131], v[196:199], v[112:115]
	v_mfma_f32_16x16x32_bf16 v[120:123], v[132:135], v[196:199], v[120:123]
	v_mfma_f32_16x16x32_bf16 v[48:51], v[136:139], v[196:199], v[48:51]
	v_mfma_f32_16x16x32_bf16 v[56:59], v[140:143], v[196:199], v[56:59]
	ds_read_b128 v[196:199], v246 offset:20480
	s_waitcnt lgkmcnt(3)
	v_mfma_f32_16x16x32_bf16 v[116:119], v[128:131], v[200:203], v[116:119]
	v_mfma_f32_16x16x32_bf16 v[124:127], v[132:135], v[200:203], v[124:127]
	v_mfma_f32_16x16x32_bf16 v[52:55], v[136:139], v[200:203], v[52:55]
	v_mfma_f32_16x16x32_bf16 v[60:63], v[140:143], v[200:203], v[60:63]
	ds_read_b128 v[200:203], v246 offset:21504
	s_waitcnt lgkmcnt(3)
	v_mfma_f32_16x16x32_bf16 v[96:99], v[128:131], v[204:207], v[96:99]
	v_mfma_f32_16x16x32_bf16 v[104:107], v[132:135], v[204:207], v[104:107]
	v_mfma_f32_16x16x32_bf16 v[32:35], v[136:139], v[204:207], v[32:35]
	v_mfma_f32_16x16x32_bf16 v[40:43], v[140:143], v[204:207], v[40:43]
	ds_read_b128 v[204:207], v246 offset:22528
	s_waitcnt lgkmcnt(3)
	v_mfma_f32_16x16x32_bf16 v[100:103], v[128:131], v[242:245], v[100:103]
	v_mfma_f32_16x16x32_bf16 v[108:111], v[132:135], v[242:245], v[108:111]
	v_mfma_f32_16x16x32_bf16 v[36:39], v[136:139], v[242:245], v[36:39]
	v_mfma_f32_16x16x32_bf16 v[44:47], v[140:143], v[242:245], v[44:47]
	ds_read_b128 v[242:245], v246 offset:23552
	s_waitcnt lgkmcnt(3)
	v_mfma_f32_16x16x32_bf16 v[80:83], v[128:131], v[196:199], v[80:83]
	v_mfma_f32_16x16x32_bf16 v[88:91], v[132:135], v[196:199], v[88:91]
	v_mfma_f32_16x16x32_bf16 v[16:19], v[136:139], v[196:199], v[16:19]
	v_mfma_f32_16x16x32_bf16 v[24:27], v[140:143], v[196:199], v[24:27]
	s_waitcnt lgkmcnt(2)
	v_mfma_f32_16x16x32_bf16 v[84:87], v[128:131], v[200:203], v[84:87]
	v_mfma_f32_16x16x32_bf16 v[92:95], v[132:135], v[200:203], v[92:95]
	v_mfma_f32_16x16x32_bf16 v[20:23], v[136:139], v[200:203], v[20:23]
	v_mfma_f32_16x16x32_bf16 v[28:31], v[140:143], v[200:203], v[28:31]
	s_waitcnt lgkmcnt(1)
	v_mfma_f32_16x16x32_bf16 v[64:67], v[128:131], v[204:207], v[64:67]
	v_mfma_f32_16x16x32_bf16 v[72:75], v[132:135], v[204:207], v[72:75]
	v_mfma_f32_16x16x32_bf16 v[0:3], v[136:139], v[204:207], v[0:3]
	v_mfma_f32_16x16x32_bf16 v[8:11], v[140:143], v[204:207], v[8:11]
	s_waitcnt lgkmcnt(0)
	v_mfma_f32_16x16x32_bf16 v[68:71], v[128:131], v[242:245], v[68:71]
	v_mfma_f32_16x16x32_bf16 v[76:79], v[132:135], v[242:245], v[76:79]
	v_mfma_f32_16x16x32_bf16 v[4:7], v[136:139], v[242:245], v[4:7]
	v_mfma_f32_16x16x32_bf16 v[12:15], v[140:143], v[242:245], v[12:15]
	global_load_dwordx4 v[128:131], v[248:249], off
	global_load_dwordx4 v[132:135], v[248:249], off offset:256
	global_load_dwordx4 v[136:139], v[250:251], off
	global_load_dwordx4 v[140:143], v[250:251], off offset:256
	ds_read_b128 v[196:199], v246 offset:24576
	ds_read_b128 v[200:203], v246 offset:25600
	ds_read_b128 v[204:207], v246 offset:26624
	ds_read_b128 v[242:245], v246 offset:27648
	s_add_i32 s9, s3, 5
	s_lshl_b32 s96, s9, 11
	v_lshl_add_u64 v[248:249], v[184:185], 0, s[96:97]
	v_lshl_add_u64 v[250:251], v[186:187], 0, s[96:97]
	s_waitcnt vmcnt(8) lgkmcnt(3)
	v_mfma_f32_16x16x32_bf16 v[112:115], v[144:147], v[196:199], v[112:115]
	v_mfma_f32_16x16x32_bf16 v[120:123], v[148:151], v[196:199], v[120:123]
	v_mfma_f32_16x16x32_bf16 v[48:51], v[152:155], v[196:199], v[48:51]
	v_mfma_f32_16x16x32_bf16 v[56:59], v[156:159], v[196:199], v[56:59]
	ds_read_b128 v[196:199], v246 offset:28672
	s_waitcnt lgkmcnt(3)
	v_mfma_f32_16x16x32_bf16 v[116:119], v[144:147], v[200:203], v[116:119]
	v_mfma_f32_16x16x32_bf16 v[124:127], v[148:151], v[200:203], v[124:127]
	v_mfma_f32_16x16x32_bf16 v[52:55], v[152:155], v[200:203], v[52:55]
	v_mfma_f32_16x16x32_bf16 v[60:63], v[156:159], v[200:203], v[60:63]
	ds_read_b128 v[200:203], v246 offset:29696
	s_waitcnt lgkmcnt(3)
	v_mfma_f32_16x16x32_bf16 v[96:99], v[144:147], v[204:207], v[96:99]
	v_mfma_f32_16x16x32_bf16 v[104:107], v[148:151], v[204:207], v[104:107]
	v_mfma_f32_16x16x32_bf16 v[32:35], v[152:155], v[204:207], v[32:35]
	v_mfma_f32_16x16x32_bf16 v[40:43], v[156:159], v[204:207], v[40:43]
	ds_read_b128 v[204:207], v246 offset:30720
	s_waitcnt lgkmcnt(3)
	v_mfma_f32_16x16x32_bf16 v[100:103], v[144:147], v[242:245], v[100:103]
	v_mfma_f32_16x16x32_bf16 v[108:111], v[148:151], v[242:245], v[108:111]
	v_mfma_f32_16x16x32_bf16 v[36:39], v[152:155], v[242:245], v[36:39]
	v_mfma_f32_16x16x32_bf16 v[44:47], v[156:159], v[242:245], v[44:47]
	ds_read_b128 v[242:245], v246 offset:31744
	s_waitcnt lgkmcnt(3)
	v_mfma_f32_16x16x32_bf16 v[80:83], v[144:147], v[196:199], v[80:83]
	v_mfma_f32_16x16x32_bf16 v[88:91], v[148:151], v[196:199], v[88:91]
	v_mfma_f32_16x16x32_bf16 v[16:19], v[152:155], v[196:199], v[16:19]
	v_mfma_f32_16x16x32_bf16 v[24:27], v[156:159], v[196:199], v[24:27]
	s_waitcnt lgkmcnt(2)
	v_mfma_f32_16x16x32_bf16 v[84:87], v[144:147], v[200:203], v[84:87]
	v_mfma_f32_16x16x32_bf16 v[92:95], v[148:151], v[200:203], v[92:95]
	v_mfma_f32_16x16x32_bf16 v[20:23], v[152:155], v[200:203], v[20:23]
	v_mfma_f32_16x16x32_bf16 v[28:31], v[156:159], v[200:203], v[28:31]
	s_waitcnt lgkmcnt(1)
	v_mfma_f32_16x16x32_bf16 v[64:67], v[144:147], v[204:207], v[64:67]
	v_mfma_f32_16x16x32_bf16 v[72:75], v[148:151], v[204:207], v[72:75]
	v_mfma_f32_16x16x32_bf16 v[0:3], v[152:155], v[204:207], v[0:3]
	v_mfma_f32_16x16x32_bf16 v[8:11], v[156:159], v[204:207], v[8:11]
	s_waitcnt lgkmcnt(0)
	v_mfma_f32_16x16x32_bf16 v[68:71], v[144:147], v[242:245], v[68:71]
	v_mfma_f32_16x16x32_bf16 v[76:79], v[148:151], v[242:245], v[76:79]
	v_mfma_f32_16x16x32_bf16 v[4:7], v[152:155], v[242:245], v[4:7]
	v_mfma_f32_16x16x32_bf16 v[12:15], v[156:159], v[242:245], v[12:15]
	global_load_dwordx4 v[144:147], v[248:249], off
	global_load_dwordx4 v[148:151], v[248:249], off offset:256
	global_load_dwordx4 v[152:155], v[250:251], off
	global_load_dwordx4 v[156:159], v[250:251], off offset:256
	s_waitcnt vmcnt(8)
	s_barrier
	s_add_i32 s3, s3, 4
	s_cmp_lt_u32 s3, 28
	s_cbranch_scc1 .Lg16_out_k
	s_mov_b32 s96, 0x3c000
	s_add_i32 m0, vcc_lo, 16384
	v_lshl_add_u64 v[160:161], v[188:189], 0, s[96:97]
	global_load_lds_dwordx4 v[160:161], off
	global_load_lds_dwordx4 v[160:161], off offset:1024
	s_mov_b32 s96, 0x3e000
	s_add_i32 m0, vcc_lo, 24576
	v_lshl_add_u64 v[160:161], v[188:189], 0, s[96:97]
	global_load_lds_dwordx4 v[160:161], off
	global_load_lds_dwordx4 v[160:161], off offset:1024
	ds_read_b128 v[196:199], v246 offset:0
	ds_read_b128 v[200:203], v246 offset:1024
	ds_read_b128 v[204:207], v246 offset:2048
	ds_read_b128 v[242:245], v246 offset:3072
	s_mov_b32 s96, 0xf000
	v_lshl_add_u64 v[248:249], v[184:185], 0, s[96:97]
	v_lshl_add_u64 v[250:251], v[186:187], 0, s[96:97]
	s_waitcnt vmcnt(8) lgkmcnt(3)
	v_mfma_f32_16x16x32_bf16 v[112:115], v[128:131], v[196:199], v[112:115]
	v_mfma_f32_16x16x32_bf16 v[120:123], v[132:135], v[196:199], v[120:123]
	v_mfma_f32_16x16x32_bf16 v[48:51], v[136:139], v[196:199], v[48:51]
	v_mfma_f32_16x16x32_bf16 v[56:59], v[140:143], v[196:199], v[56:59]
	ds_read_b128 v[196:199], v246 offset:4096
	s_waitcnt lgkmcnt(3)
	v_mfma_f32_16x16x32_bf16 v[116:119], v[128:131], v[200:203], v[116:119]
	v_mfma_f32_16x16x32_bf16 v[124:127], v[132:135], v[200:203], v[124:127]
	v_mfma_f32_16x16x32_bf16 v[52:55], v[136:139], v[200:203], v[52:55]
	v_mfma_f32_16x16x32_bf16 v[60:63], v[140:143], v[200:203], v[60:63]
	ds_read_b128 v[200:203], v246 offset:5120
	s_waitcnt lgkmcnt(3)
	v_mfma_f32_16x16x32_bf16 v[96:99], v[128:131], v[204:207], v[96:99]
	v_mfma_f32_16x16x32_bf16 v[104:107], v[132:135], v[204:207], v[104:107]
	v_mfma_f32_16x16x32_bf16 v[32:35], v[136:139], v[204:207], v[32:35]
	v_mfma_f32_16x16x32_bf16 v[40:43], v[140:143], v[204:207], v[40:43]
	ds_read_b128 v[204:207], v246 offset:6144
	s_waitcnt lgkmcnt(3)
	v_mfma_f32_16x16x32_bf16 v[100:103], v[128:131], v[242:245], v[100:103]
	v_mfma_f32_16x16x32_bf16 v[108:111], v[132:135], v[242:245], v[108:111]
	v_mfma_f32_16x16x32_bf16 v[36:39], v[136:139], v[242:245], v[36:39]
	v_mfma_f32_16x16x32_bf16 v[44:47], v[140:143], v[242:245], v[44:47]
	ds_read_b128 v[242:245], v246 offset:7168
	s_waitcnt lgkmcnt(3)
	v_mfma_f32_16x16x32_bf16 v[80:83], v[128:131], v[196:199], v[80:83]
	v_mfma_f32_16x16x32_bf16 v[88:91], v[132:135], v[196:199], v[88:91]
	v_mfma_f32_16x16x32_bf16 v[16:19], v[136:139], v[196:199], v[16:19]
	v_mfma_f32_16x16x32_bf16 v[24:27], v[140:143], v[196:199], v[24:27]
	s_waitcnt lgkmcnt(2)
	v_mfma_f32_16x16x32_bf16 v[84:87], v[128:131], v[200:203], v[84:87]
	v_mfma_f32_16x16x32_bf16 v[92:95], v[132:135], v[200:203], v[92:95]
	v_mfma_f32_16x16x32_bf16 v[20:23], v[136:139], v[200:203], v[20:23]
	v_mfma_f32_16x16x32_bf16 v[28:31], v[140:143], v[200:203], v[28:31]
	s_waitcnt lgkmcnt(1)
	v_mfma_f32_16x16x32_bf16 v[64:67], v[128:131], v[204:207], v[64:67]
	v_mfma_f32_16x16x32_bf16 v[72:75], v[132:135], v[204:207], v[72:75]
	v_mfma_f32_16x16x32_bf16 v[0:3], v[136:139], v[204:207], v[0:3]
	v_mfma_f32_16x16x32_bf16 v[8:11], v[140:143], v[204:207], v[8:11]
	s_waitcnt lgkmcnt(0)
	v_mfma_f32_16x16x32_bf16 v[68:71], v[128:131], v[242:245], v[68:71]
	v_mfma_f32_16x16x32_bf16 v[76:79], v[132:135], v[242:245], v[76:79]
	v_mfma_f32_16x16x32_bf16 v[4:7], v[136:139], v[242:245], v[4:7]
	v_mfma_f32_16x16x32_bf16 v[12:15], v[140:143], v[242:245], v[12:15]
	global_load_dwordx4 v[128:131], v[248:249], off
	global_load_dwordx4 v[132:135], v[248:249], off offset:256
	global_load_dwordx4 v[136:139], v[250:251], off
	global_load_dwordx4 v[140:143], v[250:251], off offset:256
	ds_read_b128 v[196:199], v246 offset:8192
	ds_read_b128 v[200:203], v246 offset:9216
	ds_read_b128 v[204:207], v246 offset:10240
	ds_read_b128 v[242:245], v246 offset:11264
	s_mov_b32 s96, 0xf800
	v_lshl_add_u64 v[248:249], v[184:185], 0, s[96:97]
	v_lshl_add_u64 v[250:251], v[186:187], 0, s[96:97]
	s_waitcnt vmcnt(8) lgkmcnt(3)
	v_mfma_f32_16x16x32_bf16 v[112:115], v[144:147], v[196:199], v[112:115]
	v_mfma_f32_16x16x32_bf16 v[120:123], v[148:151], v[196:199], v[120:123]
	v_mfma_f32_16x16x32_bf16 v[48:51], v[152:155], v[196:199], v[48:51]
	v_mfma_f32_16x16x32_bf16 v[56:59], v[156:159], v[196:199], v[56:59]
	ds_read_b128 v[196:199], v246 offset:12288
	s_waitcnt lgkmcnt(3)
	v_mfma_f32_16x16x32_bf16 v[116:119], v[144:147], v[200:203], v[116:119]
	v_mfma_f32_16x16x32_bf16 v[124:127], v[148:151], v[200:203], v[124:127]
	v_mfma_f32_16x16x32_bf16 v[52:55], v[152:155], v[200:203], v[52:55]
	v_mfma_f32_16x16x32_bf16 v[60:63], v[156:159], v[200:203], v[60:63]
	ds_read_b128 v[200:203], v246 offset:13312
	s_waitcnt lgkmcnt(3)
	v_mfma_f32_16x16x32_bf16 v[96:99], v[144:147], v[204:207], v[96:99]
	v_mfma_f32_16x16x32_bf16 v[104:107], v[148:151], v[204:207], v[104:107]
	v_mfma_f32_16x16x32_bf16 v[32:35], v[152:155], v[204:207], v[32:35]
	v_mfma_f32_16x16x32_bf16 v[40:43], v[156:159], v[204:207], v[40:43]
	ds_read_b128 v[204:207], v246 offset:14336
	s_waitcnt lgkmcnt(3)
	v_mfma_f32_16x16x32_bf16 v[100:103], v[144:147], v[242:245], v[100:103]
	v_mfma_f32_16x16x32_bf16 v[108:111], v[148:151], v[242:245], v[108:111]
	v_mfma_f32_16x16x32_bf16 v[36:39], v[152:155], v[242:245], v[36:39]
	v_mfma_f32_16x16x32_bf16 v[44:47], v[156:159], v[242:245], v[44:47]
	ds_read_b128 v[242:245], v246 offset:15360
	s_waitcnt lgkmcnt(3)
	v_mfma_f32_16x16x32_bf16 v[80:83], v[144:147], v[196:199], v[80:83]
	v_mfma_f32_16x16x32_bf16 v[88:91], v[148:151], v[196:199], v[88:91]
	v_mfma_f32_16x16x32_bf16 v[16:19], v[152:155], v[196:199], v[16:19]
	v_mfma_f32_16x16x32_bf16 v[24:27], v[156:159], v[196:199], v[24:27]
	s_waitcnt lgkmcnt(2)
	v_mfma_f32_16x16x32_bf16 v[84:87], v[144:147], v[200:203], v[84:87]
	v_mfma_f32_16x16x32_bf16 v[92:95], v[148:151], v[200:203], v[92:95]
	v_mfma_f32_16x16x32_bf16 v[20:23], v[152:155], v[200:203], v[20:23]
	v_mfma_f32_16x16x32_bf16 v[28:31], v[156:159], v[200:203], v[28:31]
	s_waitcnt lgkmcnt(1)
	v_mfma_f32_16x16x32_bf16 v[64:67], v[144:147], v[204:207], v[64:67]
	v_mfma_f32_16x16x32_bf16 v[72:75], v[148:151], v[204:207], v[72:75]
	v_mfma_f32_16x16x32_bf16 v[0:3], v[152:155], v[204:207], v[0:3]
	v_mfma_f32_16x16x32_bf16 v[8:11], v[156:159], v[204:207], v[8:11]
	s_waitcnt lgkmcnt(0)
	v_mfma_f32_16x16x32_bf16 v[68:71], v[144:147], v[242:245], v[68:71]
	v_mfma_f32_16x16x32_bf16 v[76:79], v[148:151], v[242:245], v[76:79]
	v_mfma_f32_16x16x32_bf16 v[4:7], v[152:155], v[242:245], v[4:7]
	v_mfma_f32_16x16x32_bf16 v[12:15], v[156:159], v[242:245], v[12:15]
	global_load_dwordx4 v[144:147], v[248:249], off
	global_load_dwordx4 v[148:151], v[248:249], off offset:256
	global_load_dwordx4 v[152:155], v[250:251], off
	global_load_dwordx4 v[156:159], v[250:251], off offset:256
	s_waitcnt vmcnt(8)
	s_barrier
	ds_read_b128 v[196:199], v246 offset:16384
	ds_read_b128 v[200:203], v246 offset:17408
	ds_read_b128 v[204:207], v246 offset:18432
	ds_read_b128 v[242:245], v246 offset:19456
	s_waitcnt vmcnt(4) lgkmcnt(3)
	v_mfma_f32_16x16x32_bf16 v[112:115], v[128:131], v[196:199], v[112:115]
	v_mfma_f32_16x16x32_bf16 v[120:123], v[132:135], v[196:199], v[120:123]
	v_mfma_f32_16x16x32_bf16 v[48:51], v[136:139], v[196:199], v[48:51]
	v_mfma_f32_16x16x32_bf16 v[56:59], v[140:143], v[196:199], v[56:59]
	ds_read_b128 v[196:199], v246 offset:20480
	s_waitcnt lgkmcnt(3)
	v_mfma_f32_16x16x32_bf16 v[116:119], v[128:131], v[200:203], v[116:119]
	v_mfma_f32_16x16x32_bf16 v[124:127], v[132:135], v[200:203], v[124:127]
	v_mfma_f32_16x16x32_bf16 v[52:55], v[136:139], v[200:203], v[52:55]
	v_mfma_f32_16x16x32_bf16 v[60:63], v[140:143], v[200:203], v[60:63]
	ds_read_b128 v[200:203], v246 offset:21504
	s_waitcnt lgkmcnt(3)
	v_mfma_f32_16x16x32_bf16 v[96:99], v[128:131], v[204:207], v[96:99]
	v_mfma_f32_16x16x32_bf16 v[104:107], v[132:135], v[204:207], v[104:107]
	v_mfma_f32_16x16x32_bf16 v[32:35], v[136:139], v[204:207], v[32:35]
	v_mfma_f32_16x16x32_bf16 v[40:43], v[140:143], v[204:207], v[40:43]
	ds_read_b128 v[204:207], v246 offset:22528
	s_waitcnt lgkmcnt(3)
	v_mfma_f32_16x16x32_bf16 v[100:103], v[128:131], v[242:245], v[100:103]
	v_mfma_f32_16x16x32_bf16 v[108:111], v[132:135], v[242:245], v[108:111]
	v_mfma_f32_16x16x32_bf16 v[36:39], v[136:139], v[242:245], v[36:39]
	v_mfma_f32_16x16x32_bf16 v[44:47], v[140:143], v[242:245], v[44:47]
	ds_read_b128 v[242:245], v246 offset:23552
	s_waitcnt lgkmcnt(3)
	v_mfma_f32_16x16x32_bf16 v[80:83], v[128:131], v[196:199], v[80:83]
	v_mfma_f32_16x16x32_bf16 v[88:91], v[132:135], v[196:199], v[88:91]
	v_mfma_f32_16x16x32_bf16 v[16:19], v[136:139], v[196:199], v[16:19]
	v_mfma_f32_16x16x32_bf16 v[24:27], v[140:143], v[196:199], v[24:27]
	s_waitcnt lgkmcnt(2)
	v_mfma_f32_16x16x32_bf16 v[84:87], v[128:131], v[200:203], v[84:87]
	v_mfma_f32_16x16x32_bf16 v[92:95], v[132:135], v[200:203], v[92:95]
	v_mfma_f32_16x16x32_bf16 v[20:23], v[136:139], v[200:203], v[20:23]
	v_mfma_f32_16x16x32_bf16 v[28:31], v[140:143], v[200:203], v[28:31]
	s_waitcnt lgkmcnt(1)
	v_mfma_f32_16x16x32_bf16 v[64:67], v[128:131], v[204:207], v[64:67]
	v_mfma_f32_16x16x32_bf16 v[72:75], v[132:135], v[204:207], v[72:75]
	v_mfma_f32_16x16x32_bf16 v[0:3], v[136:139], v[204:207], v[0:3]
	v_mfma_f32_16x16x32_bf16 v[8:11], v[140:143], v[204:207], v[8:11]
	s_waitcnt lgkmcnt(0)
	v_mfma_f32_16x16x32_bf16 v[68:71], v[128:131], v[242:245], v[68:71]
	v_mfma_f32_16x16x32_bf16 v[76:79], v[132:135], v[242:245], v[76:79]
	v_mfma_f32_16x16x32_bf16 v[4:7], v[136:139], v[242:245], v[4:7]
	v_mfma_f32_16x16x32_bf16 v[12:15], v[140:143], v[242:245], v[12:15]
	ds_read_b128 v[196:199], v246 offset:24576
	ds_read_b128 v[200:203], v246 offset:25600
	ds_read_b128 v[204:207], v246 offset:26624
	ds_read_b128 v[242:245], v246 offset:27648
	s_waitcnt vmcnt(0) lgkmcnt(3)
	v_mfma_f32_16x16x32_bf16 v[112:115], v[144:147], v[196:199], v[112:115]
	v_mfma_f32_16x16x32_bf16 v[120:123], v[148:151], v[196:199], v[120:123]
	v_mfma_f32_16x16x32_bf16 v[48:51], v[152:155], v[196:199], v[48:51]
	v_mfma_f32_16x16x32_bf16 v[56:59], v[156:159], v[196:199], v[56:59]
	ds_read_b128 v[196:199], v246 offset:28672
	s_waitcnt lgkmcnt(3)
	v_mfma_f32_16x16x32_bf16 v[116:119], v[144:147], v[200:203], v[116:119]
	v_mfma_f32_16x16x32_bf16 v[124:127], v[148:151], v[200:203], v[124:127]
	v_mfma_f32_16x16x32_bf16 v[52:55], v[152:155], v[200:203], v[52:55]
	v_mfma_f32_16x16x32_bf16 v[60:63], v[156:159], v[200:203], v[60:63]
	ds_read_b128 v[200:203], v246 offset:29696
	s_waitcnt lgkmcnt(3)
	v_mfma_f32_16x16x32_bf16 v[96:99], v[144:147], v[204:207], v[96:99]
	v_mfma_f32_16x16x32_bf16 v[104:107], v[148:151], v[204:207], v[104:107]
	v_mfma_f32_16x16x32_bf16 v[32:35], v[152:155], v[204:207], v[32:35]
	v_mfma_f32_16x16x32_bf16 v[40:43], v[156:159], v[204:207], v[40:43]
	ds_read_b128 v[204:207], v246 offset:30720
	s_waitcnt lgkmcnt(3)
	v_mfma_f32_16x16x32_bf16 v[100:103], v[144:147], v[242:245], v[100:103]
	v_mfma_f32_16x16x32_bf16 v[108:111], v[148:151], v[242:245], v[108:111]
	v_mfma_f32_16x16x32_bf16 v[36:39], v[152:155], v[242:245], v[36:39]
	v_mfma_f32_16x16x32_bf16 v[44:47], v[156:159], v[242:245], v[44:47]
	ds_read_b128 v[242:245], v246 offset:31744
	v_permlane16_swap_b32_e32 v112, v116
	v_permlane16_swap_b32_e32 v113, v117
	v_permlane16_swap_b32_e32 v114, v118
	v_permlane16_swap_b32_e32 v115, v119
	v_permlane16_swap_b32_e32 v120, v124
	v_permlane16_swap_b32_e32 v121, v125
	v_permlane16_swap_b32_e32 v122, v126
	v_permlane16_swap_b32_e32 v123, v127
	v_permlane16_swap_b32_e32 v48, v52
	v_permlane16_swap_b32_e32 v49, v53
	v_permlane16_swap_b32_e32 v50, v54
	v_permlane16_swap_b32_e32 v51, v55
	v_permlane16_swap_b32_e32 v56, v60
	v_permlane16_swap_b32_e32 v57, v61
	v_permlane16_swap_b32_e32 v58, v62
	v_permlane16_swap_b32_e32 v59, v63
	v_permlane32_swap_b32_e32 v112, v116
	v_permlane32_swap_b32_e32 v113, v117
	v_permlane32_swap_b32_e32 v114, v118
	v_permlane32_swap_b32_e32 v115, v119
	v_permlane32_swap_b32_e32 v120, v124
	v_permlane32_swap_b32_e32 v121, v125
	v_permlane32_swap_b32_e32 v122, v126
	v_permlane32_swap_b32_e32 v123, v127
	v_permlane32_swap_b32_e32 v48, v52
	v_permlane32_swap_b32_e32 v49, v53
	v_permlane32_swap_b32_e32 v50, v54
	v_permlane32_swap_b32_e32 v51, v55
	v_permlane32_swap_b32_e32 v56, v60
	v_permlane32_swap_b32_e32 v57, v61
	v_permlane32_swap_b32_e32 v58, v62
	v_permlane32_swap_b32_e32 v59, v63
	s_waitcnt lgkmcnt(3)
	v_mfma_f32_16x16x32_bf16 v[80:83], v[144:147], v[196:199], v[80:83]
	v_mfma_f32_16x16x32_bf16 v[88:91], v[148:151], v[196:199], v[88:91]
	v_mfma_f32_16x16x32_bf16 v[16:19], v[152:155], v[196:199], v[16:19]
	v_mfma_f32_16x16x32_bf16 v[24:27], v[156:159], v[196:199], v[24:27]
	s_waitcnt lgkmcnt(2)
	v_mfma_f32_16x16x32_bf16 v[84:87], v[144:147], v[200:203], v[84:87]
	v_mfma_f32_16x16x32_bf16 v[92:95], v[148:151], v[200:203], v[92:95]
	v_mfma_f32_16x16x32_bf16 v[20:23], v[152:155], v[200:203], v[20:23]
	v_mfma_f32_16x16x32_bf16 v[28:31], v[156:159], v[200:203], v[28:31]
	v_permlane16_swap_b32_e32 v96, v100
	v_permlane16_swap_b32_e32 v97, v101
	v_permlane16_swap_b32_e32 v98, v102
	v_permlane16_swap_b32_e32 v99, v103
	v_permlane16_swap_b32_e32 v104, v108
	v_permlane16_swap_b32_e32 v105, v109
	v_permlane16_swap_b32_e32 v106, v110
	v_permlane16_swap_b32_e32 v107, v111
	v_permlane16_swap_b32_e32 v32, v36
	v_permlane16_swap_b32_e32 v33, v37
	v_permlane16_swap_b32_e32 v34, v38
	v_permlane16_swap_b32_e32 v35, v39
	v_permlane16_swap_b32_e32 v40, v44
	v_permlane16_swap_b32_e32 v41, v45
	v_permlane16_swap_b32_e32 v42, v46
	v_permlane16_swap_b32_e32 v43, v47
	v_permlane32_swap_b32_e32 v96, v100
	v_permlane32_swap_b32_e32 v97, v101
	v_permlane32_swap_b32_e32 v98, v102
	v_permlane32_swap_b32_e32 v99, v103
	v_permlane32_swap_b32_e32 v104, v108
	v_permlane32_swap_b32_e32 v105, v109
	v_permlane32_swap_b32_e32 v106, v110
	v_permlane32_swap_b32_e32 v107, v111
	v_permlane32_swap_b32_e32 v32, v36
	v_permlane32_swap_b32_e32 v33, v37
	v_permlane32_swap_b32_e32 v34, v38
	v_permlane32_swap_b32_e32 v35, v39
	v_permlane32_swap_b32_e32 v40, v44
	v_permlane32_swap_b32_e32 v41, v45
	v_permlane32_swap_b32_e32 v42, v46
	v_permlane32_swap_b32_e32 v43, v47
	s_waitcnt lgkmcnt(1)
	v_mfma_f32_16x16x32_bf16 v[64:67], v[144:147], v[204:207], v[64:67]
	v_mfma_f32_16x16x32_bf16 v[72:75], v[148:151], v[204:207], v[72:75]
	v_mfma_f32_16x16x32_bf16 v[0:3], v[152:155], v[204:207], v[0:3]
	v_mfma_f32_16x16x32_bf16 v[8:11], v[156:159], v[204:207], v[8:11]
	s_waitcnt lgkmcnt(0)
	v_mfma_f32_16x16x32_bf16 v[68:71], v[144:147], v[242:245], v[68:71]
	v_mfma_f32_16x16x32_bf16 v[76:79], v[148:151], v[242:245], v[76:79]
	v_mfma_f32_16x16x32_bf16 v[4:7], v[152:155], v[242:245], v[4:7]
	v_mfma_f32_16x16x32_bf16 v[12:15], v[156:159], v[242:245], v[12:15]
	v_permlane16_swap_b32_e32 v80, v84
	v_permlane16_swap_b32_e32 v81, v85
	v_permlane16_swap_b32_e32 v82, v86
	v_permlane16_swap_b32_e32 v83, v87
	v_permlane16_swap_b32_e32 v88, v92
	v_permlane16_swap_b32_e32 v89, v93
	v_permlane16_swap_b32_e32 v90, v94
	v_permlane16_swap_b32_e32 v91, v95
	v_permlane16_swap_b32_e32 v16, v20
	v_permlane16_swap_b32_e32 v17, v21
	v_permlane16_swap_b32_e32 v18, v22
	v_permlane16_swap_b32_e32 v19, v23
	v_permlane16_swap_b32_e32 v24, v28
	v_permlane16_swap_b32_e32 v25, v29
	v_permlane16_swap_b32_e32 v26, v30
	v_permlane16_swap_b32_e32 v27, v31
	v_permlane32_swap_b32_e32 v80, v84
	v_permlane32_swap_b32_e32 v81, v85
	v_permlane32_swap_b32_e32 v82, v86
	v_permlane32_swap_b32_e32 v83, v87
	v_permlane32_swap_b32_e32 v88, v92
	v_permlane32_swap_b32_e32 v89, v93
	v_permlane32_swap_b32_e32 v90, v94
	v_permlane32_swap_b32_e32 v91, v95
	v_permlane32_swap_b32_e32 v16, v20
	v_permlane32_swap_b32_e32 v17, v21
	v_permlane32_swap_b32_e32 v18, v22
	v_permlane32_swap_b32_e32 v19, v23
	v_permlane32_swap_b32_e32 v24, v28
	v_permlane32_swap_b32_e32 v25, v29
	v_permlane32_swap_b32_e32 v26, v30
	v_permlane32_swap_b32_e32 v27, v31
	s_barrier
	s_nop 7
	v_permlane16_swap_b32_e32 v64, v68
	v_permlane16_swap_b32_e32 v65, v69
	v_permlane16_swap_b32_e32 v66, v70
	v_permlane16_swap_b32_e32 v67, v71
	v_permlane16_swap_b32_e32 v72, v76
	v_permlane16_swap_b32_e32 v73, v77
	v_permlane16_swap_b32_e32 v74, v78
	v_permlane16_swap_b32_e32 v75, v79
	v_permlane16_swap_b32_e32 v0, v4
	v_permlane16_swap_b32_e32 v1, v5
	v_permlane16_swap_b32_e32 v2, v6
	v_permlane16_swap_b32_e32 v3, v7
	v_permlane16_swap_b32_e32 v8, v12
	v_permlane16_swap_b32_e32 v9, v13
	v_permlane16_swap_b32_e32 v10, v14
	v_permlane16_swap_b32_e32 v11, v15
	v_permlane32_swap_b32_e32 v64, v68
	v_permlane32_swap_b32_e32 v65, v69
	v_permlane32_swap_b32_e32 v66, v70
	v_permlane32_swap_b32_e32 v67, v71
	v_permlane32_swap_b32_e32 v72, v76
	v_permlane32_swap_b32_e32 v73, v77
	v_permlane32_swap_b32_e32 v74, v78
	v_permlane32_swap_b32_e32 v75, v79
	v_permlane32_swap_b32_e32 v0, v4
	v_permlane32_swap_b32_e32 v1, v5
	v_permlane32_swap_b32_e32 v2, v6
	v_permlane32_swap_b32_e32 v3, v7
	v_permlane32_swap_b32_e32 v8, v12
	v_permlane32_swap_b32_e32 v9, v13
	v_permlane32_swap_b32_e32 v10, v14
	v_permlane32_swap_b32_e32 v11, v15
	s_waitcnt vmcnt(0)
	s_movk_i32 s3, 0x2400
	s_waitcnt vmcnt(6)
	v_lshlrev_b32_e32 v128, 2, v181
	s_waitcnt vmcnt(0)
	v_and_b32_e32 v133, 0xffffffc0, v181
	v_mul_lo_u32 v129, v237, s3
	v_lshlrev_b32_e32 v130, 2, v238
	v_and_b32_e32 v128, 60, v128
	v_lshl_add_u32 v176, s8, 8, v133
	v_mul_u32_u24_e32 v133, 0x110, v183
	v_or_b32_e32 v131, v129, v130
	v_lshl_or_b32 v132, v128, 2, v129
	v_lshl_or_b32 v128, s2, 7, v128
	v_lshlrev_b32_e32 v133, 2, v133
	v_lshrrev_b32_e32 v175, 4, v239
	s_movk_i32 s2, 0x110
	v_add_u32_e32 v147, v131, v133
	v_add3_u32 v148, v129, v133, v130
	v_mad_u32_u24 v146, v175, s2, v132
	v_readlane_b32 s2, v254, 39
	v_readlane_b32 s8, v253, 36
	v_add_u32_e32 v149, 0x800, v147
	v_add_u32_e32 v150, 0x800, v148
	v_add_u32_e32 v151, 0xa00, v148
	v_mov_b32_e32 v160, s2
	v_readlane_b32 s2, v254, 37
	v_readlane_b32 s9, v253, 37
	v_readlane_b32 s10, v253, 38
	v_readlane_b32 s11, v253, 39
	v_readlane_b32 s12, v253, 40
	v_readlane_b32 s13, v253, 41
	v_readlane_b32 s14, v253, 42
	v_readlane_b32 s15, v253, 43
	v_readlane_b32 s16, v253, 44
	v_readlane_b32 s17, v253, 45
	ds_write2_b32 v147, v112, v113 offset1:68
	ds_write2_b32 v148, v96, v97 offset0:32 offset1:100
	ds_write2_b32 v147, v114, v115 offset0:136 offset1:204
	ds_write2_b32 v148, v98, v99 offset0:168 offset1:236
	ds_write2_b32 v149, v116, v117 offset0:32 offset1:100
	ds_write2_b32 v150, v100, v101 offset0:64 offset1:132
	ds_write2_b32 v149, v118, v119 offset0:168 offset1:236
	ds_write2_b32 v151, v102, v103 offset0:72 offset1:140
	v_or_b32_e32 v102, v176, v175
	v_mov_b32_e32 v161, s2
	v_readlane_b32 s2, v254, 40
	v_readlane_b32 s18, v253, 46
	v_readlane_b32 s19, v253, 47
	v_readlane_b32 s20, v253, 48
	v_readlane_b32 s21, v253, 49
	v_readlane_b32 s22, v253, 50
	v_readlane_b32 s23, v253, 51
	s_mov_b64 s[8:9], s[16:17]
	v_cmp_gt_i32_e32 vcc, s39, v102
	v_add_u32_e32 v96, 0xffff8000, v102
	v_ashrrev_i32_e32 v97, 31, v102
	v_mov_b32_e32 v162, s2
	v_readlane_b32 s2, v254, 38
	s_mov_b64 s[10:11], s[18:19]
	v_cndmask_b32_e32 v97, 0, v97, vcc
	v_cndmask_b32_e32 v96, v96, v102, vcc
	v_mov_b32_e32 v163, s2
	v_mov_b32_e32 v164, s63
	v_mov_b32_e32 v165, s11
	v_mov_b32_e32 v166, s62
	v_mov_b32_e32 v167, s10
	v_min_i32_e32 v102, 0x8000, v102
	v_add_u32_e32 v152, 0x1000, v147
	v_add_u32_e32 v153, 0x1000, v148
	v_add_u32_e32 v154, 0x1200, v147
	v_add_u32_e32 v155, 0x1200, v148
	v_add_u32_e32 v156, 0x1800, v147
	v_add_u32_e32 v157, 0x1800, v148
	v_add_u32_e32 v158, 0x1a00, v147
	v_add_u32_e32 v159, 0x1c00, v148
	v_ashrrev_i32_e32 v129, 31, v128
	v_cndmask_b32_e32 v99, v160, v161, vcc
	v_cndmask_b32_e32 v98, v162, v163, vcc
	v_lshlrev_b64 v[96:97], 12, v[96:97]
	v_cndmask_b32_e32 v101, v164, v165, vcc
	v_cndmask_b32_e32 v100, v166, v167, vcc
	v_ashrrev_i32_e32 v102, 12, v102
	ds_write2_b32 v152, v120, v121 offset0:64 offset1:132
	ds_write2_b32 v153, v104, v105 offset0:96 offset1:164
	ds_write2_b32 v154, v122, v123 offset0:72 offset1:140
	ds_write2_b32 v155, v106, v107 offset0:104 offset1:172
	ds_write2_b32 v156, v124, v125 offset0:96 offset1:164
	ds_write2_b32 v157, v108, v109 offset0:128 offset1:196
	ds_write2_b32 v158, v126, v127 offset0:104 offset1:172
	ds_write2_b32 v159, v110, v111 offset0:8 offset1:76
	v_lshl_add_u64 v[98:99], v[98:99], 0, v[96:97]
	v_lshl_add_u64 v[100:101], v[100:101], 0, v[96:97]
	v_lshlrev_b64 v[96:97], 2, v[128:129]
	v_mul_hi_i32_i24_e32 v103, 0x6000, v102
	v_mul_i32_i24_e32 v102, 0x6000, v102
	s_waitcnt lgkmcnt(0)
	v_lshl_add_u64 v[98:99], v[98:99], 0, v[96:97]
	v_lshl_add_u64 v[102:103], s[0:1], 0, v[102:103]
	v_lshl_add_u64 v[102:103], v[102:103], 0, v[96:97]
	ds_read_b128 v[104:107], v146
	global_load_dwordx4 v[108:111], v[98:99], off
	global_load_dwordx4 v[112:115], v[102:103], off
	v_or_b32_e32 v168, 4, v175
	v_lshl_add_u64 v[100:101], v[100:101], 0, v[96:97]
	v_or_b32_e32 v169, 8, v175
	v_or_b32_e32 v170, 12, v175
	v_or_b32_e32 v171, 16, v175
	v_or_b32_e32 v172, 20, v175
	v_or_b32_e32 v173, 24, v175
	v_or_b32_e32 v174, 28, v175
	v_or_b32_e32 v181, v176, v174
	v_readlane_b32 s2, v254, 11
	s_add_i32 s4, s4, s2
	s_cmp_lt_i32 s4, s26
	s_mov_b64 s[12:13], s[20:21]
	s_mov_b64 s[14:15], s[22:23]
	s_waitcnt vmcnt(0) lgkmcnt(0)
	v_pk_fma_f32 v[104:105], v[104:105], v[112:113], v[108:109]
	v_pk_fma_f32 v[106:107], v[106:107], v[114:115], v[110:111]
	v_or_b32_e32 v110, v176, v168
	global_store_dwordx4 v[100:101], v[104:107], off
	v_cmp_gt_i32_e32 vcc, s39, v110
	s_nop 0
	v_ashrrev_i32_e32 v104, 31, v110
	v_add_u32_e32 v106, 0xffff8000, v110
	v_cndmask_b32_e32 v105, 0, v104, vcc
	v_cndmask_b32_e32 v104, v106, v110, vcc
	v_cndmask_b32_e32 v107, v160, v161, vcc
	v_cndmask_b32_e32 v106, v162, v163, vcc
	v_lshlrev_b64 v[104:105], 12, v[104:105]
	v_cndmask_b32_e32 v109, v164, v165, vcc
	v_cndmask_b32_e32 v108, v166, v167, vcc
	v_lshl_add_u64 v[106:107], v[106:107], 0, v[104:105]
	v_lshl_add_u64 v[104:105], v[108:109], 0, v[104:105]
	v_min_i32_e32 v108, 0x8000, v110
	v_ashrrev_i32_e32 v108, 12, v108
	v_mul_hi_i32_i24_e32 v109, 0x6000, v108
	v_mul_i32_i24_e32 v108, 0x6000, v108
	v_lshl_add_u64 v[106:107], v[106:107], 0, v[96:97]
	v_lshl_add_u64 v[108:109], s[0:1], 0, v[108:109]
	v_lshl_add_u64 v[108:109], v[108:109], 0, v[96:97]
	ds_read_b128 v[110:113], v146 offset:1088
	global_load_dwordx4 v[114:117], v[106:107], off
	global_load_dwordx4 v[118:121], v[108:109], off
	v_lshl_add_u64 v[104:105], v[104:105], 0, v[96:97]
	s_waitcnt vmcnt(0) lgkmcnt(0)
	v_pk_fma_f32 v[110:111], v[110:111], v[118:119], v[114:115]
	v_pk_fma_f32 v[112:113], v[112:113], v[120:121], v[116:117]
	v_or_b32_e32 v118, v176, v169
	global_store_dwordx4 v[104:105], v[110:113], off
	v_cmp_gt_i32_e32 vcc, s39, v118
	s_nop 0
	v_ashrrev_i32_e32 v110, 31, v118
	v_add_u32_e32 v112, 0xffff8000, v118
	v_cndmask_b32_e32 v111, 0, v110, vcc
	v_cndmask_b32_e32 v110, v112, v118, vcc
	v_cndmask_b32_e32 v113, v160, v161, vcc
	v_cndmask_b32_e32 v112, v162, v163, vcc
	v_lshlrev_b64 v[110:111], 12, v[110:111]
	v_lshl_add_u64 v[112:113], v[112:113], 0, v[110:111]
	v_cndmask_b32_e32 v115, v164, v165, vcc
	v_cndmask_b32_e32 v114, v166, v167, vcc
	v_lshl_add_u64 v[116:117], v[114:115], 0, v[110:111]
	v_lshl_add_u64 v[110:111], v[112:113], 0, v[96:97]
	v_min_i32_e32 v112, 0x8000, v118
	v_ashrrev_i32_e32 v112, 12, v112
	v_mul_hi_i32_i24_e32 v113, 0x6000, v112
	v_mul_i32_i24_e32 v112, 0x6000, v112
	v_lshl_add_u64 v[112:113], s[0:1], 0, v[112:113]
	v_lshl_add_u64 v[114:115], v[112:113], 0, v[96:97]
	v_lshl_add_u64 v[112:113], v[116:117], 0, v[96:97]
	ds_read_b128 v[116:119], v146 offset:2176
	global_load_dwordx4 v[120:123], v[110:111], off
	global_load_dwordx4 v[124:127], v[114:115], off
	s_waitcnt vmcnt(0) lgkmcnt(0)
	v_pk_fma_f32 v[116:117], v[116:117], v[124:125], v[120:121]
	v_pk_fma_f32 v[118:119], v[118:119], v[126:127], v[122:123]
	v_or_b32_e32 v124, v176, v170
	global_store_dwordx4 v[112:113], v[116:119], off
	v_cmp_gt_i32_e32 vcc, s39, v124
	s_nop 0
	v_ashrrev_i32_e32 v116, 31, v124
	v_add_u32_e32 v118, 0xffff8000, v124
	v_cndmask_b32_e32 v117, 0, v116, vcc
	v_cndmask_b32_e32 v116, v118, v124, vcc
	v_cndmask_b32_e32 v119, v160, v161, vcc
	v_cndmask_b32_e32 v118, v162, v163, vcc
	v_lshlrev_b64 v[116:117], 12, v[116:117]
	v_lshl_add_u64 v[118:119], v[118:119], 0, v[116:117]
	v_cndmask_b32_e32 v121, v164, v165, vcc
	v_cndmask_b32_e32 v120, v166, v167, vcc
	v_lshl_add_u64 v[122:123], v[120:121], 0, v[116:117]
	v_lshl_add_u64 v[116:117], v[118:119], 0, v[96:97]
	v_min_i32_e32 v118, 0x8000, v124
	v_ashrrev_i32_e32 v118, 12, v118
	v_mul_hi_i32_i24_e32 v119, 0x6000, v118
	v_mul_i32_i24_e32 v118, 0x6000, v118
	v_lshl_add_u64 v[118:119], s[0:1], 0, v[118:119]
	v_lshl_add_u64 v[120:121], v[118:119], 0, v[96:97]
	v_lshl_add_u64 v[118:119], v[122:123], 0, v[96:97]
	ds_read_b128 v[122:125], v146 offset:3264
	global_load_dwordx4 v[126:129], v[116:117], off
	global_load_dwordx4 v[130:133], v[120:121], off
	s_waitcnt vmcnt(0) lgkmcnt(0)
	v_pk_fma_f32 v[122:123], v[122:123], v[130:131], v[126:127]
	v_pk_fma_f32 v[124:125], v[124:125], v[132:133], v[128:129]
	v_or_b32_e32 v130, v176, v171
	global_store_dwordx4 v[118:119], v[122:125], off
	v_cmp_gt_i32_e32 vcc, s39, v130
	s_nop 0
	v_ashrrev_i32_e32 v122, 31, v130
	v_add_u32_e32 v124, 0xffff8000, v130
	v_cndmask_b32_e32 v123, 0, v122, vcc
	v_cndmask_b32_e32 v122, v124, v130, vcc
	v_cndmask_b32_e32 v125, v160, v161, vcc
	v_cndmask_b32_e32 v124, v162, v163, vcc
	v_lshlrev_b64 v[122:123], 12, v[122:123]
	v_lshl_add_u64 v[124:125], v[124:125], 0, v[122:123]
	v_cndmask_b32_e32 v127, v164, v165, vcc
	v_cndmask_b32_e32 v126, v166, v167, vcc
	v_lshl_add_u64 v[128:129], v[126:127], 0, v[122:123]
	v_lshl_add_u64 v[122:123], v[124:125], 0, v[96:97]
	v_min_i32_e32 v124, 0x8000, v130
	v_ashrrev_i32_e32 v124, 12, v124
	v_mul_hi_i32_i24_e32 v125, 0x6000, v124
	v_mul_i32_i24_e32 v124, 0x6000, v124
	v_lshl_add_u64 v[124:125], s[0:1], 0, v[124:125]
	v_lshl_add_u64 v[126:127], v[124:125], 0, v[96:97]
	v_lshl_add_u64 v[124:125], v[128:129], 0, v[96:97]
	ds_read_b128 v[128:131], v146 offset:4352
	global_load_dwordx4 v[132:135], v[122:123], off
	global_load_dwordx4 v[136:139], v[126:127], off
	s_waitcnt vmcnt(0) lgkmcnt(0)
	v_pk_fma_f32 v[128:129], v[128:129], v[136:137], v[132:133]
	v_pk_fma_f32 v[130:131], v[130:131], v[138:139], v[134:135]
	v_or_b32_e32 v136, v176, v172
	global_store_dwordx4 v[124:125], v[128:131], off
	v_cmp_gt_i32_e32 vcc, s39, v136
	s_nop 0
	v_ashrrev_i32_e32 v128, 31, v136
	v_add_u32_e32 v130, 0xffff8000, v136
	v_cndmask_b32_e32 v129, 0, v128, vcc
	v_cndmask_b32_e32 v128, v130, v136, vcc
	v_cndmask_b32_e32 v131, v160, v161, vcc
	v_cndmask_b32_e32 v130, v162, v163, vcc
	v_lshlrev_b64 v[128:129], 12, v[128:129]
	v_lshl_add_u64 v[130:131], v[130:131], 0, v[128:129]
	v_cndmask_b32_e32 v133, v164, v165, vcc
	v_cndmask_b32_e32 v132, v166, v167, vcc
	v_lshl_add_u64 v[134:135], v[132:133], 0, v[128:129]
	v_lshl_add_u64 v[128:129], v[130:131], 0, v[96:97]
	v_min_i32_e32 v130, 0x8000, v136
	v_ashrrev_i32_e32 v130, 12, v130
	v_mul_hi_i32_i24_e32 v131, 0x6000, v130
	v_mul_i32_i24_e32 v130, 0x6000, v130
	v_lshl_add_u64 v[130:131], s[0:1], 0, v[130:131]
	v_lshl_add_u64 v[132:133], v[130:131], 0, v[96:97]
	v_lshl_add_u64 v[130:131], v[134:135], 0, v[96:97]
	ds_read_b128 v[134:137], v146 offset:5440
	global_load_dwordx4 v[138:141], v[128:129], off
	global_load_dwordx4 v[142:145], v[132:133], off
	s_waitcnt vmcnt(0) lgkmcnt(0)
	v_pk_fma_f32 v[134:135], v[134:135], v[142:143], v[138:139]
	v_pk_fma_f32 v[136:137], v[136:137], v[144:145], v[140:141]
	v_or_b32_e32 v142, v176, v173
	global_store_dwordx4 v[130:131], v[134:137], off
	v_cmp_gt_i32_e32 vcc, s39, v142
	s_nop 0
	v_ashrrev_i32_e32 v134, 31, v142
	v_add_u32_e32 v136, 0xffff8000, v142
	v_cndmask_b32_e32 v135, 0, v134, vcc
	v_cndmask_b32_e32 v134, v136, v142, vcc
	v_cndmask_b32_e32 v137, v160, v161, vcc
	v_cndmask_b32_e32 v136, v162, v163, vcc
	v_lshlrev_b64 v[134:135], 12, v[134:135]
	v_lshl_add_u64 v[136:137], v[136:137], 0, v[134:135]
	v_cndmask_b32_e32 v139, v164, v165, vcc
	v_cndmask_b32_e32 v138, v166, v167, vcc
	v_lshl_add_u64 v[140:141], v[138:139], 0, v[134:135]
	v_lshl_add_u64 v[134:135], v[136:137], 0, v[96:97]
	v_min_i32_e32 v136, 0x8000, v142
	v_ashrrev_i32_e32 v136, 12, v136
	v_mul_hi_i32_i24_e32 v137, 0x6000, v136
	v_mul_i32_i24_e32 v136, 0x6000, v136
	v_lshl_add_u64 v[136:137], s[0:1], 0, v[136:137]
	v_lshl_add_u64 v[138:139], v[136:137], 0, v[96:97]
	v_lshl_add_u64 v[136:137], v[140:141], 0, v[96:97]
	ds_read_b128 v[140:143], v146 offset:6528
	global_load_dwordx4 v[184:187], v[134:135], off
	global_load_dwordx4 v[196:199], v[138:139], off
	v_cmp_gt_i32_e32 vcc, s39, v181
	s_waitcnt vmcnt(0) lgkmcnt(0)
	v_pk_fma_f32 v[140:141], v[140:141], v[196:197], v[184:185]
	v_pk_fma_f32 v[142:143], v[142:143], v[198:199], v[186:187]
	global_store_dwordx4 v[136:137], v[140:143], off
	v_cndmask_b32_e32 v145, v164, v165, vcc
	v_cndmask_b32_e32 v144, v166, v167, vcc
	v_ashrrev_i32_e32 v140, 31, v181
	v_add_u32_e32 v142, 0xffff8000, v181
	v_cndmask_b32_e32 v141, 0, v140, vcc
	v_cndmask_b32_e32 v140, v142, v181, vcc
	v_cndmask_b32_e32 v143, v160, v161, vcc
	v_cndmask_b32_e32 v142, v162, v163, vcc
	v_lshlrev_b64 v[140:141], 12, v[140:141]
	v_lshl_add_u64 v[142:143], v[142:143], 0, v[140:141]
	v_lshl_add_u64 v[184:185], v[144:145], 0, v[140:141]
	v_lshl_add_u64 v[140:141], v[142:143], 0, v[96:97]
	v_min_i32_e32 v142, 0x8000, v181
	v_ashrrev_i32_e32 v142, 12, v142
	v_mul_hi_i32_i24_e32 v143, 0x6000, v142
	v_mul_i32_i24_e32 v142, 0x6000, v142
	v_lshl_add_u64 v[142:143], s[0:1], 0, v[142:143]
	v_lshl_add_u64 v[144:145], v[142:143], 0, v[96:97]
	v_lshl_add_u64 v[142:143], v[184:185], 0, v[96:97]
	ds_read_b128 v[184:187], v146 offset:7616
	global_load_dwordx4 v[196:199], v[140:141], off
	global_load_dwordx4 v[200:203], v[144:145], off
	s_waitcnt vmcnt(0) lgkmcnt(0)
	v_pk_fma_f32 v[184:185], v[184:185], v[200:201], v[196:197]
	v_pk_fma_f32 v[186:187], v[186:187], v[202:203], v[198:199]
	global_store_dwordx4 v[142:143], v[184:187], off
	s_waitcnt lgkmcnt(0)
	ds_write2_b32 v147, v80, v81 offset1:68
	ds_write2_b32 v148, v64, v65 offset0:32 offset1:100
	ds_write2_b32 v147, v82, v83 offset0:136 offset1:204
	ds_write2_b32 v148, v66, v67 offset0:168 offset1:236
	ds_write2_b32 v149, v84, v85 offset0:32 offset1:100
	ds_write2_b32 v150, v68, v69 offset0:64 offset1:132
	ds_write2_b32 v149, v86, v87 offset0:168 offset1:236
	ds_write2_b32 v151, v70, v71 offset0:72 offset1:140
	ds_write2_b32 v152, v88, v89 offset0:64 offset1:132
	ds_write2_b32 v153, v72, v73 offset0:96 offset1:164
	ds_write2_b32 v154, v90, v91 offset0:72 offset1:140
	ds_write2_b32 v155, v74, v75 offset0:104 offset1:172
	ds_write2_b32 v156, v92, v93 offset0:96 offset1:164
	ds_write2_b32 v157, v76, v77 offset0:128 offset1:196
	ds_write2_b32 v158, v94, v95 offset0:104 offset1:172
	ds_write2_b32 v159, v78, v79 offset0:8 offset1:76
	s_waitcnt lgkmcnt(0)
	ds_read_b128 v[64:67], v146
	global_load_dwordx4 v[68:71], v[98:99], off offset:256
	global_load_dwordx4 v[72:75], v[102:103], off offset:256
	s_waitcnt vmcnt(0) lgkmcnt(0)
	v_pk_fma_f32 v[64:65], v[64:65], v[72:73], v[68:69]
	v_pk_fma_f32 v[66:67], v[66:67], v[74:75], v[70:71]
	global_store_dwordx4 v[100:101], v[64:67], off offset:256
	ds_read_b128 v[64:67], v146 offset:1088
	global_load_dwordx4 v[68:71], v[106:107], off offset:256
	global_load_dwordx4 v[72:75], v[108:109], off offset:256
	s_waitcnt vmcnt(0) lgkmcnt(0)
	v_pk_fma_f32 v[64:65], v[64:65], v[72:73], v[68:69]
	v_pk_fma_f32 v[66:67], v[66:67], v[74:75], v[70:71]
	global_store_dwordx4 v[104:105], v[64:67], off offset:256
	ds_read_b128 v[64:67], v146 offset:2176
	global_load_dwordx4 v[68:71], v[110:111], off offset:256
	global_load_dwordx4 v[72:75], v[114:115], off offset:256
	s_waitcnt vmcnt(0) lgkmcnt(0)
	v_pk_fma_f32 v[64:65], v[64:65], v[72:73], v[68:69]
	v_pk_fma_f32 v[66:67], v[66:67], v[74:75], v[70:71]
	global_store_dwordx4 v[112:113], v[64:67], off offset:256
	ds_read_b128 v[64:67], v146 offset:3264
	global_load_dwordx4 v[68:71], v[116:117], off offset:256
	global_load_dwordx4 v[72:75], v[120:121], off offset:256
	s_waitcnt vmcnt(0) lgkmcnt(0)
	v_pk_fma_f32 v[64:65], v[64:65], v[72:73], v[68:69]
	v_pk_fma_f32 v[66:67], v[66:67], v[74:75], v[70:71]
	global_store_dwordx4 v[118:119], v[64:67], off offset:256
	ds_read_b128 v[64:67], v146 offset:4352
	global_load_dwordx4 v[68:71], v[122:123], off offset:256
	global_load_dwordx4 v[72:75], v[126:127], off offset:256
	s_waitcnt vmcnt(0) lgkmcnt(0)
	v_pk_fma_f32 v[64:65], v[64:65], v[72:73], v[68:69]
	v_pk_fma_f32 v[66:67], v[66:67], v[74:75], v[70:71]
	global_store_dwordx4 v[124:125], v[64:67], off offset:256
	ds_read_b128 v[64:67], v146 offset:5440
	global_load_dwordx4 v[68:71], v[128:129], off offset:256
	global_load_dwordx4 v[72:75], v[132:133], off offset:256
	s_waitcnt vmcnt(0) lgkmcnt(0)
	v_pk_fma_f32 v[64:65], v[64:65], v[72:73], v[68:69]
	v_pk_fma_f32 v[66:67], v[66:67], v[74:75], v[70:71]
	global_store_dwordx4 v[130:131], v[64:67], off offset:256
	ds_read_b128 v[64:67], v146 offset:6528
	global_load_dwordx4 v[68:71], v[134:135], off offset:256
	global_load_dwordx4 v[72:75], v[138:139], off offset:256
	s_waitcnt vmcnt(0) lgkmcnt(0)
	v_pk_fma_f32 v[64:65], v[64:65], v[72:73], v[68:69]
	v_pk_fma_f32 v[66:67], v[66:67], v[74:75], v[70:71]
	global_store_dwordx4 v[136:137], v[64:67], off offset:256
	ds_read_b128 v[64:67], v146 offset:7616
	global_load_dwordx4 v[68:71], v[140:141], off offset:256
	global_load_dwordx4 v[72:75], v[144:145], off offset:256
	s_waitcnt vmcnt(0) lgkmcnt(0)
	v_pk_fma_f32 v[64:65], v[64:65], v[72:73], v[68:69]
	v_pk_fma_f32 v[66:67], v[66:67], v[74:75], v[70:71]
	global_store_dwordx4 v[142:143], v[64:67], off offset:256
	v_or_b32_e32 v74, 32, v176
	s_waitcnt lgkmcnt(0)
	ds_write2_b32 v147, v48, v49 offset1:68
	ds_write2_b32 v148, v32, v33 offset0:32 offset1:100
	ds_write2_b32 v147, v50, v51 offset0:136 offset1:204
	ds_write2_b32 v148, v34, v35 offset0:168 offset1:236
	ds_write2_b32 v149, v52, v53 offset0:32 offset1:100
	ds_write2_b32 v150, v36, v37 offset0:64 offset1:132
	ds_write2_b32 v149, v54, v55 offset0:168 offset1:236
	ds_write2_b32 v151, v38, v39 offset0:72 offset1:140
	ds_write2_b32 v152, v56, v57 offset0:64 offset1:132
	ds_write2_b32 v153, v40, v41 offset0:96 offset1:164
	ds_write2_b32 v154, v58, v59 offset0:72 offset1:140
	ds_write2_b32 v155, v42, v43 offset0:104 offset1:172
	ds_write2_b32 v156, v60, v61 offset0:96 offset1:164
	ds_write2_b32 v157, v44, v45 offset0:128 offset1:196
	ds_write2_b32 v158, v62, v63 offset0:104 offset1:172
	ds_write2_b32 v159, v46, v47 offset0:8 offset1:76
	v_or_b32_e32 v40, v74, v175
	v_cmp_gt_i32_e32 vcc, s39, v40
	v_ashrrev_i32_e32 v32, 31, v40
	v_add_u32_e32 v34, 0xffff8000, v40
	v_cndmask_b32_e32 v33, 0, v32, vcc
	v_cndmask_b32_e32 v32, v34, v40, vcc
	v_cndmask_b32_e32 v35, v160, v161, vcc
	v_cndmask_b32_e32 v34, v162, v163, vcc
	v_lshlrev_b64 v[32:33], 12, v[32:33]
	v_lshl_add_u64 v[34:35], v[34:35], 0, v[32:33]
	v_cndmask_b32_e32 v37, v164, v165, vcc
	v_cndmask_b32_e32 v36, v166, v167, vcc
	v_lshl_add_u64 v[38:39], v[36:37], 0, v[32:33]
	v_lshl_add_u64 v[32:33], v[34:35], 0, v[96:97]
	v_min_i32_e32 v34, 0x8000, v40
	v_ashrrev_i32_e32 v34, 12, v34
	v_mul_hi_i32_i24_e32 v35, 0x6000, v34
	v_mul_i32_i24_e32 v34, 0x6000, v34
	s_waitcnt lgkmcnt(0)
	v_lshl_add_u64 v[34:35], s[0:1], 0, v[34:35]
	v_lshl_add_u64 v[36:37], v[34:35], 0, v[96:97]
	v_lshl_add_u64 v[34:35], v[38:39], 0, v[96:97]
	ds_read_b128 v[38:41], v146
	global_load_dwordx4 v[42:45], v[32:33], off
	global_load_dwordx4 v[46:49], v[36:37], off
	v_or_b32_e32 v75, v74, v173
	s_waitcnt vmcnt(0) lgkmcnt(0)
	v_pk_fma_f32 v[38:39], v[38:39], v[46:47], v[42:43]
	v_pk_fma_f32 v[40:41], v[40:41], v[48:49], v[44:45]
	v_or_b32_e32 v46, v74, v168
	global_store_dwordx4 v[34:35], v[38:41], off
	v_cmp_gt_i32_e32 vcc, s39, v46
	s_nop 0
	v_ashrrev_i32_e32 v38, 31, v46
	v_add_u32_e32 v40, 0xffff8000, v46
	v_cndmask_b32_e32 v39, 0, v38, vcc
	v_cndmask_b32_e32 v38, v40, v46, vcc
	v_cndmask_b32_e32 v41, v160, v161, vcc
	v_cndmask_b32_e32 v40, v162, v163, vcc
	v_lshlrev_b64 v[38:39], 12, v[38:39]
	v_lshl_add_u64 v[40:41], v[40:41], 0, v[38:39]
	v_cndmask_b32_e32 v43, v164, v165, vcc
	v_cndmask_b32_e32 v42, v166, v167, vcc
	v_lshl_add_u64 v[44:45], v[42:43], 0, v[38:39]
	v_lshl_add_u64 v[38:39], v[40:41], 0, v[96:97]
	v_min_i32_e32 v40, 0x8000, v46
	v_ashrrev_i32_e32 v40, 12, v40
	v_mul_hi_i32_i24_e32 v41, 0x6000, v40
	v_mul_i32_i24_e32 v40, 0x6000, v40
	v_lshl_add_u64 v[40:41], s[0:1], 0, v[40:41]
	v_lshl_add_u64 v[42:43], v[40:41], 0, v[96:97]
	v_lshl_add_u64 v[40:41], v[44:45], 0, v[96:97]
	ds_read_b128 v[44:47], v146 offset:1088
	global_load_dwordx4 v[48:51], v[38:39], off
	global_load_dwordx4 v[52:55], v[42:43], off
	s_waitcnt vmcnt(0) lgkmcnt(0)
	v_pk_fma_f32 v[44:45], v[44:45], v[52:53], v[48:49]
	v_pk_fma_f32 v[46:47], v[46:47], v[54:55], v[50:51]
	v_or_b32_e32 v52, v74, v169
	global_store_dwordx4 v[40:41], v[44:47], off
	v_cmp_gt_i32_e32 vcc, s39, v52
	s_nop 0
	v_ashrrev_i32_e32 v44, 31, v52
	v_add_u32_e32 v46, 0xffff8000, v52
	v_cndmask_b32_e32 v45, 0, v44, vcc
	v_cndmask_b32_e32 v44, v46, v52, vcc
	v_cndmask_b32_e32 v47, v160, v161, vcc
	v_cndmask_b32_e32 v46, v162, v163, vcc
	v_lshlrev_b64 v[44:45], 12, v[44:45]
	v_lshl_add_u64 v[46:47], v[46:47], 0, v[44:45]
	v_cndmask_b32_e32 v49, v164, v165, vcc
	v_cndmask_b32_e32 v48, v166, v167, vcc
	v_lshl_add_u64 v[50:51], v[48:49], 0, v[44:45]
	v_lshl_add_u64 v[44:45], v[46:47], 0, v[96:97]
	v_min_i32_e32 v46, 0x8000, v52
	v_ashrrev_i32_e32 v46, 12, v46
	v_mul_hi_i32_i24_e32 v47, 0x6000, v46
	v_mul_i32_i24_e32 v46, 0x6000, v46
	v_lshl_add_u64 v[46:47], s[0:1], 0, v[46:47]
	v_lshl_add_u64 v[48:49], v[46:47], 0, v[96:97]
	v_lshl_add_u64 v[46:47], v[50:51], 0, v[96:97]
	ds_read_b128 v[50:53], v146 offset:2176
	global_load_dwordx4 v[54:57], v[44:45], off
	global_load_dwordx4 v[58:61], v[48:49], off
	s_waitcnt vmcnt(0) lgkmcnt(0)
	v_pk_fma_f32 v[50:51], v[50:51], v[58:59], v[54:55]
	v_pk_fma_f32 v[52:53], v[52:53], v[60:61], v[56:57]
	v_or_b32_e32 v58, v74, v170
	global_store_dwordx4 v[46:47], v[50:53], off
	v_cmp_gt_i32_e32 vcc, s39, v58
	s_nop 0
	v_ashrrev_i32_e32 v50, 31, v58
	v_add_u32_e32 v52, 0xffff8000, v58
	v_cndmask_b32_e32 v51, 0, v50, vcc
	v_cndmask_b32_e32 v50, v52, v58, vcc
	v_cndmask_b32_e32 v53, v160, v161, vcc
	v_cndmask_b32_e32 v52, v162, v163, vcc
	v_lshlrev_b64 v[50:51], 12, v[50:51]
	v_lshl_add_u64 v[52:53], v[52:53], 0, v[50:51]
	v_cndmask_b32_e32 v55, v164, v165, vcc
	v_cndmask_b32_e32 v54, v166, v167, vcc
	v_lshl_add_u64 v[56:57], v[54:55], 0, v[50:51]
	v_lshl_add_u64 v[50:51], v[52:53], 0, v[96:97]
	v_min_i32_e32 v52, 0x8000, v58
	v_ashrrev_i32_e32 v52, 12, v52
	v_mul_hi_i32_i24_e32 v53, 0x6000, v52
	v_mul_i32_i24_e32 v52, 0x6000, v52
	v_lshl_add_u64 v[52:53], s[0:1], 0, v[52:53]
	v_lshl_add_u64 v[54:55], v[52:53], 0, v[96:97]
	v_lshl_add_u64 v[52:53], v[56:57], 0, v[96:97]
	ds_read_b128 v[56:59], v146 offset:3264
	global_load_dwordx4 v[60:63], v[50:51], off
	global_load_dwordx4 v[64:67], v[54:55], off
	s_waitcnt vmcnt(0) lgkmcnt(0)
	v_pk_fma_f32 v[56:57], v[56:57], v[64:65], v[60:61]
	v_pk_fma_f32 v[58:59], v[58:59], v[66:67], v[62:63]
	v_or_b32_e32 v64, v74, v171
	global_store_dwordx4 v[52:53], v[56:59], off
	v_cmp_gt_i32_e32 vcc, s39, v64
	s_nop 0
	v_ashrrev_i32_e32 v56, 31, v64
	v_add_u32_e32 v58, 0xffff8000, v64
	v_cndmask_b32_e32 v57, 0, v56, vcc
	v_cndmask_b32_e32 v56, v58, v64, vcc
	v_cndmask_b32_e32 v59, v160, v161, vcc
	v_cndmask_b32_e32 v58, v162, v163, vcc
	v_lshlrev_b64 v[56:57], 12, v[56:57]
	v_lshl_add_u64 v[58:59], v[58:59], 0, v[56:57]
	v_cndmask_b32_e32 v61, v164, v165, vcc
	v_cndmask_b32_e32 v60, v166, v167, vcc
	v_lshl_add_u64 v[62:63], v[60:61], 0, v[56:57]
	v_lshl_add_u64 v[56:57], v[58:59], 0, v[96:97]
	v_min_i32_e32 v58, 0x8000, v64
	v_ashrrev_i32_e32 v58, 12, v58
	v_mul_hi_i32_i24_e32 v59, 0x6000, v58
	v_mul_i32_i24_e32 v58, 0x6000, v58
	v_lshl_add_u64 v[58:59], s[0:1], 0, v[58:59]
	v_lshl_add_u64 v[60:61], v[58:59], 0, v[96:97]
	v_lshl_add_u64 v[58:59], v[62:63], 0, v[96:97]
	ds_read_b128 v[62:65], v146 offset:4352
	global_load_dwordx4 v[66:69], v[56:57], off
	global_load_dwordx4 v[70:73], v[60:61], off
	s_waitcnt vmcnt(0) lgkmcnt(0)
	v_pk_fma_f32 v[62:63], v[62:63], v[70:71], v[66:67]
	v_pk_fma_f32 v[64:65], v[64:65], v[72:73], v[68:69]
	v_or_b32_e32 v70, v74, v172
	global_store_dwordx4 v[58:59], v[62:65], off
	v_cmp_gt_i32_e32 vcc, s39, v70
	s_nop 0
	v_ashrrev_i32_e32 v62, 31, v70
	v_add_u32_e32 v64, 0xffff8000, v70
	v_cndmask_b32_e32 v63, 0, v62, vcc
	v_cndmask_b32_e32 v62, v64, v70, vcc
	v_cndmask_b32_e32 v65, v160, v161, vcc
	v_cndmask_b32_e32 v64, v162, v163, vcc
	v_lshlrev_b64 v[62:63], 12, v[62:63]
	v_lshl_add_u64 v[64:65], v[64:65], 0, v[62:63]
	v_cndmask_b32_e32 v67, v164, v165, vcc
	v_cndmask_b32_e32 v66, v166, v167, vcc
	v_lshl_add_u64 v[68:69], v[66:67], 0, v[62:63]
	v_lshl_add_u64 v[62:63], v[64:65], 0, v[96:97]
	v_min_i32_e32 v64, 0x8000, v70
	v_ashrrev_i32_e32 v64, 12, v64
	v_mul_hi_i32_i24_e32 v65, 0x6000, v64
	v_mul_i32_i24_e32 v64, 0x6000, v64
	v_lshl_add_u64 v[64:65], s[0:1], 0, v[64:65]
	v_lshl_add_u64 v[66:67], v[64:65], 0, v[96:97]
	v_lshl_add_u64 v[64:65], v[68:69], 0, v[96:97]
	ds_read_b128 v[68:71], v146 offset:5440
	global_load_dwordx4 v[76:79], v[62:63], off
	global_load_dwordx4 v[80:83], v[66:67], off
	v_cmp_gt_i32_e32 vcc, s39, v75
	s_waitcnt vmcnt(0) lgkmcnt(0)
	v_pk_fma_f32 v[68:69], v[68:69], v[80:81], v[76:77]
	v_pk_fma_f32 v[70:71], v[70:71], v[82:83], v[78:79]
	global_store_dwordx4 v[64:65], v[68:71], off
	v_cndmask_b32_e32 v73, v164, v165, vcc
	v_cndmask_b32_e32 v72, v166, v167, vcc
	v_ashrrev_i32_e32 v68, 31, v75
	v_add_u32_e32 v70, 0xffff8000, v75
	v_cndmask_b32_e32 v69, 0, v68, vcc
	v_cndmask_b32_e32 v68, v70, v75, vcc
	v_cndmask_b32_e32 v71, v160, v161, vcc
	v_cndmask_b32_e32 v70, v162, v163, vcc
	v_lshlrev_b64 v[68:69], 12, v[68:69]
	v_lshl_add_u64 v[70:71], v[70:71], 0, v[68:69]
	v_lshl_add_u64 v[76:77], v[72:73], 0, v[68:69]
	v_lshl_add_u64 v[68:69], v[70:71], 0, v[96:97]
	v_min_i32_e32 v70, 0x8000, v75
	v_ashrrev_i32_e32 v70, 12, v70
	v_mul_hi_i32_i24_e32 v71, 0x6000, v70
	v_mul_i32_i24_e32 v70, 0x6000, v70
	v_lshl_add_u64 v[70:71], s[0:1], 0, v[70:71]
	v_lshl_add_u64 v[72:73], v[70:71], 0, v[96:97]
	v_lshl_add_u64 v[70:71], v[76:77], 0, v[96:97]
	ds_read_b128 v[76:79], v146 offset:6528
	global_load_dwordx4 v[80:83], v[68:69], off
	global_load_dwordx4 v[84:87], v[72:73], off
	s_waitcnt vmcnt(0) lgkmcnt(0)
	v_pk_fma_f32 v[76:77], v[76:77], v[84:85], v[80:81]
	v_pk_fma_f32 v[78:79], v[78:79], v[86:87], v[82:83]
	v_or_b32_e32 v82, v74, v174
	global_store_dwordx4 v[70:71], v[76:79], off
	v_cmp_gt_i32_e32 vcc, s39, v82
	v_ashrrev_i32_e32 v74, 31, v82
	v_add_u32_e32 v76, 0xffff8000, v82
	v_cndmask_b32_e32 v75, 0, v74, vcc
	v_cndmask_b32_e32 v74, v76, v82, vcc
	v_cndmask_b32_e32 v77, v160, v161, vcc
	v_cndmask_b32_e32 v76, v162, v163, vcc
	v_lshlrev_b64 v[74:75], 12, v[74:75]
	v_lshl_add_u64 v[76:77], v[76:77], 0, v[74:75]
	v_cndmask_b32_e32 v79, v164, v165, vcc
	v_cndmask_b32_e32 v78, v166, v167, vcc
	v_lshl_add_u64 v[80:81], v[78:79], 0, v[74:75]
	v_lshl_add_u64 v[74:75], v[76:77], 0, v[96:97]
	v_min_i32_e32 v76, 0x8000, v82
	v_ashrrev_i32_e32 v76, 12, v76
	v_mul_hi_i32_i24_e32 v77, 0x6000, v76
	v_mul_i32_i24_e32 v76, 0x6000, v76
	v_lshl_add_u64 v[76:77], s[0:1], 0, v[76:77]
	v_lshl_add_u64 v[78:79], v[76:77], 0, v[96:97]
	v_lshl_add_u64 v[76:77], v[80:81], 0, v[96:97]
	ds_read_b128 v[80:83], v146 offset:7616
	global_load_dwordx4 v[84:87], v[74:75], off
	global_load_dwordx4 v[88:91], v[78:79], off
	s_waitcnt vmcnt(0) lgkmcnt(0)
	v_pk_fma_f32 v[80:81], v[80:81], v[88:89], v[84:85]
	v_pk_fma_f32 v[82:83], v[82:83], v[90:91], v[86:87]
	global_store_dwordx4 v[76:77], v[80:83], off
	s_waitcnt lgkmcnt(0)
	ds_write2_b32 v147, v16, v17 offset1:68
	ds_write2_b32 v148, v0, v1 offset0:32 offset1:100
	ds_write2_b32 v147, v18, v19 offset0:136 offset1:204
	ds_write2_b32 v148, v2, v3 offset0:168 offset1:236
	ds_write2_b32 v149, v20, v21 offset0:32 offset1:100
	ds_write2_b32 v150, v4, v5 offset0:64 offset1:132
	ds_write2_b32 v149, v22, v23 offset0:168 offset1:236
	ds_write2_b32 v151, v6, v7 offset0:72 offset1:140
	ds_write2_b32 v152, v24, v25 offset0:64 offset1:132
	ds_write2_b32 v153, v8, v9 offset0:96 offset1:164
	ds_write2_b32 v154, v26, v27 offset0:72 offset1:140
	ds_write2_b32 v155, v10, v11 offset0:104 offset1:172
	ds_write2_b32 v156, v28, v29 offset0:96 offset1:164
	ds_write2_b32 v157, v12, v13 offset0:128 offset1:196
	ds_write2_b32 v158, v30, v31 offset0:104 offset1:172
	ds_write2_b32 v159, v14, v15 offset0:8 offset1:76
	s_waitcnt lgkmcnt(0)
	ds_read_b128 v[0:3], v146
	global_load_dwordx4 v[4:7], v[32:33], off offset:256
	global_load_dwordx4 v[8:11], v[36:37], off offset:256
	s_waitcnt vmcnt(0) lgkmcnt(0)
	v_pk_fma_f32 v[0:1], v[0:1], v[8:9], v[4:5]
	v_pk_fma_f32 v[2:3], v[2:3], v[10:11], v[6:7]
	global_store_dwordx4 v[34:35], v[0:3], off offset:256
	ds_read_b128 v[0:3], v146 offset:1088
	global_load_dwordx4 v[4:7], v[38:39], off offset:256
	global_load_dwordx4 v[8:11], v[42:43], off offset:256
	s_waitcnt vmcnt(0) lgkmcnt(0)
	v_pk_fma_f32 v[0:1], v[0:1], v[8:9], v[4:5]
	v_pk_fma_f32 v[2:3], v[2:3], v[10:11], v[6:7]
	global_store_dwordx4 v[40:41], v[0:3], off offset:256
	ds_read_b128 v[0:3], v146 offset:2176
	global_load_dwordx4 v[4:7], v[44:45], off offset:256
	global_load_dwordx4 v[8:11], v[48:49], off offset:256
	s_waitcnt vmcnt(0) lgkmcnt(0)
	v_pk_fma_f32 v[0:1], v[0:1], v[8:9], v[4:5]
	v_pk_fma_f32 v[2:3], v[2:3], v[10:11], v[6:7]
	global_store_dwordx4 v[46:47], v[0:3], off offset:256
	ds_read_b128 v[0:3], v146 offset:3264
	global_load_dwordx4 v[4:7], v[50:51], off offset:256
	global_load_dwordx4 v[8:11], v[54:55], off offset:256
	s_waitcnt vmcnt(0) lgkmcnt(0)
	v_pk_fma_f32 v[0:1], v[0:1], v[8:9], v[4:5]
	v_pk_fma_f32 v[2:3], v[2:3], v[10:11], v[6:7]
	global_store_dwordx4 v[52:53], v[0:3], off offset:256
	ds_read_b128 v[0:3], v146 offset:4352
	global_load_dwordx4 v[4:7], v[56:57], off offset:256
	global_load_dwordx4 v[8:11], v[60:61], off offset:256
	s_waitcnt vmcnt(0) lgkmcnt(0)
	v_pk_fma_f32 v[0:1], v[0:1], v[8:9], v[4:5]
	v_pk_fma_f32 v[2:3], v[2:3], v[10:11], v[6:7]
	global_store_dwordx4 v[58:59], v[0:3], off offset:256
	ds_read_b128 v[0:3], v146 offset:5440
	global_load_dwordx4 v[4:7], v[62:63], off offset:256
	global_load_dwordx4 v[8:11], v[66:67], off offset:256
	s_waitcnt vmcnt(0) lgkmcnt(0)
	v_pk_fma_f32 v[0:1], v[0:1], v[8:9], v[4:5]
	v_pk_fma_f32 v[2:3], v[2:3], v[10:11], v[6:7]
	global_store_dwordx4 v[64:65], v[0:3], off offset:256
	ds_read_b128 v[0:3], v146 offset:6528
	global_load_dwordx4 v[4:7], v[68:69], off offset:256
	global_load_dwordx4 v[8:11], v[72:73], off offset:256
	s_waitcnt vmcnt(0) lgkmcnt(0)
	v_pk_fma_f32 v[0:1], v[0:1], v[8:9], v[4:5]
	v_pk_fma_f32 v[2:3], v[2:3], v[10:11], v[6:7]
	global_store_dwordx4 v[70:71], v[0:3], off offset:256
	ds_read_b128 v[0:3], v146 offset:7616
	global_load_dwordx4 v[4:7], v[74:75], off offset:256
	global_load_dwordx4 v[8:11], v[78:79], off offset:256
	s_waitcnt vmcnt(0) lgkmcnt(0)
	v_pk_fma_f32 v[0:1], v[0:1], v[8:9], v[4:5]
	v_pk_fma_f32 v[2:3], v[2:3], v[10:11], v[6:7]
	global_store_dwordx4 v[76:77], v[0:3], off offset:256
	s_waitcnt lgkmcnt(0)
	s_barrier
	s_cbranch_scc1 .LBB0_923

.LBB0_1031:
	s_mul_hi_i32 s0, s2, 0x2e8ba2e9
	s_lshr_b32 s1, s0, 31
	s_ashr_i32 s0, s0, 6
	s_add_i32 s0, s0, s1
	s_lshl_b32 s1, s0, 3
	s_sub_i32 s7, s25, s1
	s_min_i32 s7, s7, 8
	s_abs_i32 s8, s7
	v_cvt_f32_u32_e32 v0, s8
	s_sub_i32 s11, 0, s8
	s_mulk_i32 s0, 0xfea0
	s_add_i32 s9, s0, s2
	v_rcp_iflag_f32_e32 v0, v0
	s_abs_i32 s0, s9
	s_xor_b32 s10, s9, s7
	s_ashr_i32 s10, s10, 31
	v_mul_f32_e32 v0, 0x4f7ffffe, v0
	v_cvt_u32_f32_e32 v0, v0
	v_mov_b32_e32 v237, v179
	v_readfirstlane_b32 s12, v0
	s_mul_i32 s11, s11, s12
	s_mul_hi_u32 s11, s12, s11
	s_add_i32 s12, s12, s11
	s_mul_hi_u32 s11, s0, s12
	s_mul_i32 s12, s11, s8
	s_sub_i32 s0, s0, s12
	s_add_i32 s13, s11, 1
	s_sub_i32 s12, s0, s8
	s_cmp_ge_u32 s0, s8
	s_cselect_b32 s11, s13, s11
	s_cselect_b32 s0, s12, s0
	s_add_i32 s12, s11, 1
	s_cmp_ge_u32 s0, s8
	s_cselect_b32 s0, s12, s11
	s_xor_b32 s0, s0, s10
	s_sub_i32 s0, s0, s10
	s_mul_i32 s7, s7, s0
	s_sub_i32 s7, s9, s7
	s_add_i32 s1, s1, s6
	v_ashrrev_i32_e32 v238, 6, v237
	s_add_i32 s7, s1, s7
	v_lshlrev_b32_e32 v0, 1, v238
	v_lshl_add_u32 v0, s7, 3, v0
	v_ashrrev_i32_e32 v1, 31, v0
	v_bfe_u32 v183, v237, 5, 1
	v_lshlrev_b64 v[0:1], 16, v[0:1]
	v_and_b32_e32 v239, 31, v237
	v_lshl_add_u64 v[0:1], s[64:65], 0, v[0:1]
	v_lshlrev_b32_e32 v176, 9, v183
	s_ashr_i32 s1, s0, 31
	v_lshl_add_u64 v[0:1], v[0:1], 0, v[176:177]
	v_lshlrev_b32_e32 v176, 4, v239
	v_ashrrev_i32_e32 v38, 2, v237
	s_lshl_b64 s[8:9], s[0:1], 18
	v_lshl_add_u64 v[184:185], v[0:1], 0, v[176:177]
	s_add_u32 s8, s4, s8
	v_lshlrev_b32_e32 v0, 5, v38
	v_lshlrev_b32_e32 v2, 3, v237
	s_addc_u32 s9, s5, s9
	v_ashrrev_i32_e32 v1, 31, v0
	v_and_b32_e32 v181, 24, v2
	v_lshl_add_u64 v[0:1], v[0:1], 1, s[8:9]
	v_lshlrev_b32_e32 v176, 1, v181
	v_lshl_add_u64 v[186:187], v[0:1], 0, v[176:177]
	s_movk_i32 s1, 0x2000
	v_add_co_u32_e32 v34, vcc, s1, v186
	v_mul_u32_u24_e32 v36, 40, v239
	s_nop 0
	v_addc_co_u32_e32 v35, vcc, 0, v187, vcc
	v_lshlrev_b32_e32 v37, 4, v183
	v_lshl_add_u32 v241, v36, 1, v37
	v_add_co_u32_e32 v36, vcc, s41, v184
	s_movk_i32 s8, 0x50
	s_nop 0
	v_addc_co_u32_e32 v37, vcc, 0, v185, vcc
	v_mad_u64_u32 v[188:189], s[8:9], v38, s8, v[176:177]
	v_and_b32_e32 v240, 63, v237
	v_bfe_u32 v247, v237, 4, 2
	v_lshlrev_b32_e32 v247, 1, v247
	v_mov_b32_e32 v176, 0x78
	v_lshrrev_b32_e32 v247, v247, v176
	v_and_b32_e32 v247, 3, v247
	v_and_b32_e32 v246, 3, v237
	v_xor_b32_e32 v247, v247, v246
	v_lshlrev_b32_e32 v247, 4, v247
	v_and_b32_e32 v188, 0xffffffcf, v186
	v_or_b32_e32 v188, v188, v247
	v_mov_b32_e32 v189, v187
	v_lshrrev_b32_e32 v176, 6, v237
	v_lshlrev_b32_e32 v247, 11, v176
	v_lshlrev_b32_e32 v176, 10, v176
	v_lshl_add_u64 v[188:189], v[188:189], 0, v[176:177]
	v_readfirstlane_b32 vcc_lo, v247
	v_bfe_u32 v247, v237, 4, 1
	v_lshlrev_b32_e32 v176, 9, v183
	v_lshl_add_u32 v176, v247, 8, v176
	v_lshl_add_u64 v[184:185], v[184:185], 0, v[176:177]
	v_mov_b32_e32 v176, s41
	v_lshl_add_u64 v[186:187], v[184:185], 0, v[176:177]
	v_mov_b32_e32 v176, 0x78
	v_bfe_u32 v247, v237, 2, 2
	v_lshlrev_b32_e32 v247, 1, v247
	v_lshrrev_b32_e32 v247, v247, v176
	v_and_b32_e32 v247, 3, v247
	v_bfe_u32 v246, v237, 4, 2
	v_xor_b32_e32 v247, v247, v246
	v_lshlrev_b32_e32 v247, 4, v247
	v_and_b32_e32 v246, 15, v237
	v_lshl_add_u32 v246, v246, 6, v247
	s_mov_b32 s96, 0
	s_mov_b32 m0, vcc_lo
	v_lshl_add_u64 v[160:161], v[188:189], 0, s[96:97]
	global_load_lds_dwordx4 v[160:161], off
	global_load_lds_dwordx4 v[160:161], off offset:1024
	s_movk_i32 s96, 0x2000
	s_add_i32 m0, vcc_lo, 8192
	v_lshl_add_u64 v[160:161], v[188:189], 0, s[96:97]
	global_load_lds_dwordx4 v[160:161], off
	global_load_lds_dwordx4 v[160:161], off offset:1024
	s_mov_b32 s96, 0
	v_lshl_add_u64 v[248:249], v[184:185], 0, s[96:97]
	v_lshl_add_u64 v[250:251], v[186:187], 0, s[96:97]
	global_load_dwordx4 v[128:131], v[248:249], off
	global_load_dwordx4 v[132:135], v[248:249], off offset:256
	global_load_dwordx4 v[136:139], v[250:251], off
	global_load_dwordx4 v[140:143], v[250:251], off offset:256
	s_movk_i32 s96, 0x800
	v_lshl_add_u64 v[248:249], v[184:185], 0, s[96:97]
	v_lshl_add_u64 v[250:251], v[186:187], 0, s[96:97]
	global_load_dwordx4 v[144:147], v[248:249], off
	global_load_dwordx4 v[148:151], v[248:249], off offset:256
	global_load_dwordx4 v[152:155], v[250:251], off
	global_load_dwordx4 v[156:159], v[250:251], off offset:256
	v_mov_b32_e32 v0, 0
	v_mov_b32_e32 v1, 0
	v_mov_b32_e32 v2, 0
	v_mov_b32_e32 v3, 0
	v_mov_b32_e32 v4, 0
	v_mov_b32_e32 v5, 0
	v_mov_b32_e32 v6, 0
	v_mov_b32_e32 v7, 0
	v_mov_b32_e32 v8, 0
	v_mov_b32_e32 v9, 0
	v_mov_b32_e32 v10, 0
	v_mov_b32_e32 v11, 0
	v_mov_b32_e32 v12, 0
	v_mov_b32_e32 v13, 0
	v_mov_b32_e32 v14, 0
	v_mov_b32_e32 v15, 0
	v_mov_b32_e32 v16, 0
	v_mov_b32_e32 v17, 0
	v_mov_b32_e32 v18, 0
	v_mov_b32_e32 v19, 0
	v_mov_b32_e32 v20, 0
	v_mov_b32_e32 v21, 0
	v_mov_b32_e32 v22, 0
	v_mov_b32_e32 v23, 0
	v_mov_b32_e32 v24, 0
	v_mov_b32_e32 v25, 0
	v_mov_b32_e32 v26, 0
	v_mov_b32_e32 v27, 0
	v_mov_b32_e32 v28, 0
	v_mov_b32_e32 v29, 0
	v_mov_b32_e32 v30, 0
	v_mov_b32_e32 v31, 0
	v_mov_b32_e32 v32, 0
	v_mov_b32_e32 v33, 0
	v_mov_b32_e32 v34, 0
	v_mov_b32_e32 v35, 0
	v_mov_b32_e32 v36, 0
	v_mov_b32_e32 v37, 0
	v_mov_b32_e32 v38, 0
	v_mov_b32_e32 v39, 0
	v_mov_b32_e32 v40, 0
	v_mov_b32_e32 v41, 0
	v_mov_b32_e32 v42, 0
	v_mov_b32_e32 v43, 0
	v_mov_b32_e32 v44, 0
	v_mov_b32_e32 v45, 0
	v_mov_b32_e32 v46, 0
	v_mov_b32_e32 v47, 0
	v_mov_b32_e32 v48, 0
	v_mov_b32_e32 v49, 0
	v_mov_b32_e32 v50, 0
	v_mov_b32_e32 v51, 0
	v_mov_b32_e32 v52, 0
	v_mov_b32_e32 v53, 0
	v_mov_b32_e32 v54, 0
	v_mov_b32_e32 v55, 0
	v_mov_b32_e32 v56, 0
	v_mov_b32_e32 v57, 0
	v_mov_b32_e32 v58, 0
	v_mov_b32_e32 v59, 0
	v_mov_b32_e32 v60, 0
	v_mov_b32_e32 v61, 0
	v_mov_b32_e32 v62, 0
	v_mov_b32_e32 v63, 0
	v_mov_b32_e32 v64, 0
	v_mov_b32_e32 v65, 0
	v_mov_b32_e32 v66, 0
	v_mov_b32_e32 v67, 0
	v_mov_b32_e32 v68, 0
	v_mov_b32_e32 v69, 0
	v_mov_b32_e32 v70, 0
	v_mov_b32_e32 v71, 0
	v_mov_b32_e32 v72, 0
	v_mov_b32_e32 v73, 0
	v_mov_b32_e32 v74, 0
	v_mov_b32_e32 v75, 0
	v_mov_b32_e32 v76, 0
	v_mov_b32_e32 v77, 0
	v_mov_b32_e32 v78, 0
	v_mov_b32_e32 v79, 0
	v_mov_b32_e32 v80, 0
	v_mov_b32_e32 v81, 0
	v_mov_b32_e32 v82, 0
	v_mov_b32_e32 v83, 0
	v_mov_b32_e32 v84, 0
	v_mov_b32_e32 v85, 0
	v_mov_b32_e32 v86, 0
	v_mov_b32_e32 v87, 0
	v_mov_b32_e32 v88, 0
	v_mov_b32_e32 v89, 0
	v_mov_b32_e32 v90, 0
	v_mov_b32_e32 v91, 0
	v_mov_b32_e32 v92, 0
	v_mov_b32_e32 v93, 0
	v_mov_b32_e32 v94, 0
	v_mov_b32_e32 v95, 0
	v_mov_b32_e32 v96, 0
	v_mov_b32_e32 v97, 0
	v_mov_b32_e32 v98, 0
	v_mov_b32_e32 v99, 0
	v_mov_b32_e32 v100, 0
	v_mov_b32_e32 v101, 0
	v_mov_b32_e32 v102, 0
	v_mov_b32_e32 v103, 0
	v_mov_b32_e32 v104, 0
	v_mov_b32_e32 v105, 0
	v_mov_b32_e32 v106, 0
	v_mov_b32_e32 v107, 0
	v_mov_b32_e32 v108, 0
	v_mov_b32_e32 v109, 0
	v_mov_b32_e32 v110, 0
	v_mov_b32_e32 v111, 0
	v_mov_b32_e32 v112, 0
	v_mov_b32_e32 v113, 0
	v_mov_b32_e32 v114, 0
	v_mov_b32_e32 v115, 0
	v_mov_b32_e32 v116, 0
	v_mov_b32_e32 v117, 0
	v_mov_b32_e32 v118, 0
	v_mov_b32_e32 v119, 0
	v_mov_b32_e32 v120, 0
	v_mov_b32_e32 v121, 0
	v_mov_b32_e32 v122, 0
	v_mov_b32_e32 v123, 0
	v_mov_b32_e32 v124, 0
	v_mov_b32_e32 v125, 0
	v_mov_b32_e32 v126, 0
	v_mov_b32_e32 v127, 0
	s_mov_b32 s1, 0
	s_waitcnt vmcnt(4)
	s_barrier
.Lg16_gu_k:
	s_add_i32 s8, s1, 2
	s_lshl_b32 s96, s8, 13
	s_add_i32 m0, vcc_lo, 16384
	v_lshl_add_u64 v[160:161], v[188:189], 0, s[96:97]
	global_load_lds_dwordx4 v[160:161], off
	global_load_lds_dwordx4 v[160:161], off offset:1024
	s_add_i32 s8, s1, 3
	s_lshl_b32 s96, s8, 13
	s_add_i32 m0, vcc_lo, 24576
	v_lshl_add_u64 v[160:161], v[188:189], 0, s[96:97]
	global_load_lds_dwordx4 v[160:161], off
	global_load_lds_dwordx4 v[160:161], off offset:1024
	ds_read_b128 v[196:199], v246 offset:0
	ds_read_b128 v[200:203], v246 offset:1024
	ds_read_b128 v[204:207], v246 offset:2048
	ds_read_b128 v[242:245], v246 offset:3072
	s_add_i32 s8, s1, 2
	s_lshl_b32 s96, s8, 11
	v_lshl_add_u64 v[248:249], v[184:185], 0, s[96:97]
	v_lshl_add_u64 v[250:251], v[186:187], 0, s[96:97]
	s_waitcnt vmcnt(8) lgkmcnt(3)
	v_mfma_f32_16x16x32_bf16 v[112:115], v[128:131], v[196:199], v[112:115]
	v_mfma_f32_16x16x32_bf16 v[120:123], v[132:135], v[196:199], v[120:123]
	v_mfma_f32_16x16x32_bf16 v[80:83], v[136:139], v[196:199], v[80:83]
	v_mfma_f32_16x16x32_bf16 v[88:91], v[140:143], v[196:199], v[88:91]
	ds_read_b128 v[196:199], v246 offset:4096
	s_waitcnt lgkmcnt(3)
	v_mfma_f32_16x16x32_bf16 v[116:119], v[128:131], v[200:203], v[116:119]
	v_mfma_f32_16x16x32_bf16 v[124:127], v[132:135], v[200:203], v[124:127]
	v_mfma_f32_16x16x32_bf16 v[84:87], v[136:139], v[200:203], v[84:87]
	v_mfma_f32_16x16x32_bf16 v[92:95], v[140:143], v[200:203], v[92:95]
	ds_read_b128 v[200:203], v246 offset:5120
	s_waitcnt lgkmcnt(3)
	v_mfma_f32_16x16x32_bf16 v[96:99], v[128:131], v[204:207], v[96:99]
	v_mfma_f32_16x16x32_bf16 v[104:107], v[132:135], v[204:207], v[104:107]
	v_mfma_f32_16x16x32_bf16 v[64:67], v[136:139], v[204:207], v[64:67]
	v_mfma_f32_16x16x32_bf16 v[72:75], v[140:143], v[204:207], v[72:75]
	ds_read_b128 v[204:207], v246 offset:6144
	s_waitcnt lgkmcnt(3)
	v_mfma_f32_16x16x32_bf16 v[100:103], v[128:131], v[242:245], v[100:103]
	v_mfma_f32_16x16x32_bf16 v[108:111], v[132:135], v[242:245], v[108:111]
	v_mfma_f32_16x16x32_bf16 v[68:71], v[136:139], v[242:245], v[68:71]
	v_mfma_f32_16x16x32_bf16 v[76:79], v[140:143], v[242:245], v[76:79]
	ds_read_b128 v[242:245], v246 offset:7168
	s_waitcnt lgkmcnt(3)
	v_mfma_f32_16x16x32_bf16 v[48:51], v[128:131], v[196:199], v[48:51]
	v_mfma_f32_16x16x32_bf16 v[56:59], v[132:135], v[196:199], v[56:59]
	v_mfma_f32_16x16x32_bf16 v[16:19], v[136:139], v[196:199], v[16:19]
	v_mfma_f32_16x16x32_bf16 v[24:27], v[140:143], v[196:199], v[24:27]
	s_waitcnt lgkmcnt(2)
	v_mfma_f32_16x16x32_bf16 v[52:55], v[128:131], v[200:203], v[52:55]
	v_mfma_f32_16x16x32_bf16 v[60:63], v[132:135], v[200:203], v[60:63]
	v_mfma_f32_16x16x32_bf16 v[20:23], v[136:139], v[200:203], v[20:23]
	v_mfma_f32_16x16x32_bf16 v[28:31], v[140:143], v[200:203], v[28:31]
	s_waitcnt lgkmcnt(1)
	v_mfma_f32_16x16x32_bf16 v[32:35], v[128:131], v[204:207], v[32:35]
	v_mfma_f32_16x16x32_bf16 v[40:43], v[132:135], v[204:207], v[40:43]
	v_mfma_f32_16x16x32_bf16 v[0:3], v[136:139], v[204:207], v[0:3]
	v_mfma_f32_16x16x32_bf16 v[8:11], v[140:143], v[204:207], v[8:11]
	s_waitcnt lgkmcnt(0)
	v_mfma_f32_16x16x32_bf16 v[36:39], v[128:131], v[242:245], v[36:39]
	v_mfma_f32_16x16x32_bf16 v[44:47], v[132:135], v[242:245], v[44:47]
	v_mfma_f32_16x16x32_bf16 v[4:7], v[136:139], v[242:245], v[4:7]
	v_mfma_f32_16x16x32_bf16 v[12:15], v[140:143], v[242:245], v[12:15]
	global_load_dwordx4 v[128:131], v[248:249], off
	global_load_dwordx4 v[132:135], v[248:249], off offset:256
	global_load_dwordx4 v[136:139], v[250:251], off
	global_load_dwordx4 v[140:143], v[250:251], off offset:256
	ds_read_b128 v[196:199], v246 offset:8192
	ds_read_b128 v[200:203], v246 offset:9216
	ds_read_b128 v[204:207], v246 offset:10240
	ds_read_b128 v[242:245], v246 offset:11264
	s_add_i32 s8, s1, 3
	s_lshl_b32 s96, s8, 11
	v_lshl_add_u64 v[248:249], v[184:185], 0, s[96:97]
	v_lshl_add_u64 v[250:251], v[186:187], 0, s[96:97]
	s_waitcnt vmcnt(8) lgkmcnt(3)
	v_mfma_f32_16x16x32_bf16 v[112:115], v[144:147], v[196:199], v[112:115]
	v_mfma_f32_16x16x32_bf16 v[120:123], v[148:151], v[196:199], v[120:123]
	v_mfma_f32_16x16x32_bf16 v[80:83], v[152:155], v[196:199], v[80:83]
	v_mfma_f32_16x16x32_bf16 v[88:91], v[156:159], v[196:199], v[88:91]
	ds_read_b128 v[196:199], v246 offset:12288
	s_waitcnt lgkmcnt(3)
	v_mfma_f32_16x16x32_bf16 v[116:119], v[144:147], v[200:203], v[116:119]
	v_mfma_f32_16x16x32_bf16 v[124:127], v[148:151], v[200:203], v[124:127]
	v_mfma_f32_16x16x32_bf16 v[84:87], v[152:155], v[200:203], v[84:87]
	v_mfma_f32_16x16x32_bf16 v[92:95], v[156:159], v[200:203], v[92:95]
	ds_read_b128 v[200:203], v246 offset:13312
	s_waitcnt lgkmcnt(3)
	v_mfma_f32_16x16x32_bf16 v[96:99], v[144:147], v[204:207], v[96:99]
	v_mfma_f32_16x16x32_bf16 v[104:107], v[148:151], v[204:207], v[104:107]
	v_mfma_f32_16x16x32_bf16 v[64:67], v[152:155], v[204:207], v[64:67]
	v_mfma_f32_16x16x32_bf16 v[72:75], v[156:159], v[204:207], v[72:75]
	ds_read_b128 v[204:207], v246 offset:14336
	s_waitcnt lgkmcnt(3)
	v_mfma_f32_16x16x32_bf16 v[100:103], v[144:147], v[242:245], v[100:103]
	v_mfma_f32_16x16x32_bf16 v[108:111], v[148:151], v[242:245], v[108:111]
	v_mfma_f32_16x16x32_bf16 v[68:71], v[152:155], v[242:245], v[68:71]
	v_mfma_f32_16x16x32_bf16 v[76:79], v[156:159], v[242:245], v[76:79]
	ds_read_b128 v[242:245], v246 offset:15360
	s_waitcnt lgkmcnt(3)
	v_mfma_f32_16x16x32_bf16 v[48:51], v[144:147], v[196:199], v[48:51]
	v_mfma_f32_16x16x32_bf16 v[56:59], v[148:151], v[196:199], v[56:59]
	v_mfma_f32_16x16x32_bf16 v[16:19], v[152:155], v[196:199], v[16:19]
	v_mfma_f32_16x16x32_bf16 v[24:27], v[156:159], v[196:199], v[24:27]
	s_waitcnt lgkmcnt(2)
	v_mfma_f32_16x16x32_bf16 v[52:55], v[144:147], v[200:203], v[52:55]
	v_mfma_f32_16x16x32_bf16 v[60:63], v[148:151], v[200:203], v[60:63]
	v_mfma_f32_16x16x32_bf16 v[20:23], v[152:155], v[200:203], v[20:23]
	v_mfma_f32_16x16x32_bf16 v[28:31], v[156:159], v[200:203], v[28:31]
	s_waitcnt lgkmcnt(1)
	v_mfma_f32_16x16x32_bf16 v[32:35], v[144:147], v[204:207], v[32:35]
	v_mfma_f32_16x16x32_bf16 v[40:43], v[148:151], v[204:207], v[40:43]
	v_mfma_f32_16x16x32_bf16 v[0:3], v[152:155], v[204:207], v[0:3]
	v_mfma_f32_16x16x32_bf16 v[8:11], v[156:159], v[204:207], v[8:11]
	s_waitcnt lgkmcnt(0)
	v_mfma_f32_16x16x32_bf16 v[36:39], v[144:147], v[242:245], v[36:39]
	v_mfma_f32_16x16x32_bf16 v[44:47], v[148:151], v[242:245], v[44:47]
	v_mfma_f32_16x16x32_bf16 v[4:7], v[152:155], v[242:245], v[4:7]
	v_mfma_f32_16x16x32_bf16 v[12:15], v[156:159], v[242:245], v[12:15]
	global_load_dwordx4 v[144:147], v[248:249], off
	global_load_dwordx4 v[148:151], v[248:249], off offset:256
	global_load_dwordx4 v[152:155], v[250:251], off
	global_load_dwordx4 v[156:159], v[250:251], off offset:256
	s_waitcnt vmcnt(8)
	s_barrier
	s_add_i32 s8, s1, 4
	s_lshl_b32 s96, s8, 13
	s_mov_b32 m0, vcc_lo
	v_lshl_add_u64 v[160:161], v[188:189], 0, s[96:97]
	global_load_lds_dwordx4 v[160:161], off
	global_load_lds_dwordx4 v[160:161], off offset:1024
	s_add_i32 s8, s1, 5
	s_lshl_b32 s96, s8, 13
	s_add_i32 m0, vcc_lo, 8192
	v_lshl_add_u64 v[160:161], v[188:189], 0, s[96:97]
	global_load_lds_dwordx4 v[160:161], off
	global_load_lds_dwordx4 v[160:161], off offset:1024
	ds_read_b128 v[196:199], v246 offset:16384
	ds_read_b128 v[200:203], v246 offset:17408
	ds_read_b128 v[204:207], v246 offset:18432
	ds_read_b128 v[242:245], v246 offset:19456
	s_add_i32 s8, s1, 4
	s_lshl_b32 s96, s8, 11
	v_lshl_add_u64 v[248:249], v[184:185], 0, s[96:97]
	v_lshl_add_u64 v[250:251], v[186:187], 0, s[96:97]
	s_waitcnt vmcnt(8) lgkmcnt(3)
	v_mfma_f32_16x16x32_bf16 v[112:115], v[128:131], v[196:199], v[112:115]
	v_mfma_f32_16x16x32_bf16 v[120:123], v[132:135], v[196:199], v[120:123]
	v_mfma_f32_16x16x32_bf16 v[80:83], v[136:139], v[196:199], v[80:83]
	v_mfma_f32_16x16x32_bf16 v[88:91], v[140:143], v[196:199], v[88:91]
	ds_read_b128 v[196:199], v246 offset:20480
	s_waitcnt lgkmcnt(3)
	v_mfma_f32_16x16x32_bf16 v[116:119], v[128:131], v[200:203], v[116:119]
	v_mfma_f32_16x16x32_bf16 v[124:127], v[132:135], v[200:203], v[124:127]
	v_mfma_f32_16x16x32_bf16 v[84:87], v[136:139], v[200:203], v[84:87]
	v_mfma_f32_16x16x32_bf16 v[92:95], v[140:143], v[200:203], v[92:95]
	ds_read_b128 v[200:203], v246 offset:21504
	s_waitcnt lgkmcnt(3)
	v_mfma_f32_16x16x32_bf16 v[96:99], v[128:131], v[204:207], v[96:99]
	v_mfma_f32_16x16x32_bf16 v[104:107], v[132:135], v[204:207], v[104:107]
	v_mfma_f32_16x16x32_bf16 v[64:67], v[136:139], v[204:207], v[64:67]
	v_mfma_f32_16x16x32_bf16 v[72:75], v[140:143], v[204:207], v[72:75]
	ds_read_b128 v[204:207], v246 offset:22528
	s_waitcnt lgkmcnt(3)
	v_mfma_f32_16x16x32_bf16 v[100:103], v[128:131], v[242:245], v[100:103]
	v_mfma_f32_16x16x32_bf16 v[108:111], v[132:135], v[242:245], v[108:111]
	v_mfma_f32_16x16x32_bf16 v[68:71], v[136:139], v[242:245], v[68:71]
	v_mfma_f32_16x16x32_bf16 v[76:79], v[140:143], v[242:245], v[76:79]
	ds_read_b128 v[242:245], v246 offset:23552
	s_waitcnt lgkmcnt(3)
	v_mfma_f32_16x16x32_bf16 v[48:51], v[128:131], v[196:199], v[48:51]
	v_mfma_f32_16x16x32_bf16 v[56:59], v[132:135], v[196:199], v[56:59]
	v_mfma_f32_16x16x32_bf16 v[16:19], v[136:139], v[196:199], v[16:19]
	v_mfma_f32_16x16x32_bf16 v[24:27], v[140:143], v[196:199], v[24:27]
	s_waitcnt lgkmcnt(2)
	v_mfma_f32_16x16x32_bf16 v[52:55], v[128:131], v[200:203], v[52:55]
	v_mfma_f32_16x16x32_bf16 v[60:63], v[132:135], v[200:203], v[60:63]
	v_mfma_f32_16x16x32_bf16 v[20:23], v[136:139], v[200:203], v[20:23]
	v_mfma_f32_16x16x32_bf16 v[28:31], v[140:143], v[200:203], v[28:31]
	s_waitcnt lgkmcnt(1)
	v_mfma_f32_16x16x32_bf16 v[32:35], v[128:131], v[204:207], v[32:35]
	v_mfma_f32_16x16x32_bf16 v[40:43], v[132:135], v[204:207], v[40:43]
	v_mfma_f32_16x16x32_bf16 v[0:3], v[136:139], v[204:207], v[0:3]
	v_mfma_f32_16x16x32_bf16 v[8:11], v[140:143], v[204:207], v[8:11]
	s_waitcnt lgkmcnt(0)
	v_mfma_f32_16x16x32_bf16 v[36:39], v[128:131], v[242:245], v[36:39]
	v_mfma_f32_16x16x32_bf16 v[44:47], v[132:135], v[242:245], v[44:47]
	v_mfma_f32_16x16x32_bf16 v[4:7], v[136:139], v[242:245], v[4:7]
	v_mfma_f32_16x16x32_bf16 v[12:15], v[140:143], v[242:245], v[12:15]
	global_load_dwordx4 v[128:131], v[248:249], off
	global_load_dwordx4 v[132:135], v[248:249], off offset:256
	global_load_dwordx4 v[136:139], v[250:251], off
	global_load_dwordx4 v[140:143], v[250:251], off offset:256
	ds_read_b128 v[196:199], v246 offset:24576
	ds_read_b128 v[200:203], v246 offset:25600
	ds_read_b128 v[204:207], v246 offset:26624
	ds_read_b128 v[242:245], v246 offset:27648
	s_add_i32 s8, s1, 5
	s_lshl_b32 s96, s8, 11
	v_lshl_add_u64 v[248:249], v[184:185], 0, s[96:97]
	v_lshl_add_u64 v[250:251], v[186:187], 0, s[96:97]
	s_waitcnt vmcnt(8) lgkmcnt(3)
	v_mfma_f32_16x16x32_bf16 v[112:115], v[144:147], v[196:199], v[112:115]
	v_mfma_f32_16x16x32_bf16 v[120:123], v[148:151], v[196:199], v[120:123]
	v_mfma_f32_16x16x32_bf16 v[80:83], v[152:155], v[196:199], v[80:83]
	v_mfma_f32_16x16x32_bf16 v[88:91], v[156:159], v[196:199], v[88:91]
	ds_read_b128 v[196:199], v246 offset:28672
	s_waitcnt lgkmcnt(3)
	v_mfma_f32_16x16x32_bf16 v[116:119], v[144:147], v[200:203], v[116:119]
	v_mfma_f32_16x16x32_bf16 v[124:127], v[148:151], v[200:203], v[124:127]
	v_mfma_f32_16x16x32_bf16 v[84:87], v[152:155], v[200:203], v[84:87]
	v_mfma_f32_16x16x32_bf16 v[92:95], v[156:159], v[200:203], v[92:95]
	ds_read_b128 v[200:203], v246 offset:29696
	s_waitcnt lgkmcnt(3)
	v_mfma_f32_16x16x32_bf16 v[96:99], v[144:147], v[204:207], v[96:99]
	v_mfma_f32_16x16x32_bf16 v[104:107], v[148:151], v[204:207], v[104:107]
	v_mfma_f32_16x16x32_bf16 v[64:67], v[152:155], v[204:207], v[64:67]
	v_mfma_f32_16x16x32_bf16 v[72:75], v[156:159], v[204:207], v[72:75]
	ds_read_b128 v[204:207], v246 offset:30720
	s_waitcnt lgkmcnt(3)
	v_mfma_f32_16x16x32_bf16 v[100:103], v[144:147], v[242:245], v[100:103]
	v_mfma_f32_16x16x32_bf16 v[108:111], v[148:151], v[242:245], v[108:111]
	v_mfma_f32_16x16x32_bf16 v[68:71], v[152:155], v[242:245], v[68:71]
	v_mfma_f32_16x16x32_bf16 v[76:79], v[156:159], v[242:245], v[76:79]
	ds_read_b128 v[242:245], v246 offset:31744
	s_waitcnt lgkmcnt(3)
	v_mfma_f32_16x16x32_bf16 v[48:51], v[144:147], v[196:199], v[48:51]
	v_mfma_f32_16x16x32_bf16 v[56:59], v[148:151], v[196:199], v[56:59]
	v_mfma_f32_16x16x32_bf16 v[16:19], v[152:155], v[196:199], v[16:19]
	v_mfma_f32_16x16x32_bf16 v[24:27], v[156:159], v[196:199], v[24:27]
	s_waitcnt lgkmcnt(2)
	v_mfma_f32_16x16x32_bf16 v[52:55], v[144:147], v[200:203], v[52:55]
	v_mfma_f32_16x16x32_bf16 v[60:63], v[148:151], v[200:203], v[60:63]
	v_mfma_f32_16x16x32_bf16 v[20:23], v[152:155], v[200:203], v[20:23]
	v_mfma_f32_16x16x32_bf16 v[28:31], v[156:159], v[200:203], v[28:31]
	s_waitcnt lgkmcnt(1)
	v_mfma_f32_16x16x32_bf16 v[32:35], v[144:147], v[204:207], v[32:35]
	v_mfma_f32_16x16x32_bf16 v[40:43], v[148:151], v[204:207], v[40:43]
	v_mfma_f32_16x16x32_bf16 v[0:3], v[152:155], v[204:207], v[0:3]
	v_mfma_f32_16x16x32_bf16 v[8:11], v[156:159], v[204:207], v[8:11]
	s_waitcnt lgkmcnt(0)
	v_mfma_f32_16x16x32_bf16 v[36:39], v[144:147], v[242:245], v[36:39]
	v_mfma_f32_16x16x32_bf16 v[44:47], v[148:151], v[242:245], v[44:47]
	v_mfma_f32_16x16x32_bf16 v[4:7], v[152:155], v[242:245], v[4:7]
	v_mfma_f32_16x16x32_bf16 v[12:15], v[156:159], v[242:245], v[12:15]
	global_load_dwordx4 v[144:147], v[248:249], off
	global_load_dwordx4 v[148:151], v[248:249], off offset:256
	global_load_dwordx4 v[152:155], v[250:251], off
	global_load_dwordx4 v[156:159], v[250:251], off offset:256
	s_waitcnt vmcnt(8)
	s_barrier
	s_add_i32 s1, s1, 4
	s_cmp_lt_u32 s1, 28
	s_cbranch_scc1 .Lg16_gu_k
	s_mov_b32 s96, 0x3c000
	s_add_i32 m0, vcc_lo, 16384
	v_lshl_add_u64 v[160:161], v[188:189], 0, s[96:97]
	global_load_lds_dwordx4 v[160:161], off
	global_load_lds_dwordx4 v[160:161], off offset:1024
	s_mov_b32 s96, 0x3e000
	s_add_i32 m0, vcc_lo, 24576
	v_lshl_add_u64 v[160:161], v[188:189], 0, s[96:97]
	global_load_lds_dwordx4 v[160:161], off
	global_load_lds_dwordx4 v[160:161], off offset:1024
	ds_read_b128 v[196:199], v246 offset:0
	ds_read_b128 v[200:203], v246 offset:1024
	ds_read_b128 v[204:207], v246 offset:2048
	ds_read_b128 v[242:245], v246 offset:3072
	s_mov_b32 s96, 0xf000
	v_lshl_add_u64 v[248:249], v[184:185], 0, s[96:97]
	v_lshl_add_u64 v[250:251], v[186:187], 0, s[96:97]
	s_waitcnt vmcnt(8) lgkmcnt(3)
	v_mfma_f32_16x16x32_bf16 v[112:115], v[128:131], v[196:199], v[112:115]
	v_mfma_f32_16x16x32_bf16 v[120:123], v[132:135], v[196:199], v[120:123]
	v_mfma_f32_16x16x32_bf16 v[80:83], v[136:139], v[196:199], v[80:83]
	v_mfma_f32_16x16x32_bf16 v[88:91], v[140:143], v[196:199], v[88:91]
	ds_read_b128 v[196:199], v246 offset:4096
	s_waitcnt lgkmcnt(3)
	v_mfma_f32_16x16x32_bf16 v[116:119], v[128:131], v[200:203], v[116:119]
	v_mfma_f32_16x16x32_bf16 v[124:127], v[132:135], v[200:203], v[124:127]
	v_mfma_f32_16x16x32_bf16 v[84:87], v[136:139], v[200:203], v[84:87]
	v_mfma_f32_16x16x32_bf16 v[92:95], v[140:143], v[200:203], v[92:95]
	ds_read_b128 v[200:203], v246 offset:5120
	s_waitcnt lgkmcnt(3)
	v_mfma_f32_16x16x32_bf16 v[96:99], v[128:131], v[204:207], v[96:99]
	v_mfma_f32_16x16x32_bf16 v[104:107], v[132:135], v[204:207], v[104:107]
	v_mfma_f32_16x16x32_bf16 v[64:67], v[136:139], v[204:207], v[64:67]
	v_mfma_f32_16x16x32_bf16 v[72:75], v[140:143], v[204:207], v[72:75]
	ds_read_b128 v[204:207], v246 offset:6144
	s_waitcnt lgkmcnt(3)
	v_mfma_f32_16x16x32_bf16 v[100:103], v[128:131], v[242:245], v[100:103]
	v_mfma_f32_16x16x32_bf16 v[108:111], v[132:135], v[242:245], v[108:111]
	v_mfma_f32_16x16x32_bf16 v[68:71], v[136:139], v[242:245], v[68:71]
	v_mfma_f32_16x16x32_bf16 v[76:79], v[140:143], v[242:245], v[76:79]
	ds_read_b128 v[242:245], v246 offset:7168
	s_waitcnt lgkmcnt(3)
	v_mfma_f32_16x16x32_bf16 v[48:51], v[128:131], v[196:199], v[48:51]
	v_mfma_f32_16x16x32_bf16 v[56:59], v[132:135], v[196:199], v[56:59]
	v_mfma_f32_16x16x32_bf16 v[16:19], v[136:139], v[196:199], v[16:19]
	v_mfma_f32_16x16x32_bf16 v[24:27], v[140:143], v[196:199], v[24:27]
	s_waitcnt lgkmcnt(2)
	v_mfma_f32_16x16x32_bf16 v[52:55], v[128:131], v[200:203], v[52:55]
	v_mfma_f32_16x16x32_bf16 v[60:63], v[132:135], v[200:203], v[60:63]
	v_mfma_f32_16x16x32_bf16 v[20:23], v[136:139], v[200:203], v[20:23]
	v_mfma_f32_16x16x32_bf16 v[28:31], v[140:143], v[200:203], v[28:31]
	s_waitcnt lgkmcnt(1)
	v_mfma_f32_16x16x32_bf16 v[32:35], v[128:131], v[204:207], v[32:35]
	v_mfma_f32_16x16x32_bf16 v[40:43], v[132:135], v[204:207], v[40:43]
	v_mfma_f32_16x16x32_bf16 v[0:3], v[136:139], v[204:207], v[0:3]
	v_mfma_f32_16x16x32_bf16 v[8:11], v[140:143], v[204:207], v[8:11]
	s_waitcnt lgkmcnt(0)
	v_mfma_f32_16x16x32_bf16 v[36:39], v[128:131], v[242:245], v[36:39]
	v_mfma_f32_16x16x32_bf16 v[44:47], v[132:135], v[242:245], v[44:47]
	v_mfma_f32_16x16x32_bf16 v[4:7], v[136:139], v[242:245], v[4:7]
	v_mfma_f32_16x16x32_bf16 v[12:15], v[140:143], v[242:245], v[12:15]
	global_load_dwordx4 v[128:131], v[248:249], off
	global_load_dwordx4 v[132:135], v[248:249], off offset:256
	global_load_dwordx4 v[136:139], v[250:251], off
	global_load_dwordx4 v[140:143], v[250:251], off offset:256
	ds_read_b128 v[196:199], v246 offset:8192
	ds_read_b128 v[200:203], v246 offset:9216
	ds_read_b128 v[204:207], v246 offset:10240
	ds_read_b128 v[242:245], v246 offset:11264
	s_mov_b32 s96, 0xf800
	v_lshl_add_u64 v[248:249], v[184:185], 0, s[96:97]
	v_lshl_add_u64 v[250:251], v[186:187], 0, s[96:97]
	s_waitcnt vmcnt(8) lgkmcnt(3)
	v_mfma_f32_16x16x32_bf16 v[112:115], v[144:147], v[196:199], v[112:115]
	v_mfma_f32_16x16x32_bf16 v[120:123], v[148:151], v[196:199], v[120:123]
	v_mfma_f32_16x16x32_bf16 v[80:83], v[152:155], v[196:199], v[80:83]
	v_mfma_f32_16x16x32_bf16 v[88:91], v[156:159], v[196:199], v[88:91]
	ds_read_b128 v[196:199], v246 offset:12288
	s_waitcnt lgkmcnt(3)
	v_mfma_f32_16x16x32_bf16 v[116:119], v[144:147], v[200:203], v[116:119]
	v_mfma_f32_16x16x32_bf16 v[124:127], v[148:151], v[200:203], v[124:127]
	v_mfma_f32_16x16x32_bf16 v[84:87], v[152:155], v[200:203], v[84:87]
	v_mfma_f32_16x16x32_bf16 v[92:95], v[156:159], v[200:203], v[92:95]
	ds_read_b128 v[200:203], v246 offset:13312
	s_waitcnt lgkmcnt(3)
	v_mfma_f32_16x16x32_bf16 v[96:99], v[144:147], v[204:207], v[96:99]
	v_mfma_f32_16x16x32_bf16 v[104:107], v[148:151], v[204:207], v[104:107]
	v_mfma_f32_16x16x32_bf16 v[64:67], v[152:155], v[204:207], v[64:67]
	v_mfma_f32_16x16x32_bf16 v[72:75], v[156:159], v[204:207], v[72:75]
	ds_read_b128 v[204:207], v246 offset:14336
	s_waitcnt lgkmcnt(3)
	v_mfma_f32_16x16x32_bf16 v[100:103], v[144:147], v[242:245], v[100:103]
	v_mfma_f32_16x16x32_bf16 v[108:111], v[148:151], v[242:245], v[108:111]
	v_mfma_f32_16x16x32_bf16 v[68:71], v[152:155], v[242:245], v[68:71]
	v_mfma_f32_16x16x32_bf16 v[76:79], v[156:159], v[242:245], v[76:79]
	ds_read_b128 v[242:245], v246 offset:15360
	s_waitcnt lgkmcnt(3)
	v_mfma_f32_16x16x32_bf16 v[48:51], v[144:147], v[196:199], v[48:51]
	v_mfma_f32_16x16x32_bf16 v[56:59], v[148:151], v[196:199], v[56:59]
	v_mfma_f32_16x16x32_bf16 v[16:19], v[152:155], v[196:199], v[16:19]
	v_mfma_f32_16x16x32_bf16 v[24:27], v[156:159], v[196:199], v[24:27]
	s_waitcnt lgkmcnt(2)
	v_mfma_f32_16x16x32_bf16 v[52:55], v[144:147], v[200:203], v[52:55]
	v_mfma_f32_16x16x32_bf16 v[60:63], v[148:151], v[200:203], v[60:63]
	v_mfma_f32_16x16x32_bf16 v[20:23], v[152:155], v[200:203], v[20:23]
	v_mfma_f32_16x16x32_bf16 v[28:31], v[156:159], v[200:203], v[28:31]
	s_waitcnt lgkmcnt(1)
	v_mfma_f32_16x16x32_bf16 v[32:35], v[144:147], v[204:207], v[32:35]
	v_mfma_f32_16x16x32_bf16 v[40:43], v[148:151], v[204:207], v[40:43]
	v_mfma_f32_16x16x32_bf16 v[0:3], v[152:155], v[204:207], v[0:3]
	v_mfma_f32_16x16x32_bf16 v[8:11], v[156:159], v[204:207], v[8:11]
	s_waitcnt lgkmcnt(0)
	v_mfma_f32_16x16x32_bf16 v[36:39], v[144:147], v[242:245], v[36:39]
	v_mfma_f32_16x16x32_bf16 v[44:47], v[148:151], v[242:245], v[44:47]
	v_mfma_f32_16x16x32_bf16 v[4:7], v[152:155], v[242:245], v[4:7]
	v_mfma_f32_16x16x32_bf16 v[12:15], v[156:159], v[242:245], v[12:15]
	global_load_dwordx4 v[144:147], v[248:249], off
	global_load_dwordx4 v[148:151], v[248:249], off offset:256
	global_load_dwordx4 v[152:155], v[250:251], off
	global_load_dwordx4 v[156:159], v[250:251], off offset:256
	s_waitcnt vmcnt(8)
	s_barrier
	ds_read_b128 v[196:199], v246 offset:16384
	ds_read_b128 v[200:203], v246 offset:17408
	ds_read_b128 v[204:207], v246 offset:18432
	ds_read_b128 v[242:245], v246 offset:19456
	s_waitcnt vmcnt(4) lgkmcnt(3)
	v_mfma_f32_16x16x32_bf16 v[112:115], v[128:131], v[196:199], v[112:115]
	v_mfma_f32_16x16x32_bf16 v[120:123], v[132:135], v[196:199], v[120:123]
	v_mfma_f32_16x16x32_bf16 v[80:83], v[136:139], v[196:199], v[80:83]
	v_mfma_f32_16x16x32_bf16 v[88:91], v[140:143], v[196:199], v[88:91]
	ds_read_b128 v[196:199], v246 offset:20480
	s_waitcnt lgkmcnt(3)
	v_mfma_f32_16x16x32_bf16 v[116:119], v[128:131], v[200:203], v[116:119]
	v_mfma_f32_16x16x32_bf16 v[124:127], v[132:135], v[200:203], v[124:127]
	v_mfma_f32_16x16x32_bf16 v[84:87], v[136:139], v[200:203], v[84:87]
	v_mfma_f32_16x16x32_bf16 v[92:95], v[140:143], v[200:203], v[92:95]
	ds_read_b128 v[200:203], v246 offset:21504
	s_waitcnt lgkmcnt(3)
	v_mfma_f32_16x16x32_bf16 v[96:99], v[128:131], v[204:207], v[96:99]
	v_mfma_f32_16x16x32_bf16 v[104:107], v[132:135], v[204:207], v[104:107]
	v_mfma_f32_16x16x32_bf16 v[64:67], v[136:139], v[204:207], v[64:67]
	v_mfma_f32_16x16x32_bf16 v[72:75], v[140:143], v[204:207], v[72:75]
	ds_read_b128 v[204:207], v246 offset:22528
	s_waitcnt lgkmcnt(3)
	v_mfma_f32_16x16x32_bf16 v[100:103], v[128:131], v[242:245], v[100:103]
	v_mfma_f32_16x16x32_bf16 v[108:111], v[132:135], v[242:245], v[108:111]
	v_mfma_f32_16x16x32_bf16 v[68:71], v[136:139], v[242:245], v[68:71]
	v_mfma_f32_16x16x32_bf16 v[76:79], v[140:143], v[242:245], v[76:79]
	ds_read_b128 v[242:245], v246 offset:23552
	s_waitcnt lgkmcnt(3)
	v_mfma_f32_16x16x32_bf16 v[48:51], v[128:131], v[196:199], v[48:51]
	v_mfma_f32_16x16x32_bf16 v[56:59], v[132:135], v[196:199], v[56:59]
	v_mfma_f32_16x16x32_bf16 v[16:19], v[136:139], v[196:199], v[16:19]
	v_mfma_f32_16x16x32_bf16 v[24:27], v[140:143], v[196:199], v[24:27]
	s_waitcnt lgkmcnt(2)
	v_mfma_f32_16x16x32_bf16 v[52:55], v[128:131], v[200:203], v[52:55]
	v_mfma_f32_16x16x32_bf16 v[60:63], v[132:135], v[200:203], v[60:63]
	v_mfma_f32_16x16x32_bf16 v[20:23], v[136:139], v[200:203], v[20:23]
	v_mfma_f32_16x16x32_bf16 v[28:31], v[140:143], v[200:203], v[28:31]
	s_waitcnt lgkmcnt(1)
	v_mfma_f32_16x16x32_bf16 v[32:35], v[128:131], v[204:207], v[32:35]
	v_mfma_f32_16x16x32_bf16 v[40:43], v[132:135], v[204:207], v[40:43]
	v_mfma_f32_16x16x32_bf16 v[0:3], v[136:139], v[204:207], v[0:3]
	v_mfma_f32_16x16x32_bf16 v[8:11], v[140:143], v[204:207], v[8:11]
	s_waitcnt lgkmcnt(0)
	v_mfma_f32_16x16x32_bf16 v[36:39], v[128:131], v[242:245], v[36:39]
	v_mfma_f32_16x16x32_bf16 v[44:47], v[132:135], v[242:245], v[44:47]
	v_mfma_f32_16x16x32_bf16 v[4:7], v[136:139], v[242:245], v[4:7]
	v_mfma_f32_16x16x32_bf16 v[12:15], v[140:143], v[242:245], v[12:15]
	ds_read_b128 v[196:199], v246 offset:24576
	ds_read_b128 v[200:203], v246 offset:25600
	ds_read_b128 v[204:207], v246 offset:26624
	ds_read_b128 v[242:245], v246 offset:27648
	s_waitcnt vmcnt(0) lgkmcnt(3)
	v_mfma_f32_16x16x32_bf16 v[112:115], v[144:147], v[196:199], v[112:115]
	v_mfma_f32_16x16x32_bf16 v[120:123], v[148:151], v[196:199], v[120:123]
	v_mfma_f32_16x16x32_bf16 v[80:83], v[152:155], v[196:199], v[80:83]
	v_mfma_f32_16x16x32_bf16 v[88:91], v[156:159], v[196:199], v[88:91]
	ds_read_b128 v[196:199], v246 offset:28672
	s_waitcnt lgkmcnt(3)
	v_mfma_f32_16x16x32_bf16 v[116:119], v[144:147], v[200:203], v[116:119]
	v_mfma_f32_16x16x32_bf16 v[124:127], v[148:151], v[200:203], v[124:127]
	v_mfma_f32_16x16x32_bf16 v[84:87], v[152:155], v[200:203], v[84:87]
	v_mfma_f32_16x16x32_bf16 v[92:95], v[156:159], v[200:203], v[92:95]
	ds_read_b128 v[200:203], v246 offset:29696
	s_waitcnt lgkmcnt(3)
	v_mfma_f32_16x16x32_bf16 v[96:99], v[144:147], v[204:207], v[96:99]
	v_mfma_f32_16x16x32_bf16 v[104:107], v[148:151], v[204:207], v[104:107]
	v_mfma_f32_16x16x32_bf16 v[64:67], v[152:155], v[204:207], v[64:67]
	v_mfma_f32_16x16x32_bf16 v[72:75], v[156:159], v[204:207], v[72:75]
	ds_read_b128 v[204:207], v246 offset:30720
	s_waitcnt lgkmcnt(3)
	v_mfma_f32_16x16x32_bf16 v[100:103], v[144:147], v[242:245], v[100:103]
	v_mfma_f32_16x16x32_bf16 v[108:111], v[148:151], v[242:245], v[108:111]
	v_mfma_f32_16x16x32_bf16 v[68:71], v[152:155], v[242:245], v[68:71]
	v_mfma_f32_16x16x32_bf16 v[76:79], v[156:159], v[242:245], v[76:79]
	ds_read_b128 v[242:245], v246 offset:31744
	v_permlane16_swap_b32_e32 v112, v116
	v_permlane16_swap_b32_e32 v113, v117
	v_permlane16_swap_b32_e32 v114, v118
	v_permlane16_swap_b32_e32 v115, v119
	v_permlane16_swap_b32_e32 v120, v124
	v_permlane16_swap_b32_e32 v121, v125
	v_permlane16_swap_b32_e32 v122, v126
	v_permlane16_swap_b32_e32 v123, v127
	v_permlane16_swap_b32_e32 v80, v84
	v_permlane16_swap_b32_e32 v81, v85
	v_permlane16_swap_b32_e32 v82, v86
	v_permlane16_swap_b32_e32 v83, v87
	v_permlane16_swap_b32_e32 v88, v92
	v_permlane16_swap_b32_e32 v89, v93
	v_permlane16_swap_b32_e32 v90, v94
	v_permlane16_swap_b32_e32 v91, v95
	v_permlane32_swap_b32_e32 v112, v116
	v_permlane32_swap_b32_e32 v113, v117
	v_permlane32_swap_b32_e32 v114, v118
	v_permlane32_swap_b32_e32 v115, v119
	v_permlane32_swap_b32_e32 v120, v124
	v_permlane32_swap_b32_e32 v121, v125
	v_permlane32_swap_b32_e32 v122, v126
	v_permlane32_swap_b32_e32 v123, v127
	v_permlane32_swap_b32_e32 v80, v84
	v_permlane32_swap_b32_e32 v81, v85
	v_permlane32_swap_b32_e32 v82, v86
	v_permlane32_swap_b32_e32 v83, v87
	v_permlane32_swap_b32_e32 v88, v92
	v_permlane32_swap_b32_e32 v89, v93
	v_permlane32_swap_b32_e32 v90, v94
	v_permlane32_swap_b32_e32 v91, v95
	s_waitcnt lgkmcnt(3)
	v_mfma_f32_16x16x32_bf16 v[48:51], v[144:147], v[196:199], v[48:51]
	v_mfma_f32_16x16x32_bf16 v[56:59], v[148:151], v[196:199], v[56:59]
	v_mfma_f32_16x16x32_bf16 v[16:19], v[152:155], v[196:199], v[16:19]
	v_mfma_f32_16x16x32_bf16 v[24:27], v[156:159], v[196:199], v[24:27]
	s_waitcnt lgkmcnt(2)
	v_mfma_f32_16x16x32_bf16 v[52:55], v[144:147], v[200:203], v[52:55]
	v_mfma_f32_16x16x32_bf16 v[60:63], v[148:151], v[200:203], v[60:63]
	v_mfma_f32_16x16x32_bf16 v[20:23], v[152:155], v[200:203], v[20:23]
	v_mfma_f32_16x16x32_bf16 v[28:31], v[156:159], v[200:203], v[28:31]
	v_permlane16_swap_b32_e32 v96, v100
	v_permlane16_swap_b32_e32 v97, v101
	v_permlane16_swap_b32_e32 v98, v102
	v_permlane16_swap_b32_e32 v99, v103
	v_permlane16_swap_b32_e32 v104, v108
	v_permlane16_swap_b32_e32 v105, v109
	v_permlane16_swap_b32_e32 v106, v110
	v_permlane16_swap_b32_e32 v107, v111
	v_permlane16_swap_b32_e32 v64, v68
	v_permlane16_swap_b32_e32 v65, v69
	v_permlane16_swap_b32_e32 v66, v70
	v_permlane16_swap_b32_e32 v67, v71
	v_permlane16_swap_b32_e32 v72, v76
	v_permlane16_swap_b32_e32 v73, v77
	v_permlane16_swap_b32_e32 v74, v78
	v_permlane16_swap_b32_e32 v75, v79
	v_permlane32_swap_b32_e32 v96, v100
	v_permlane32_swap_b32_e32 v97, v101
	v_permlane32_swap_b32_e32 v98, v102
	v_permlane32_swap_b32_e32 v99, v103
	v_permlane32_swap_b32_e32 v104, v108
	v_permlane32_swap_b32_e32 v105, v109
	v_permlane32_swap_b32_e32 v106, v110
	v_permlane32_swap_b32_e32 v107, v111
	v_permlane32_swap_b32_e32 v64, v68
	v_permlane32_swap_b32_e32 v65, v69
	v_permlane32_swap_b32_e32 v66, v70
	v_permlane32_swap_b32_e32 v67, v71
	v_permlane32_swap_b32_e32 v72, v76
	v_permlane32_swap_b32_e32 v73, v77
	v_permlane32_swap_b32_e32 v74, v78
	v_permlane32_swap_b32_e32 v75, v79
	s_waitcnt lgkmcnt(1)
	v_mfma_f32_16x16x32_bf16 v[32:35], v[144:147], v[204:207], v[32:35]
	v_mfma_f32_16x16x32_bf16 v[40:43], v[148:151], v[204:207], v[40:43]
	v_mfma_f32_16x16x32_bf16 v[0:3], v[152:155], v[204:207], v[0:3]
	v_mfma_f32_16x16x32_bf16 v[8:11], v[156:159], v[204:207], v[8:11]
	s_waitcnt lgkmcnt(0)
	v_mfma_f32_16x16x32_bf16 v[36:39], v[144:147], v[242:245], v[36:39]
	v_mfma_f32_16x16x32_bf16 v[44:47], v[148:151], v[242:245], v[44:47]
	v_mfma_f32_16x16x32_bf16 v[4:7], v[152:155], v[242:245], v[4:7]
	v_mfma_f32_16x16x32_bf16 v[12:15], v[156:159], v[242:245], v[12:15]
	v_permlane16_swap_b32_e32 v48, v52
	v_permlane16_swap_b32_e32 v49, v53
	v_permlane16_swap_b32_e32 v50, v54
	v_permlane16_swap_b32_e32 v51, v55
	v_permlane16_swap_b32_e32 v56, v60
	v_permlane16_swap_b32_e32 v57, v61
	v_permlane16_swap_b32_e32 v58, v62
	v_permlane16_swap_b32_e32 v59, v63
	v_permlane16_swap_b32_e32 v16, v20
	v_permlane16_swap_b32_e32 v17, v21
	v_permlane16_swap_b32_e32 v18, v22
	v_permlane16_swap_b32_e32 v19, v23
	v_permlane16_swap_b32_e32 v24, v28
	v_permlane16_swap_b32_e32 v25, v29
	v_permlane16_swap_b32_e32 v26, v30
	v_permlane16_swap_b32_e32 v27, v31
	v_permlane32_swap_b32_e32 v48, v52
	v_permlane32_swap_b32_e32 v49, v53
	v_permlane32_swap_b32_e32 v50, v54
	v_permlane32_swap_b32_e32 v51, v55
	v_permlane32_swap_b32_e32 v56, v60
	v_permlane32_swap_b32_e32 v57, v61
	v_permlane32_swap_b32_e32 v58, v62
	v_permlane32_swap_b32_e32 v59, v63
	v_permlane32_swap_b32_e32 v16, v20
	v_permlane32_swap_b32_e32 v17, v21
	v_permlane32_swap_b32_e32 v18, v22
	v_permlane32_swap_b32_e32 v19, v23
	v_permlane32_swap_b32_e32 v24, v28
	v_permlane32_swap_b32_e32 v25, v29
	v_permlane32_swap_b32_e32 v26, v30
	v_permlane32_swap_b32_e32 v27, v31
	s_barrier
	s_nop 7
	v_permlane16_swap_b32_e32 v32, v36
	v_permlane16_swap_b32_e32 v33, v37
	v_permlane16_swap_b32_e32 v34, v38
	v_permlane16_swap_b32_e32 v35, v39
	v_permlane16_swap_b32_e32 v40, v44
	v_permlane16_swap_b32_e32 v41, v45
	v_permlane16_swap_b32_e32 v42, v46
	v_permlane16_swap_b32_e32 v43, v47
	v_permlane16_swap_b32_e32 v0, v4
	v_permlane16_swap_b32_e32 v1, v5
	v_permlane16_swap_b32_e32 v2, v6
	v_permlane16_swap_b32_e32 v3, v7
	v_permlane16_swap_b32_e32 v8, v12
	v_permlane16_swap_b32_e32 v9, v13
	v_permlane16_swap_b32_e32 v10, v14
	v_permlane16_swap_b32_e32 v11, v15
	v_permlane32_swap_b32_e32 v32, v36
	v_permlane32_swap_b32_e32 v33, v37
	v_permlane32_swap_b32_e32 v34, v38
	v_permlane32_swap_b32_e32 v35, v39
	v_permlane32_swap_b32_e32 v40, v44
	v_permlane32_swap_b32_e32 v41, v45
	v_permlane32_swap_b32_e32 v42, v46
	v_permlane32_swap_b32_e32 v43, v47
	v_permlane32_swap_b32_e32 v0, v4
	v_permlane32_swap_b32_e32 v1, v5
	v_permlane32_swap_b32_e32 v2, v6
	v_permlane32_swap_b32_e32 v3, v7
	v_permlane32_swap_b32_e32 v8, v12
	v_permlane32_swap_b32_e32 v9, v13
	v_permlane32_swap_b32_e32 v10, v14
	v_permlane32_swap_b32_e32 v11, v15
	s_waitcnt vmcnt(0)
	s_waitcnt vmcnt(0)
	v_mul_f32_e32 v133, 0xbfb8aa3b, v112
	v_exp_f32_e32 v133, v133
	s_movk_i32 s1, 0x2400
	v_mul_lo_u32 v128, v238, s1
	v_lshl_or_b32 v131, s0, 6, v181
	v_add_f32_e32 v133, 1.0, v133
	v_lshl_or_b32 v132, v239, 1, v128
	v_and_b32_e32 v129, 0xffffffc0, v237
	v_lshl_or_b32 v128, v181, 1, v128
	v_rcp_f32_e32 v135, v133
	s_nop 0
	v_mul_f32_e32 v112, v112, v135
	v_mul_f32_e32 v96, v96, v112
	v_cvt_pk_bf16_f32 v112, v96, s0
	s_movk_i32 s0, 0x240
	v_mad_u32_u24 v96, v183, s0, v132
	ds_write_b16 v96, v112
	v_mul_f32_e32 v112, 0xbfb8aa3b, v113
	v_exp_f32_e32 v112, v112
	v_lshl_add_u32 v130, s7, 8, v129
	v_lshrrev_b32_e32 v129, 2, v240
	v_mad_u32_u24 v128, v129, s42, v128
	v_add_f32_e32 v112, 1.0, v112
	v_rcp_f32_e32 v133, v112
	s_nop 0
	v_mul_f32_e32 v112, v113, v133
	v_mul_f32_e32 v97, v97, v112
	v_cvt_pk_bf16_f32 v97, v97, s0
	ds_write_b16 v96, v97 offset:144
	v_mul_f32_e32 v97, 0xbfb8aa3b, v114
	v_exp_f32_e32 v97, v97
	s_nop 0
	v_add_f32_e32 v97, 1.0, v97
	v_rcp_f32_e32 v113, v97
	s_nop 0
	v_mul_f32_e32 v97, v114, v113
	v_mul_f32_e32 v97, v98, v97
	v_cvt_pk_bf16_f32 v97, v97, s0
	ds_write_b16 v96, v97 offset:288
	v_mul_f32_e32 v97, 0xbfb8aa3b, v115
	v_exp_f32_e32 v97, v97
	s_nop 0
	v_add_f32_e32 v97, 1.0, v97
	v_rcp_f32_e32 v112, v97
	s_nop 0
	v_mul_f32_e32 v97, v115, v112
	v_mul_f32_e32 v97, v99, v97
	v_cvt_pk_bf16_f32 v97, v97, s0
	ds_write_b16 v96, v97 offset:432
	v_mul_f32_e32 v97, 0xbfb8aa3b, v116
	v_exp_f32_e32 v97, v97
	s_nop 0
	v_add_f32_e32 v97, 1.0, v97
	v_rcp_f32_e32 v99, v97
	s_nop 0
	v_mul_f32_e32 v97, v116, v99
	v_mul_f32_e32 v97, v100, v97
	v_cvt_pk_bf16_f32 v97, v97, s0
	ds_write_b16 v96, v97 offset:1152
	v_mul_f32_e32 v97, 0xbfb8aa3b, v117
	v_exp_f32_e32 v97, v97
	s_nop 0
	v_add_f32_e32 v97, 1.0, v97
	v_rcp_f32_e32 v99, v97
	s_nop 0
	v_mul_f32_e32 v97, v117, v99
	v_mul_f32_e32 v97, v101, v97
	v_cvt_pk_bf16_f32 v97, v97, s0
	ds_write_b16 v96, v97 offset:1296
	v_mul_f32_e32 v97, 0xbfb8aa3b, v118
	v_exp_f32_e32 v97, v97
	s_nop 0
	v_add_f32_e32 v97, 1.0, v97
	v_rcp_f32_e32 v99, v97
	s_nop 0
	v_mul_f32_e32 v97, v118, v99
	v_mul_f32_e32 v97, v102, v97
	v_cvt_pk_bf16_f32 v97, v97, s0
	ds_write_b16 v96, v97 offset:1440
	v_mul_f32_e32 v97, 0xbfb8aa3b, v119
	v_exp_f32_e32 v97, v97
	s_nop 0
	v_add_f32_e32 v97, 1.0, v97
	v_rcp_f32_e32 v99, v97
	s_nop 0
	v_mul_f32_e32 v97, v119, v99
	v_mul_f32_e32 v97, v103, v97
	v_cvt_pk_bf16_f32 v97, v97, s0
	ds_write_b16 v96, v97 offset:1584
	v_mul_f32_e32 v97, 0xbfb8aa3b, v120
	v_exp_f32_e32 v97, v97
	s_nop 0
	v_add_f32_e32 v97, 1.0, v97
	v_rcp_f32_e32 v99, v97
	s_nop 0
	v_mul_f32_e32 v97, v120, v99
	v_mul_f32_e32 v97, v104, v97
	v_cvt_pk_bf16_f32 v97, v97, s0
	ds_write_b16 v96, v97 offset:2304
	v_mul_f32_e32 v97, 0xbfb8aa3b, v121
	v_exp_f32_e32 v97, v97
	s_nop 0
	v_add_f32_e32 v97, 1.0, v97
	v_rcp_f32_e32 v99, v97
	s_nop 0
	v_mul_f32_e32 v97, v121, v99
	v_mul_f32_e32 v97, v105, v97
	v_cvt_pk_bf16_f32 v97, v97, s0
	ds_write_b16 v96, v97 offset:2448
	v_mul_f32_e32 v97, 0xbfb8aa3b, v122
	v_exp_f32_e32 v97, v97
	s_nop 0
	v_add_f32_e32 v97, 1.0, v97
	v_rcp_f32_e32 v99, v97
	s_nop 0
	v_mul_f32_e32 v97, v122, v99
	v_mul_f32_e32 v97, v106, v97
	v_cvt_pk_bf16_f32 v97, v97, s0
	ds_write_b16 v96, v97 offset:2592
	v_mul_f32_e32 v97, 0xbfb8aa3b, v123
	v_exp_f32_e32 v97, v97
	s_nop 0
	v_add_f32_e32 v97, 1.0, v97
	v_rcp_f32_e32 v99, v97
	s_nop 0
	v_mul_f32_e32 v97, v123, v99
	v_mul_f32_e32 v97, v107, v97
	v_cvt_pk_bf16_f32 v97, v97, s0
	ds_write_b16 v96, v97 offset:2736
	v_mul_f32_e32 v97, 0xbfb8aa3b, v124
	v_exp_f32_e32 v97, v97
	s_nop 0
	v_add_f32_e32 v97, 1.0, v97
	v_rcp_f32_e32 v99, v97
	s_nop 0
	v_mul_f32_e32 v97, v124, v99
	v_mul_f32_e32 v97, v108, v97
	v_cvt_pk_bf16_f32 v97, v97, s0
	ds_write_b16 v96, v97 offset:3456
	v_mul_f32_e32 v97, 0xbfb8aa3b, v125
	v_exp_f32_e32 v97, v97
	s_nop 0
	v_add_f32_e32 v97, 1.0, v97
	v_rcp_f32_e32 v99, v97
	s_nop 0
	v_mul_f32_e32 v97, v125, v99
	v_mul_f32_e32 v97, v109, v97
	v_cvt_pk_bf16_f32 v97, v97, s0
	ds_write_b16 v96, v97 offset:3600
	v_mul_f32_e32 v97, 0xbfb8aa3b, v126
	v_exp_f32_e32 v97, v97
	s_nop 0
	v_add_f32_e32 v97, 1.0, v97
	v_rcp_f32_e32 v99, v97
	s_nop 0
	v_mul_f32_e32 v97, v126, v99
	v_mul_f32_e32 v97, v110, v97
	v_cvt_pk_bf16_f32 v97, v97, s0
	ds_write_b16 v96, v97 offset:3744
	v_mul_f32_e32 v97, 0xbfb8aa3b, v127
	v_exp_f32_e32 v97, v97
	s_nop 0
	v_add_f32_e32 v97, 1.0, v97
	v_rcp_f32_e32 v99, v97
	s_nop 0
	v_mul_f32_e32 v97, v127, v99
	v_mul_f32_e32 v97, v111, v97
	v_cvt_pk_bf16_f32 v97, v97, s0
	ds_write_b16 v96, v97 offset:3888
	v_mul_f32_e32 v97, 0xbfb8aa3b, v80
	v_exp_f32_e32 v97, v97
	s_nop 0
	v_add_f32_e32 v97, 1.0, v97
	v_rcp_f32_e32 v99, v97
	s_nop 0
	v_mul_f32_e32 v80, v80, v99
	v_mul_f32_e32 v64, v64, v80
	v_cvt_pk_bf16_f32 v64, v64, s0
	ds_write_b16 v96, v64 offset:4608
	v_mul_f32_e32 v64, 0xbfb8aa3b, v81
	v_exp_f32_e32 v64, v64
	s_nop 0
	v_add_f32_e32 v64, 1.0, v64
	v_rcp_f32_e32 v97, v64
	s_nop 0
	v_mul_f32_e32 v64, v81, v97
	v_mul_f32_e32 v64, v65, v64
	v_cvt_pk_bf16_f32 v64, v64, s0
	ds_write_b16 v96, v64 offset:4752
	v_mul_f32_e32 v64, 0xbfb8aa3b, v82
	v_exp_f32_e32 v64, v64
	s_nop 0
	v_add_f32_e32 v64, 1.0, v64
	v_rcp_f32_e32 v80, v64
	s_nop 0
	v_mul_f32_e32 v64, v82, v80
	v_mul_f32_e32 v64, v66, v64
	v_cvt_pk_bf16_f32 v64, v64, s0
	ds_write_b16 v96, v64 offset:4896
	v_mul_f32_e32 v64, 0xbfb8aa3b, v83
	v_exp_f32_e32 v64, v64
	s_nop 0
	v_add_f32_e32 v64, 1.0, v64
	v_rcp_f32_e32 v66, v64
	s_nop 0
	v_mul_f32_e32 v64, v83, v66
	v_mul_f32_e32 v64, v67, v64
	v_cvt_pk_bf16_f32 v64, v64, s0
	ds_write_b16 v96, v64 offset:5040
	v_mul_f32_e32 v64, 0xbfb8aa3b, v84
	v_exp_f32_e32 v64, v64
	s_nop 0
	v_add_f32_e32 v64, 1.0, v64
	v_rcp_f32_e32 v66, v64
	s_nop 0
	v_mul_f32_e32 v64, v84, v66
	v_mul_f32_e32 v64, v68, v64
	v_cvt_pk_bf16_f32 v64, v64, s0
	ds_write_b16 v96, v64 offset:5760
	v_mul_f32_e32 v64, 0xbfb8aa3b, v85
	v_exp_f32_e32 v64, v64
	s_nop 0
	v_add_f32_e32 v64, 1.0, v64
	v_rcp_f32_e32 v66, v64
	s_nop 0
	v_mul_f32_e32 v64, v85, v66
	v_mul_f32_e32 v64, v69, v64
	v_cvt_pk_bf16_f32 v64, v64, s0
	ds_write_b16 v96, v64 offset:5904
	v_mul_f32_e32 v64, 0xbfb8aa3b, v86
	v_exp_f32_e32 v64, v64
	s_nop 0
	v_add_f32_e32 v64, 1.0, v64
	v_rcp_f32_e32 v66, v64
	s_nop 0
	v_mul_f32_e32 v64, v86, v66
	v_mul_f32_e32 v64, v70, v64
	v_cvt_pk_bf16_f32 v64, v64, s0
	ds_write_b16 v96, v64 offset:6048
	v_mul_f32_e32 v64, 0xbfb8aa3b, v87
	v_exp_f32_e32 v64, v64
	s_nop 0
	v_add_f32_e32 v64, 1.0, v64
	v_rcp_f32_e32 v66, v64
	s_nop 0
	v_mul_f32_e32 v64, v87, v66
	v_mul_f32_e32 v64, v71, v64
	v_cvt_pk_bf16_f32 v64, v64, s0
	ds_write_b16 v96, v64 offset:6192
	v_mul_f32_e32 v64, 0xbfb8aa3b, v88
	v_exp_f32_e32 v64, v64
	v_ashrrev_i32_e32 v71, 5, v130
	v_or_b32_e32 v70, 1, v71
	v_add_f32_e32 v64, 1.0, v64
	v_rcp_f32_e32 v66, v64
	s_nop 0
	v_mul_f32_e32 v64, v88, v66
	v_mul_f32_e32 v64, v72, v64
	v_cvt_pk_bf16_f32 v64, v64, s0
	ds_write_b16 v96, v64 offset:6912
	v_mul_f32_e32 v64, 0xbfb8aa3b, v89
	v_exp_f32_e32 v64, v64
	s_nop 0
	v_add_f32_e32 v64, 1.0, v64
	v_rcp_f32_e32 v66, v64
	s_nop 0
	v_mul_f32_e32 v64, v89, v66
	v_mul_f32_e32 v64, v73, v64
	v_cvt_pk_bf16_f32 v64, v64, s0
	ds_write_b16 v96, v64 offset:7056
	v_mul_f32_e32 v64, 0xbfb8aa3b, v90
	v_exp_f32_e32 v64, v64
	s_nop 0
	v_add_f32_e32 v64, 1.0, v64
	v_rcp_f32_e32 v66, v64
	s_nop 0
	v_mul_f32_e32 v64, v90, v66
	v_mul_f32_e32 v64, v74, v64
	v_cvt_pk_bf16_f32 v64, v64, s0
	ds_write_b16 v96, v64 offset:7200
	v_mul_f32_e32 v64, 0xbfb8aa3b, v91
	v_exp_f32_e32 v64, v64
	s_nop 0
	v_add_f32_e32 v64, 1.0, v64
	v_rcp_f32_e32 v66, v64
	s_nop 0
	v_mul_f32_e32 v64, v91, v66
	v_mul_f32_e32 v64, v75, v64
	v_cvt_pk_bf16_f32 v64, v64, s0
	ds_write_b16 v96, v64 offset:7344
	v_mul_f32_e32 v64, 0xbfb8aa3b, v92
	v_exp_f32_e32 v64, v64
	s_nop 0
	v_add_f32_e32 v64, 1.0, v64
	v_rcp_f32_e32 v66, v64
	s_nop 0
	v_mul_f32_e32 v64, v92, v66
	v_mul_f32_e32 v64, v76, v64
	v_cvt_pk_bf16_f32 v64, v64, s0
	ds_write_b16 v96, v64 offset:8064
	v_mul_f32_e32 v64, 0xbfb8aa3b, v93
	v_exp_f32_e32 v64, v64
	s_nop 0
	v_add_f32_e32 v64, 1.0, v64
	v_rcp_f32_e32 v66, v64
	s_nop 0
	v_mul_f32_e32 v64, v93, v66
	v_mul_f32_e32 v64, v77, v64
	v_cvt_pk_bf16_f32 v64, v64, s0
	ds_write_b16 v96, v64 offset:8208
	v_mul_f32_e32 v64, 0xbfb8aa3b, v94
	v_exp_f32_e32 v64, v64
	s_nop 0
	v_add_f32_e32 v64, 1.0, v64
	v_rcp_f32_e32 v66, v64
	s_nop 0
	v_mul_f32_e32 v64, v94, v66
	v_mul_f32_e32 v64, v78, v64
	v_cvt_pk_bf16_f32 v64, v64, s0
	ds_write_b16 v96, v64 offset:8352
	v_mul_f32_e32 v64, 0xbfb8aa3b, v95
	v_exp_f32_e32 v64, v64
	s_nop 0
	v_add_f32_e32 v64, 1.0, v64
	v_rcp_f32_e32 v66, v64
	s_nop 0
	v_mul_f32_e32 v64, v95, v66
	v_mul_f32_e32 v64, v79, v64
	v_cvt_pk_bf16_f32 v64, v64, s0
	ds_write_b16 v96, v64 offset:8496
	v_ashrrev_i32_e32 v68, 4, v131
	s_waitcnt lgkmcnt(0)
	v_ashrrev_i32_e32 v69, 31, v68
	ds_read_b128 v[72:75], v128
	v_mad_i64_i32 v[64:65], s[0:1], v71, s23, v[68:69]
	v_lshlrev_b64 v[64:65], 10, v[64:65]
	v_lshlrev_b32_e32 v66, 6, v181
	v_lshl_add_u64 v[64:65], s[66:67], 0, v[64:65]
	v_and_b32_e32 v176, 0x200, v66
	v_lshl_add_u64 v[76:77], v[64:65], 0, v[176:177]
	v_lshlrev_b32_e32 v66, 4, v129
	v_mov_b32_e32 v67, v177
	v_lshl_add_u64 v[64:65], v[76:77], 0, v[66:67]
	s_waitcnt lgkmcnt(0)
	global_store_dwordx4 v[64:65], v[72:75], off
	ds_read_b128 v[72:75], v128 offset:2304
	v_or_b32_e32 v64, 0x100, v66
	v_mov_b32_e32 v65, v177
	v_lshl_add_u64 v[76:77], v[76:77], 0, v[64:65]
	s_waitcnt lgkmcnt(0)
	global_store_dwordx4 v[76:77], v[72:75], off
	ds_read_b128 v[72:75], v128 offset:4608
	v_mad_i64_i32 v[76:77], s[0:1], v70, s23, v[68:69]
	v_lshlrev_b64 v[76:77], 10, v[76:77]
	v_lshl_add_u64 v[76:77], s[66:67], 0, v[76:77]
	v_lshl_add_u64 v[76:77], v[76:77], 0, v[176:177]
	v_lshl_add_u64 v[78:79], v[76:77], 0, v[66:67]
	v_mul_f32_e32 v69, 0xbfb8aa3b, v48
	s_waitcnt lgkmcnt(0)
	global_store_dwordx4 v[78:79], v[72:75], off
	ds_read_b128 v[72:75], v128 offset:6912
	v_exp_f32_e32 v69, v69
	v_lshl_add_u64 v[76:77], v[76:77], 0, v[64:65]
	v_add_f32_e32 v69, 1.0, v69
	s_waitcnt lgkmcnt(0)
	global_store_dwordx4 v[76:77], v[72:75], off
	s_waitcnt lgkmcnt(0)
	s_nop 1
	v_rcp_f32_e32 v73, v69
	s_nop 0
	v_mul_f32_e32 v48, v48, v73
	v_mul_f32_e32 v32, v32, v48
	v_cvt_pk_bf16_f32 v32, v32, s0
	ds_write_b16 v96, v32
	v_mul_f32_e32 v32, 0xbfb8aa3b, v49
	v_exp_f32_e32 v32, v32
	s_nop 0
	v_add_f32_e32 v32, 1.0, v32
	v_rcp_f32_e32 v69, v32
	s_nop 0
	v_mul_f32_e32 v32, v49, v69
	v_mul_f32_e32 v32, v33, v32
	v_cvt_pk_bf16_f32 v32, v32, s0
	ds_write_b16 v96, v32 offset:144
	v_mul_f32_e32 v32, 0xbfb8aa3b, v50
	v_exp_f32_e32 v32, v32
	s_nop 0
	v_add_f32_e32 v32, 1.0, v32
	v_rcp_f32_e32 v48, v32
	s_nop 0
	v_mul_f32_e32 v32, v50, v48
	v_mul_f32_e32 v32, v34, v32
	v_cvt_pk_bf16_f32 v32, v32, s0
	ds_write_b16 v96, v32 offset:288
	v_mul_f32_e32 v32, 0xbfb8aa3b, v51
	v_exp_f32_e32 v32, v32
	s_nop 0
	v_add_f32_e32 v32, 1.0, v32
	v_rcp_f32_e32 v34, v32
	s_nop 0
	v_mul_f32_e32 v32, v51, v34
	v_mul_f32_e32 v32, v35, v32
	v_cvt_pk_bf16_f32 v32, v32, s0
	ds_write_b16 v96, v32 offset:432
	v_mul_f32_e32 v32, 0xbfb8aa3b, v52
	v_exp_f32_e32 v32, v32
	s_nop 0
	v_add_f32_e32 v32, 1.0, v32
	v_rcp_f32_e32 v34, v32
	s_nop 0
	v_mul_f32_e32 v32, v52, v34
	v_mul_f32_e32 v32, v36, v32
	v_cvt_pk_bf16_f32 v32, v32, s0
	ds_write_b16 v96, v32 offset:1152
	v_mul_f32_e32 v32, 0xbfb8aa3b, v53
	v_exp_f32_e32 v32, v32
	s_nop 0
	v_add_f32_e32 v32, 1.0, v32
	v_rcp_f32_e32 v34, v32
	s_nop 0
	v_mul_f32_e32 v32, v53, v34
	v_mul_f32_e32 v32, v37, v32
	v_cvt_pk_bf16_f32 v32, v32, s0
	ds_write_b16 v96, v32 offset:1296
	v_mul_f32_e32 v32, 0xbfb8aa3b, v54
	v_exp_f32_e32 v32, v32
	s_nop 0
	v_add_f32_e32 v32, 1.0, v32
	v_rcp_f32_e32 v34, v32
	s_nop 0
	v_mul_f32_e32 v32, v54, v34
	v_mul_f32_e32 v32, v38, v32
	v_cvt_pk_bf16_f32 v32, v32, s0
	ds_write_b16 v96, v32 offset:1440
	v_mul_f32_e32 v32, 0xbfb8aa3b, v55
	v_exp_f32_e32 v32, v32
	s_nop 0
	v_add_f32_e32 v32, 1.0, v32
	v_rcp_f32_e32 v34, v32
	s_nop 0
	v_mul_f32_e32 v32, v55, v34
	v_mul_f32_e32 v32, v39, v32
	v_cvt_pk_bf16_f32 v32, v32, s0
	ds_write_b16 v96, v32 offset:1584
	v_mul_f32_e32 v32, 0xbfb8aa3b, v56
	v_exp_f32_e32 v32, v32
	s_nop 0
	v_add_f32_e32 v32, 1.0, v32
	v_rcp_f32_e32 v34, v32
	s_nop 0
	v_mul_f32_e32 v32, v56, v34
	v_mul_f32_e32 v32, v40, v32
	v_cvt_pk_bf16_f32 v32, v32, s0
	ds_write_b16 v96, v32 offset:2304
	v_mul_f32_e32 v32, 0xbfb8aa3b, v57
	v_exp_f32_e32 v32, v32
	s_nop 0
	v_add_f32_e32 v32, 1.0, v32
	v_rcp_f32_e32 v34, v32
	s_nop 0
	v_mul_f32_e32 v32, v57, v34
	v_mul_f32_e32 v32, v41, v32
	v_cvt_pk_bf16_f32 v32, v32, s0
	ds_write_b16 v96, v32 offset:2448
	v_mul_f32_e32 v32, 0xbfb8aa3b, v58
	v_exp_f32_e32 v32, v32
	s_nop 0
	v_add_f32_e32 v32, 1.0, v32
	v_rcp_f32_e32 v34, v32
	s_nop 0
	v_mul_f32_e32 v32, v58, v34
	v_mul_f32_e32 v32, v42, v32
	v_cvt_pk_bf16_f32 v32, v32, s0
	ds_write_b16 v96, v32 offset:2592
	v_mul_f32_e32 v32, 0xbfb8aa3b, v59
	v_exp_f32_e32 v32, v32
	s_nop 0
	v_add_f32_e32 v32, 1.0, v32
	v_rcp_f32_e32 v34, v32
	s_nop 0
	v_mul_f32_e32 v32, v59, v34
	v_mul_f32_e32 v32, v43, v32
	v_cvt_pk_bf16_f32 v32, v32, s0
	ds_write_b16 v96, v32 offset:2736
	v_mul_f32_e32 v32, 0xbfb8aa3b, v60
	v_exp_f32_e32 v32, v32
	s_nop 0
	v_add_f32_e32 v32, 1.0, v32
	v_rcp_f32_e32 v34, v32
	s_nop 0
	v_mul_f32_e32 v32, v60, v34
	v_mul_f32_e32 v32, v44, v32
	v_cvt_pk_bf16_f32 v32, v32, s0
	ds_write_b16 v96, v32 offset:3456
	v_mul_f32_e32 v32, 0xbfb8aa3b, v61
	v_exp_f32_e32 v32, v32
	s_nop 0
	v_add_f32_e32 v32, 1.0, v32
	v_rcp_f32_e32 v34, v32
	s_nop 0
	v_mul_f32_e32 v32, v61, v34
	v_mul_f32_e32 v32, v45, v32
	v_cvt_pk_bf16_f32 v32, v32, s0
	ds_write_b16 v96, v32 offset:3600
	v_mul_f32_e32 v32, 0xbfb8aa3b, v62
	v_exp_f32_e32 v32, v32
	s_nop 0
	v_add_f32_e32 v32, 1.0, v32
	v_rcp_f32_e32 v34, v32
	s_nop 0
	v_mul_f32_e32 v32, v62, v34
	v_mul_f32_e32 v32, v46, v32
	v_cvt_pk_bf16_f32 v32, v32, s0
	ds_write_b16 v96, v32 offset:3744
	v_mul_f32_e32 v32, 0xbfb8aa3b, v63
	v_exp_f32_e32 v32, v32
	s_nop 0
	v_add_f32_e32 v32, 1.0, v32
	v_rcp_f32_e32 v34, v32
	s_nop 0
	v_mul_f32_e32 v32, v63, v34
	v_mul_f32_e32 v32, v47, v32
	v_cvt_pk_bf16_f32 v32, v32, s0
	ds_write_b16 v96, v32 offset:3888
	v_mul_f32_e32 v32, 0xbfb8aa3b, v16
	v_exp_f32_e32 v32, v32
	s_nop 0
	v_add_f32_e32 v32, 1.0, v32
	v_rcp_f32_e32 v34, v32
	s_nop 0
	v_mul_f32_e32 v16, v16, v34
	v_mul_f32_e32 v0, v0, v16
	v_cvt_pk_bf16_f32 v0, v0, s0
	ds_write_b16 v96, v0 offset:4608
	v_mul_f32_e32 v0, 0xbfb8aa3b, v17
	v_exp_f32_e32 v0, v0
	s_nop 0
	v_add_f32_e32 v0, 1.0, v0
	v_rcp_f32_e32 v32, v0
	s_nop 0
	v_mul_f32_e32 v0, v17, v32
	v_mul_f32_e32 v0, v1, v0
	v_cvt_pk_bf16_f32 v0, v0, s0
	ds_write_b16 v96, v0 offset:4752
	v_mul_f32_e32 v0, 0xbfb8aa3b, v18
	v_exp_f32_e32 v0, v0
	s_nop 0
	v_add_f32_e32 v0, 1.0, v0
	v_rcp_f32_e32 v16, v0
	s_nop 0
	v_mul_f32_e32 v0, v18, v16
	v_mul_f32_e32 v0, v2, v0
	v_cvt_pk_bf16_f32 v0, v0, s0
	ds_write_b16 v96, v0 offset:4896
	v_mul_f32_e32 v0, 0xbfb8aa3b, v19
	v_exp_f32_e32 v0, v0
	s_nop 0
	v_add_f32_e32 v0, 1.0, v0
	v_rcp_f32_e32 v2, v0
	s_nop 0
	v_mul_f32_e32 v0, v19, v2
	v_mul_f32_e32 v0, v3, v0
	v_cvt_pk_bf16_f32 v0, v0, s0
	ds_write_b16 v96, v0 offset:5040
	v_mul_f32_e32 v0, 0xbfb8aa3b, v20
	v_exp_f32_e32 v0, v0
	s_nop 0
	v_add_f32_e32 v0, 1.0, v0
	v_rcp_f32_e32 v2, v0
	s_nop 0
	v_mul_f32_e32 v0, v20, v2
	v_mul_f32_e32 v0, v4, v0
	v_cvt_pk_bf16_f32 v0, v0, s0
	ds_write_b16 v96, v0 offset:5760
	v_mul_f32_e32 v0, 0xbfb8aa3b, v21
	v_exp_f32_e32 v0, v0
	s_nop 0
	v_add_f32_e32 v0, 1.0, v0
	v_rcp_f32_e32 v2, v0
	s_nop 0
	v_mul_f32_e32 v0, v21, v2
	v_mul_f32_e32 v0, v5, v0
	v_cvt_pk_bf16_f32 v0, v0, s0
	ds_write_b16 v96, v0 offset:5904
	v_mul_f32_e32 v0, 0xbfb8aa3b, v22
	v_exp_f32_e32 v0, v0
	s_nop 0
	v_add_f32_e32 v0, 1.0, v0
	v_rcp_f32_e32 v2, v0
	s_nop 0
	v_mul_f32_e32 v0, v22, v2
	v_mul_f32_e32 v0, v6, v0
	v_cvt_pk_bf16_f32 v0, v0, s0
	ds_write_b16 v96, v0 offset:6048
	v_mul_f32_e32 v0, 0xbfb8aa3b, v23
	v_exp_f32_e32 v0, v0
	s_nop 0
	v_add_f32_e32 v0, 1.0, v0
	v_rcp_f32_e32 v2, v0
	s_nop 0
	v_mul_f32_e32 v0, v23, v2
	v_mul_f32_e32 v0, v7, v0
	v_cvt_pk_bf16_f32 v0, v0, s0
	ds_write_b16 v96, v0 offset:6192
	v_mul_f32_e32 v0, 0xbfb8aa3b, v24
	v_exp_f32_e32 v0, v0
	s_nop 0
	v_add_f32_e32 v0, 1.0, v0
	v_rcp_f32_e32 v2, v0
	s_nop 0
	v_mul_f32_e32 v0, v24, v2
	v_mul_f32_e32 v0, v8, v0
	v_cvt_pk_bf16_f32 v0, v0, s0
	ds_write_b16 v96, v0 offset:6912
	v_mul_f32_e32 v0, 0xbfb8aa3b, v25
	v_exp_f32_e32 v0, v0
	s_nop 0
	v_add_f32_e32 v0, 1.0, v0
	v_rcp_f32_e32 v2, v0
	s_nop 0
	v_mul_f32_e32 v0, v25, v2
	v_mul_f32_e32 v0, v9, v0
	v_cvt_pk_bf16_f32 v0, v0, s0
	ds_write_b16 v96, v0 offset:7056
	v_mul_f32_e32 v0, 0xbfb8aa3b, v26
	v_exp_f32_e32 v0, v0
	s_nop 0
	v_add_f32_e32 v0, 1.0, v0
	v_rcp_f32_e32 v2, v0
	s_nop 0
	v_mul_f32_e32 v0, v26, v2
	v_mul_f32_e32 v0, v10, v0
	v_cvt_pk_bf16_f32 v0, v0, s0
	ds_write_b16 v96, v0 offset:7200
	v_mul_f32_e32 v0, 0xbfb8aa3b, v27
	v_exp_f32_e32 v0, v0
	s_nop 0
	v_add_f32_e32 v0, 1.0, v0
	v_rcp_f32_e32 v2, v0
	s_nop 0
	v_mul_f32_e32 v0, v27, v2
	v_mul_f32_e32 v0, v11, v0
	v_cvt_pk_bf16_f32 v0, v0, s0
	ds_write_b16 v96, v0 offset:7344
	v_mul_f32_e32 v0, 0xbfb8aa3b, v28
	v_exp_f32_e32 v0, v0
	s_nop 0
	v_add_f32_e32 v0, 1.0, v0
	v_rcp_f32_e32 v2, v0
	s_nop 0
	v_mul_f32_e32 v0, v28, v2
	v_mul_f32_e32 v0, v12, v0
	v_cvt_pk_bf16_f32 v0, v0, s0
	ds_write_b16 v96, v0 offset:8064
	v_mul_f32_e32 v0, 0xbfb8aa3b, v29
	v_exp_f32_e32 v0, v0
	s_nop 0
	v_add_f32_e32 v0, 1.0, v0
	v_rcp_f32_e32 v2, v0
	s_nop 0
	v_mul_f32_e32 v0, v29, v2
	v_mul_f32_e32 v0, v13, v0
	v_cvt_pk_bf16_f32 v0, v0, s0
	ds_write_b16 v96, v0 offset:8208
	v_mul_f32_e32 v0, 0xbfb8aa3b, v30
	v_exp_f32_e32 v0, v0
	s_nop 0
	v_add_f32_e32 v0, 1.0, v0
	v_rcp_f32_e32 v2, v0
	s_nop 0
	v_mul_f32_e32 v0, v30, v2
	v_mul_f32_e32 v0, v14, v0
	v_cvt_pk_bf16_f32 v0, v0, s0
	ds_write_b16 v96, v0 offset:8352
	v_mul_f32_e32 v0, 0xbfb8aa3b, v31
	v_exp_f32_e32 v0, v0
	s_nop 0
	v_add_f32_e32 v0, 1.0, v0
	v_rcp_f32_e32 v2, v0
	s_nop 0
	v_mul_f32_e32 v0, v31, v2
	v_mul_f32_e32 v0, v15, v0
	v_cvt_pk_bf16_f32 v0, v0, s0
	ds_write_b16 v96, v0 offset:8496
	v_or_b32_e32 v4, 2, v68
	s_waitcnt lgkmcnt(0)
	v_ashrrev_i32_e32 v5, 31, v4
	ds_read_b128 v[0:3], v128
	v_mad_i64_i32 v[6:7], s[0:1], v71, s23, v[4:5]
	v_lshlrev_b64 v[6:7], 10, v[6:7]
	v_lshl_add_u64 v[6:7], s[66:67], 0, v[6:7]
	v_lshl_add_u64 v[6:7], v[6:7], 0, v[176:177]
	v_lshl_add_u64 v[8:9], v[6:7], 0, v[66:67]
	s_waitcnt lgkmcnt(0)
	global_store_dwordx4 v[8:9], v[0:3], off
	ds_read_b128 v[0:3], v128 offset:2304
	v_lshl_add_u64 v[6:7], v[6:7], 0, v[64:65]
	v_mad_i64_i32 v[4:5], s[0:1], v70, s23, v[4:5]
	v_lshlrev_b64 v[4:5], 10, v[4:5]
	s_waitcnt lgkmcnt(0)
	global_store_dwordx4 v[6:7], v[0:3], off
	ds_read_b128 v[0:3], v128 offset:4608
	v_lshl_add_u64 v[4:5], s[66:67], 0, v[4:5]
	v_lshl_add_u64 v[4:5], v[4:5], 0, v[176:177]
	v_lshl_add_u64 v[6:7], v[4:5], 0, v[66:67]
	v_lshl_add_u64 v[4:5], v[4:5], 0, v[64:65]
	s_waitcnt lgkmcnt(0)
	global_store_dwordx4 v[6:7], v[0:3], off
	ds_read_b128 v[0:3], v128 offset:6912
	v_readlane_b32 s0, v254, 11
	s_add_i32 s2, s2, s0
	s_cmp_lt_i32 s2, s3
	s_waitcnt lgkmcnt(0)
	global_store_dwordx4 v[4:5], v[0:3], off
	s_waitcnt lgkmcnt(0)
	s_barrier
	s_cbranch_scc1 .LBB0_1031

.LBB0_1086:
	s_ashr_i32 s6, s2, 31
	s_lshr_b32 s6, s6, 26
	s_add_i32 s6, s2, s6
	s_ashr_i32 s7, s6, 6
	s_lshl_b32 s7, s7, 3
	s_sub_i32 s8, s25, s7
	s_min_i32 s8, s8, 8
	s_abs_i32 s9, s8
	v_cvt_f32_u32_e32 v0, s9
	s_sub_i32 s12, 0, s9
	s_andn2_b32 s6, s6, 63
	s_sub_i32 s10, s2, s6
	v_rcp_iflag_f32_e32 v0, v0
	s_abs_i32 s6, s10
	s_xor_b32 s11, s10, s8
	s_ashr_i32 s11, s11, 31
	v_mul_f32_e32 v0, 0x4f7ffffe, v0
	v_cvt_u32_f32_e32 v0, v0
	v_mov_b32_e32 v181, v179
	v_readfirstlane_b32 s13, v0
	s_mul_i32 s12, s12, s13
	s_mul_hi_u32 s12, s13, s12
	s_add_i32 s13, s13, s12
	s_mul_hi_u32 s12, s6, s13
	s_mul_i32 s13, s12, s9
	s_sub_i32 s6, s6, s13
	s_add_i32 s14, s12, 1
	s_sub_i32 s13, s6, s9
	s_cmp_ge_u32 s6, s9
	s_cselect_b32 s12, s14, s12
	s_cselect_b32 s6, s13, s6
	s_add_i32 s13, s12, 1
	s_cmp_ge_u32 s6, s9
	s_cselect_b32 s6, s13, s12
	s_xor_b32 s6, s6, s11
	s_sub_i32 s6, s6, s11
	s_mul_i32 s8, s8, s6
	s_add_i32 s7, s7, s5
	s_sub_i32 s8, s10, s8
	v_ashrrev_i32_e32 v237, 6, v181
	s_add_i32 s7, s7, s8
	v_lshlrev_b32_e32 v0, 1, v237
	v_bfe_u32 v183, v181, 5, 1
	v_lshl_add_u32 v2, s7, 3, v0
	v_mov_b64_e32 v[0:1], s[66:67]
	v_and_b32_e32 v238, 31, v181
	v_mad_i64_i32 v[0:1], s[8:9], v2, s24, v[0:1]
	v_lshlrev_b32_e32 v176, 9, v183
	v_lshl_add_u64 v[0:1], v[0:1], 0, v[176:177]
	v_lshlrev_b32_e32 v176, 4, v238
	v_ashrrev_i32_e32 v38, 2, v181
	s_mul_i32 s8, s6, 0xb0000
	v_lshl_add_u64 v[184:185], v[0:1], 0, v[176:177]
	s_mul_hi_i32 s9, s6, 0xb0000
	s_add_u32 s8, s3, s8
	v_lshlrev_b32_e32 v0, 5, v38
	s_addc_u32 s9, s4, s9
	v_ashrrev_i32_e32 v1, 31, v0
	v_lshlrev_b32_e32 v2, 4, v181
	v_lshl_add_u64 v[0:1], v[0:1], 1, s[8:9]
	v_and_b32_e32 v176, 48, v2
	v_lshl_add_u64 v[186:187], v[0:1], 0, v[176:177]
	s_movk_i32 s8, 0x2000
	v_add_co_u32_e32 v34, vcc, s8, v186
	v_mul_u32_u24_e32 v36, 40, v238
	s_nop 0
	v_addc_co_u32_e32 v35, vcc, 0, v187, vcc
	v_lshlrev_b32_e32 v37, 4, v183
	v_lshl_add_u32 v240, v36, 1, v37
	v_add_co_u32_e32 v36, vcc, s24, v184
	s_movk_i32 s9, 0x50
	s_nop 0
	v_addc_co_u32_e32 v37, vcc, 0, v185, vcc
	v_and_b32_e32 v239, 63, v181
	v_bfe_u32 v247, v181, 4, 2
	v_lshlrev_b32_e32 v247, 1, v247
	v_mov_b32_e32 v176, 0x78
	v_lshrrev_b32_e32 v247, v247, v176
	v_and_b32_e32 v247, 3, v247
	v_and_b32_e32 v246, 3, v181
	v_xor_b32_e32 v247, v247, v246
	v_lshlrev_b32_e32 v247, 4, v247
	v_and_b32_e32 v188, 0xffffffcf, v186
	v_or_b32_e32 v188, v188, v247
	v_mov_b32_e32 v189, v187
	v_lshrrev_b32_e32 v176, 6, v181
	v_lshlrev_b32_e32 v247, 11, v176
	v_lshlrev_b32_e32 v176, 10, v176
	v_lshl_add_u64 v[188:189], v[188:189], 0, v[176:177]
	v_readfirstlane_b32 vcc_lo, v247
	v_bfe_u32 v247, v181, 4, 1
	v_lshlrev_b32_e32 v176, 9, v183
	v_lshl_add_u32 v176, v247, 8, v176
	v_lshl_add_u64 v[184:185], v[184:185], 0, v[176:177]
	v_mov_b32_e32 v176, s24
	v_lshl_add_u64 v[186:187], v[184:185], 0, v[176:177]
	v_mov_b32_e32 v176, 0x78
	v_bfe_u32 v247, v181, 2, 2
	v_lshlrev_b32_e32 v247, 1, v247
	v_lshrrev_b32_e32 v247, v247, v176
	v_and_b32_e32 v247, 3, v247
	v_bfe_u32 v246, v181, 4, 2
	v_xor_b32_e32 v247, v247, v246
	v_lshlrev_b32_e32 v247, 4, v247
	v_and_b32_e32 v246, 15, v181
	v_lshl_add_u32 v246, v246, 6, v247
	s_mov_b32 s96, 0
	s_mov_b32 m0, vcc_lo
	v_lshl_add_u64 v[160:161], v[188:189], 0, s[96:97]
	global_load_lds_dwordx4 v[160:161], off
	global_load_lds_dwordx4 v[160:161], off offset:1024
	s_movk_i32 s96, 0x2000
	s_add_i32 m0, vcc_lo, 8192
	v_lshl_add_u64 v[160:161], v[188:189], 0, s[96:97]
	global_load_lds_dwordx4 v[160:161], off
	global_load_lds_dwordx4 v[160:161], off offset:1024
	s_mov_b32 s96, 0
	v_lshl_add_u64 v[248:249], v[184:185], 0, s[96:97]
	v_lshl_add_u64 v[250:251], v[186:187], 0, s[96:97]
	global_load_dwordx4 v[128:131], v[248:249], off
	global_load_dwordx4 v[132:135], v[248:249], off offset:256
	global_load_dwordx4 v[136:139], v[250:251], off
	global_load_dwordx4 v[140:143], v[250:251], off offset:256
	s_movk_i32 s96, 0x800
	v_lshl_add_u64 v[248:249], v[184:185], 0, s[96:97]
	v_lshl_add_u64 v[250:251], v[186:187], 0, s[96:97]
	global_load_dwordx4 v[144:147], v[248:249], off
	global_load_dwordx4 v[148:151], v[248:249], off offset:256
	global_load_dwordx4 v[152:155], v[250:251], off
	global_load_dwordx4 v[156:159], v[250:251], off offset:256
	v_mov_b32_e32 v0, 0
	v_mov_b32_e32 v1, 0
	v_mov_b32_e32 v2, 0
	v_mov_b32_e32 v3, 0
	v_mov_b32_e32 v4, 0
	v_mov_b32_e32 v5, 0
	v_mov_b32_e32 v6, 0
	v_mov_b32_e32 v7, 0
	v_mov_b32_e32 v8, 0
	v_mov_b32_e32 v9, 0
	v_mov_b32_e32 v10, 0
	v_mov_b32_e32 v11, 0
	v_mov_b32_e32 v12, 0
	v_mov_b32_e32 v13, 0
	v_mov_b32_e32 v14, 0
	v_mov_b32_e32 v15, 0
	v_mov_b32_e32 v16, 0
	v_mov_b32_e32 v17, 0
	v_mov_b32_e32 v18, 0
	v_mov_b32_e32 v19, 0
	v_mov_b32_e32 v20, 0
	v_mov_b32_e32 v21, 0
	v_mov_b32_e32 v22, 0
	v_mov_b32_e32 v23, 0
	v_mov_b32_e32 v24, 0
	v_mov_b32_e32 v25, 0
	v_mov_b32_e32 v26, 0
	v_mov_b32_e32 v27, 0
	v_mov_b32_e32 v28, 0
	v_mov_b32_e32 v29, 0
	v_mov_b32_e32 v30, 0
	v_mov_b32_e32 v31, 0
	v_mov_b32_e32 v32, 0
	v_mov_b32_e32 v33, 0
	v_mov_b32_e32 v34, 0
	v_mov_b32_e32 v35, 0
	v_mov_b32_e32 v36, 0
	v_mov_b32_e32 v37, 0
	v_mov_b32_e32 v38, 0
	v_mov_b32_e32 v39, 0
	v_mov_b32_e32 v40, 0
	v_mov_b32_e32 v41, 0
	v_mov_b32_e32 v42, 0
	v_mov_b32_e32 v43, 0
	v_mov_b32_e32 v44, 0
	v_mov_b32_e32 v45, 0
	v_mov_b32_e32 v46, 0
	v_mov_b32_e32 v47, 0
	v_mov_b32_e32 v48, 0
	v_mov_b32_e32 v49, 0
	v_mov_b32_e32 v50, 0
	v_mov_b32_e32 v51, 0
	v_mov_b32_e32 v52, 0
	v_mov_b32_e32 v53, 0
	v_mov_b32_e32 v54, 0
	v_mov_b32_e32 v55, 0
	v_mov_b32_e32 v56, 0
	v_mov_b32_e32 v57, 0
	v_mov_b32_e32 v58, 0
	v_mov_b32_e32 v59, 0
	v_mov_b32_e32 v60, 0
	v_mov_b32_e32 v61, 0
	v_mov_b32_e32 v62, 0
	v_mov_b32_e32 v63, 0
	v_mov_b32_e32 v64, 0
	v_mov_b32_e32 v65, 0
	v_mov_b32_e32 v66, 0
	v_mov_b32_e32 v67, 0
	v_mov_b32_e32 v68, 0
	v_mov_b32_e32 v69, 0
	v_mov_b32_e32 v70, 0
	v_mov_b32_e32 v71, 0
	v_mov_b32_e32 v72, 0
	v_mov_b32_e32 v73, 0
	v_mov_b32_e32 v74, 0
	v_mov_b32_e32 v75, 0
	v_mov_b32_e32 v76, 0
	v_mov_b32_e32 v77, 0
	v_mov_b32_e32 v78, 0
	v_mov_b32_e32 v79, 0
	v_mov_b32_e32 v80, 0
	v_mov_b32_e32 v81, 0
	v_mov_b32_e32 v82, 0
	v_mov_b32_e32 v83, 0
	v_mov_b32_e32 v84, 0
	v_mov_b32_e32 v85, 0
	v_mov_b32_e32 v86, 0
	v_mov_b32_e32 v87, 0
	v_mov_b32_e32 v88, 0
	v_mov_b32_e32 v89, 0
	v_mov_b32_e32 v90, 0
	v_mov_b32_e32 v91, 0
	v_mov_b32_e32 v92, 0
	v_mov_b32_e32 v93, 0
	v_mov_b32_e32 v94, 0
	v_mov_b32_e32 v95, 0
	v_mov_b32_e32 v96, 0
	v_mov_b32_e32 v97, 0
	v_mov_b32_e32 v98, 0
	v_mov_b32_e32 v99, 0
	v_mov_b32_e32 v100, 0
	v_mov_b32_e32 v101, 0
	v_mov_b32_e32 v102, 0
	v_mov_b32_e32 v103, 0
	v_mov_b32_e32 v104, 0
	v_mov_b32_e32 v105, 0
	v_mov_b32_e32 v106, 0
	v_mov_b32_e32 v107, 0
	v_mov_b32_e32 v108, 0
	v_mov_b32_e32 v109, 0
	v_mov_b32_e32 v110, 0
	v_mov_b32_e32 v111, 0
	v_mov_b32_e32 v112, 0
	v_mov_b32_e32 v113, 0
	v_mov_b32_e32 v114, 0
	v_mov_b32_e32 v115, 0
	v_mov_b32_e32 v116, 0
	v_mov_b32_e32 v117, 0
	v_mov_b32_e32 v118, 0
	v_mov_b32_e32 v119, 0
	v_mov_b32_e32 v120, 0
	v_mov_b32_e32 v121, 0
	v_mov_b32_e32 v122, 0
	v_mov_b32_e32 v123, 0
	v_mov_b32_e32 v124, 0
	v_mov_b32_e32 v125, 0
	v_mov_b32_e32 v126, 0
	v_mov_b32_e32 v127, 0
	s_mov_b32 s8, 0
	s_waitcnt vmcnt(4)
	s_barrier
.Lg16_down_k:
	s_add_i32 s9, s8, 2
	s_lshl_b32 s96, s9, 13
	s_add_i32 m0, vcc_lo, 16384
	v_lshl_add_u64 v[160:161], v[188:189], 0, s[96:97]
	global_load_lds_dwordx4 v[160:161], off
	global_load_lds_dwordx4 v[160:161], off offset:1024
	s_add_i32 s9, s8, 3
	s_lshl_b32 s96, s9, 13
	s_add_i32 m0, vcc_lo, 24576
	v_lshl_add_u64 v[160:161], v[188:189], 0, s[96:97]
	global_load_lds_dwordx4 v[160:161], off
	global_load_lds_dwordx4 v[160:161], off offset:1024
	ds_read_b128 v[196:199], v246 offset:0
	ds_read_b128 v[200:203], v246 offset:1024
	ds_read_b128 v[204:207], v246 offset:2048
	ds_read_b128 v[242:245], v246 offset:3072
	s_add_i32 s9, s8, 2
	s_lshl_b32 s96, s9, 11
	v_lshl_add_u64 v[248:249], v[184:185], 0, s[96:97]
	v_lshl_add_u64 v[250:251], v[186:187], 0, s[96:97]
	s_waitcnt vmcnt(8) lgkmcnt(3)
	v_mfma_f32_16x16x32_bf16 v[112:115], v[128:131], v[196:199], v[112:115]
	v_mfma_f32_16x16x32_bf16 v[120:123], v[132:135], v[196:199], v[120:123]
	v_mfma_f32_16x16x32_bf16 v[48:51], v[136:139], v[196:199], v[48:51]
	v_mfma_f32_16x16x32_bf16 v[56:59], v[140:143], v[196:199], v[56:59]
	ds_read_b128 v[196:199], v246 offset:4096
	s_waitcnt lgkmcnt(3)
	v_mfma_f32_16x16x32_bf16 v[116:119], v[128:131], v[200:203], v[116:119]
	v_mfma_f32_16x16x32_bf16 v[124:127], v[132:135], v[200:203], v[124:127]
	v_mfma_f32_16x16x32_bf16 v[52:55], v[136:139], v[200:203], v[52:55]
	v_mfma_f32_16x16x32_bf16 v[60:63], v[140:143], v[200:203], v[60:63]
	ds_read_b128 v[200:203], v246 offset:5120
	s_waitcnt lgkmcnt(3)
	v_mfma_f32_16x16x32_bf16 v[96:99], v[128:131], v[204:207], v[96:99]
	v_mfma_f32_16x16x32_bf16 v[104:107], v[132:135], v[204:207], v[104:107]
	v_mfma_f32_16x16x32_bf16 v[32:35], v[136:139], v[204:207], v[32:35]
	v_mfma_f32_16x16x32_bf16 v[40:43], v[140:143], v[204:207], v[40:43]
	ds_read_b128 v[204:207], v246 offset:6144
	s_waitcnt lgkmcnt(3)
	v_mfma_f32_16x16x32_bf16 v[100:103], v[128:131], v[242:245], v[100:103]
	v_mfma_f32_16x16x32_bf16 v[108:111], v[132:135], v[242:245], v[108:111]
	v_mfma_f32_16x16x32_bf16 v[36:39], v[136:139], v[242:245], v[36:39]
	v_mfma_f32_16x16x32_bf16 v[44:47], v[140:143], v[242:245], v[44:47]
	ds_read_b128 v[242:245], v246 offset:7168
	s_waitcnt lgkmcnt(3)
	v_mfma_f32_16x16x32_bf16 v[80:83], v[128:131], v[196:199], v[80:83]
	v_mfma_f32_16x16x32_bf16 v[88:91], v[132:135], v[196:199], v[88:91]
	v_mfma_f32_16x16x32_bf16 v[16:19], v[136:139], v[196:199], v[16:19]
	v_mfma_f32_16x16x32_bf16 v[24:27], v[140:143], v[196:199], v[24:27]
	s_waitcnt lgkmcnt(2)
	v_mfma_f32_16x16x32_bf16 v[84:87], v[128:131], v[200:203], v[84:87]
	v_mfma_f32_16x16x32_bf16 v[92:95], v[132:135], v[200:203], v[92:95]
	v_mfma_f32_16x16x32_bf16 v[20:23], v[136:139], v[200:203], v[20:23]
	v_mfma_f32_16x16x32_bf16 v[28:31], v[140:143], v[200:203], v[28:31]
	s_waitcnt lgkmcnt(1)
	v_mfma_f32_16x16x32_bf16 v[64:67], v[128:131], v[204:207], v[64:67]
	v_mfma_f32_16x16x32_bf16 v[72:75], v[132:135], v[204:207], v[72:75]
	v_mfma_f32_16x16x32_bf16 v[0:3], v[136:139], v[204:207], v[0:3]
	v_mfma_f32_16x16x32_bf16 v[8:11], v[140:143], v[204:207], v[8:11]
	s_waitcnt lgkmcnt(0)
	v_mfma_f32_16x16x32_bf16 v[68:71], v[128:131], v[242:245], v[68:71]
	v_mfma_f32_16x16x32_bf16 v[76:79], v[132:135], v[242:245], v[76:79]
	v_mfma_f32_16x16x32_bf16 v[4:7], v[136:139], v[242:245], v[4:7]
	v_mfma_f32_16x16x32_bf16 v[12:15], v[140:143], v[242:245], v[12:15]
	global_load_dwordx4 v[128:131], v[248:249], off
	global_load_dwordx4 v[132:135], v[248:249], off offset:256
	global_load_dwordx4 v[136:139], v[250:251], off
	global_load_dwordx4 v[140:143], v[250:251], off offset:256
	ds_read_b128 v[196:199], v246 offset:8192
	ds_read_b128 v[200:203], v246 offset:9216
	ds_read_b128 v[204:207], v246 offset:10240
	ds_read_b128 v[242:245], v246 offset:11264
	s_add_i32 s9, s8, 3
	s_lshl_b32 s96, s9, 11
	v_lshl_add_u64 v[248:249], v[184:185], 0, s[96:97]
	v_lshl_add_u64 v[250:251], v[186:187], 0, s[96:97]
	s_waitcnt vmcnt(8) lgkmcnt(3)
	v_mfma_f32_16x16x32_bf16 v[112:115], v[144:147], v[196:199], v[112:115]
	v_mfma_f32_16x16x32_bf16 v[120:123], v[148:151], v[196:199], v[120:123]
	v_mfma_f32_16x16x32_bf16 v[48:51], v[152:155], v[196:199], v[48:51]
	v_mfma_f32_16x16x32_bf16 v[56:59], v[156:159], v[196:199], v[56:59]
	ds_read_b128 v[196:199], v246 offset:12288
	s_waitcnt lgkmcnt(3)
	v_mfma_f32_16x16x32_bf16 v[116:119], v[144:147], v[200:203], v[116:119]
	v_mfma_f32_16x16x32_bf16 v[124:127], v[148:151], v[200:203], v[124:127]
	v_mfma_f32_16x16x32_bf16 v[52:55], v[152:155], v[200:203], v[52:55]
	v_mfma_f32_16x16x32_bf16 v[60:63], v[156:159], v[200:203], v[60:63]
	ds_read_b128 v[200:203], v246 offset:13312
	s_waitcnt lgkmcnt(3)
	v_mfma_f32_16x16x32_bf16 v[96:99], v[144:147], v[204:207], v[96:99]
	v_mfma_f32_16x16x32_bf16 v[104:107], v[148:151], v[204:207], v[104:107]
	v_mfma_f32_16x16x32_bf16 v[32:35], v[152:155], v[204:207], v[32:35]
	v_mfma_f32_16x16x32_bf16 v[40:43], v[156:159], v[204:207], v[40:43]
	ds_read_b128 v[204:207], v246 offset:14336
	s_waitcnt lgkmcnt(3)
	v_mfma_f32_16x16x32_bf16 v[100:103], v[144:147], v[242:245], v[100:103]
	v_mfma_f32_16x16x32_bf16 v[108:111], v[148:151], v[242:245], v[108:111]
	v_mfma_f32_16x16x32_bf16 v[36:39], v[152:155], v[242:245], v[36:39]
	v_mfma_f32_16x16x32_bf16 v[44:47], v[156:159], v[242:245], v[44:47]
	ds_read_b128 v[242:245], v246 offset:15360
	s_waitcnt lgkmcnt(3)
	v_mfma_f32_16x16x32_bf16 v[80:83], v[144:147], v[196:199], v[80:83]
	v_mfma_f32_16x16x32_bf16 v[88:91], v[148:151], v[196:199], v[88:91]
	v_mfma_f32_16x16x32_bf16 v[16:19], v[152:155], v[196:199], v[16:19]
	v_mfma_f32_16x16x32_bf16 v[24:27], v[156:159], v[196:199], v[24:27]
	s_waitcnt lgkmcnt(2)
	v_mfma_f32_16x16x32_bf16 v[84:87], v[144:147], v[200:203], v[84:87]
	v_mfma_f32_16x16x32_bf16 v[92:95], v[148:151], v[200:203], v[92:95]
	v_mfma_f32_16x16x32_bf16 v[20:23], v[152:155], v[200:203], v[20:23]
	v_mfma_f32_16x16x32_bf16 v[28:31], v[156:159], v[200:203], v[28:31]
	s_waitcnt lgkmcnt(1)
	v_mfma_f32_16x16x32_bf16 v[64:67], v[144:147], v[204:207], v[64:67]
	v_mfma_f32_16x16x32_bf16 v[72:75], v[148:151], v[204:207], v[72:75]
	v_mfma_f32_16x16x32_bf16 v[0:3], v[152:155], v[204:207], v[0:3]
	v_mfma_f32_16x16x32_bf16 v[8:11], v[156:159], v[204:207], v[8:11]
	s_waitcnt lgkmcnt(0)
	v_mfma_f32_16x16x32_bf16 v[68:71], v[144:147], v[242:245], v[68:71]
	v_mfma_f32_16x16x32_bf16 v[76:79], v[148:151], v[242:245], v[76:79]
	v_mfma_f32_16x16x32_bf16 v[4:7], v[152:155], v[242:245], v[4:7]
	v_mfma_f32_16x16x32_bf16 v[12:15], v[156:159], v[242:245], v[12:15]
	global_load_dwordx4 v[144:147], v[248:249], off
	global_load_dwordx4 v[148:151], v[248:249], off offset:256
	global_load_dwordx4 v[152:155], v[250:251], off
	global_load_dwordx4 v[156:159], v[250:251], off offset:256
	s_waitcnt vmcnt(8)
	s_barrier
	s_add_i32 s9, s8, 4
	s_lshl_b32 s96, s9, 13
	s_mov_b32 m0, vcc_lo
	v_lshl_add_u64 v[160:161], v[188:189], 0, s[96:97]
	global_load_lds_dwordx4 v[160:161], off
	global_load_lds_dwordx4 v[160:161], off offset:1024
	s_add_i32 s9, s8, 5
	s_lshl_b32 s96, s9, 13
	s_add_i32 m0, vcc_lo, 8192
	v_lshl_add_u64 v[160:161], v[188:189], 0, s[96:97]
	global_load_lds_dwordx4 v[160:161], off
	global_load_lds_dwordx4 v[160:161], off offset:1024
	ds_read_b128 v[196:199], v246 offset:16384
	ds_read_b128 v[200:203], v246 offset:17408
	ds_read_b128 v[204:207], v246 offset:18432
	ds_read_b128 v[242:245], v246 offset:19456
	s_add_i32 s9, s8, 4
	s_lshl_b32 s96, s9, 11
	v_lshl_add_u64 v[248:249], v[184:185], 0, s[96:97]
	v_lshl_add_u64 v[250:251], v[186:187], 0, s[96:97]
	s_waitcnt vmcnt(8) lgkmcnt(3)
	v_mfma_f32_16x16x32_bf16 v[112:115], v[128:131], v[196:199], v[112:115]
	v_mfma_f32_16x16x32_bf16 v[120:123], v[132:135], v[196:199], v[120:123]
	v_mfma_f32_16x16x32_bf16 v[48:51], v[136:139], v[196:199], v[48:51]
	v_mfma_f32_16x16x32_bf16 v[56:59], v[140:143], v[196:199], v[56:59]
	ds_read_b128 v[196:199], v246 offset:20480
	s_waitcnt lgkmcnt(3)
	v_mfma_f32_16x16x32_bf16 v[116:119], v[128:131], v[200:203], v[116:119]
	v_mfma_f32_16x16x32_bf16 v[124:127], v[132:135], v[200:203], v[124:127]
	v_mfma_f32_16x16x32_bf16 v[52:55], v[136:139], v[200:203], v[52:55]
	v_mfma_f32_16x16x32_bf16 v[60:63], v[140:143], v[200:203], v[60:63]
	ds_read_b128 v[200:203], v246 offset:21504
	s_waitcnt lgkmcnt(3)
	v_mfma_f32_16x16x32_bf16 v[96:99], v[128:131], v[204:207], v[96:99]
	v_mfma_f32_16x16x32_bf16 v[104:107], v[132:135], v[204:207], v[104:107]
	v_mfma_f32_16x16x32_bf16 v[32:35], v[136:139], v[204:207], v[32:35]
	v_mfma_f32_16x16x32_bf16 v[40:43], v[140:143], v[204:207], v[40:43]
	ds_read_b128 v[204:207], v246 offset:22528
	s_waitcnt lgkmcnt(3)
	v_mfma_f32_16x16x32_bf16 v[100:103], v[128:131], v[242:245], v[100:103]
	v_mfma_f32_16x16x32_bf16 v[108:111], v[132:135], v[242:245], v[108:111]
	v_mfma_f32_16x16x32_bf16 v[36:39], v[136:139], v[242:245], v[36:39]
	v_mfma_f32_16x16x32_bf16 v[44:47], v[140:143], v[242:245], v[44:47]
	ds_read_b128 v[242:245], v246 offset:23552
	s_waitcnt lgkmcnt(3)
	v_mfma_f32_16x16x32_bf16 v[80:83], v[128:131], v[196:199], v[80:83]
	v_mfma_f32_16x16x32_bf16 v[88:91], v[132:135], v[196:199], v[88:91]
	v_mfma_f32_16x16x32_bf16 v[16:19], v[136:139], v[196:199], v[16:19]
	v_mfma_f32_16x16x32_bf16 v[24:27], v[140:143], v[196:199], v[24:27]
	s_waitcnt lgkmcnt(2)
	v_mfma_f32_16x16x32_bf16 v[84:87], v[128:131], v[200:203], v[84:87]
	v_mfma_f32_16x16x32_bf16 v[92:95], v[132:135], v[200:203], v[92:95]
	v_mfma_f32_16x16x32_bf16 v[20:23], v[136:139], v[200:203], v[20:23]
	v_mfma_f32_16x16x32_bf16 v[28:31], v[140:143], v[200:203], v[28:31]
	s_waitcnt lgkmcnt(1)
	v_mfma_f32_16x16x32_bf16 v[64:67], v[128:131], v[204:207], v[64:67]
	v_mfma_f32_16x16x32_bf16 v[72:75], v[132:135], v[204:207], v[72:75]
	v_mfma_f32_16x16x32_bf16 v[0:3], v[136:139], v[204:207], v[0:3]
	v_mfma_f32_16x16x32_bf16 v[8:11], v[140:143], v[204:207], v[8:11]
	s_waitcnt lgkmcnt(0)
	v_mfma_f32_16x16x32_bf16 v[68:71], v[128:131], v[242:245], v[68:71]
	v_mfma_f32_16x16x32_bf16 v[76:79], v[132:135], v[242:245], v[76:79]
	v_mfma_f32_16x16x32_bf16 v[4:7], v[136:139], v[242:245], v[4:7]
	v_mfma_f32_16x16x32_bf16 v[12:15], v[140:143], v[242:245], v[12:15]
	global_load_dwordx4 v[128:131], v[248:249], off
	global_load_dwordx4 v[132:135], v[248:249], off offset:256
	global_load_dwordx4 v[136:139], v[250:251], off
	global_load_dwordx4 v[140:143], v[250:251], off offset:256
	ds_read_b128 v[196:199], v246 offset:24576
	ds_read_b128 v[200:203], v246 offset:25600
	ds_read_b128 v[204:207], v246 offset:26624
	ds_read_b128 v[242:245], v246 offset:27648
	s_add_i32 s9, s8, 5
	s_lshl_b32 s96, s9, 11
	v_lshl_add_u64 v[248:249], v[184:185], 0, s[96:97]
	v_lshl_add_u64 v[250:251], v[186:187], 0, s[96:97]
	s_waitcnt vmcnt(8) lgkmcnt(3)
	v_mfma_f32_16x16x32_bf16 v[112:115], v[144:147], v[196:199], v[112:115]
	v_mfma_f32_16x16x32_bf16 v[120:123], v[148:151], v[196:199], v[120:123]
	v_mfma_f32_16x16x32_bf16 v[48:51], v[152:155], v[196:199], v[48:51]
	v_mfma_f32_16x16x32_bf16 v[56:59], v[156:159], v[196:199], v[56:59]
	ds_read_b128 v[196:199], v246 offset:28672
	s_waitcnt lgkmcnt(3)
	v_mfma_f32_16x16x32_bf16 v[116:119], v[144:147], v[200:203], v[116:119]
	v_mfma_f32_16x16x32_bf16 v[124:127], v[148:151], v[200:203], v[124:127]
	v_mfma_f32_16x16x32_bf16 v[52:55], v[152:155], v[200:203], v[52:55]
	v_mfma_f32_16x16x32_bf16 v[60:63], v[156:159], v[200:203], v[60:63]
	ds_read_b128 v[200:203], v246 offset:29696
	s_waitcnt lgkmcnt(3)
	v_mfma_f32_16x16x32_bf16 v[96:99], v[144:147], v[204:207], v[96:99]
	v_mfma_f32_16x16x32_bf16 v[104:107], v[148:151], v[204:207], v[104:107]
	v_mfma_f32_16x16x32_bf16 v[32:35], v[152:155], v[204:207], v[32:35]
	v_mfma_f32_16x16x32_bf16 v[40:43], v[156:159], v[204:207], v[40:43]
	ds_read_b128 v[204:207], v246 offset:30720
	s_waitcnt lgkmcnt(3)
	v_mfma_f32_16x16x32_bf16 v[100:103], v[144:147], v[242:245], v[100:103]
	v_mfma_f32_16x16x32_bf16 v[108:111], v[148:151], v[242:245], v[108:111]
	v_mfma_f32_16x16x32_bf16 v[36:39], v[152:155], v[242:245], v[36:39]
	v_mfma_f32_16x16x32_bf16 v[44:47], v[156:159], v[242:245], v[44:47]
	ds_read_b128 v[242:245], v246 offset:31744
	s_waitcnt lgkmcnt(3)
	v_mfma_f32_16x16x32_bf16 v[80:83], v[144:147], v[196:199], v[80:83]
	v_mfma_f32_16x16x32_bf16 v[88:91], v[148:151], v[196:199], v[88:91]
	v_mfma_f32_16x16x32_bf16 v[16:19], v[152:155], v[196:199], v[16:19]
	v_mfma_f32_16x16x32_bf16 v[24:27], v[156:159], v[196:199], v[24:27]
	s_waitcnt lgkmcnt(2)
	v_mfma_f32_16x16x32_bf16 v[84:87], v[144:147], v[200:203], v[84:87]
	v_mfma_f32_16x16x32_bf16 v[92:95], v[148:151], v[200:203], v[92:95]
	v_mfma_f32_16x16x32_bf16 v[20:23], v[152:155], v[200:203], v[20:23]
	v_mfma_f32_16x16x32_bf16 v[28:31], v[156:159], v[200:203], v[28:31]
	s_waitcnt lgkmcnt(1)
	v_mfma_f32_16x16x32_bf16 v[64:67], v[144:147], v[204:207], v[64:67]
	v_mfma_f32_16x16x32_bf16 v[72:75], v[148:151], v[204:207], v[72:75]
	v_mfma_f32_16x16x32_bf16 v[0:3], v[152:155], v[204:207], v[0:3]
	v_mfma_f32_16x16x32_bf16 v[8:11], v[156:159], v[204:207], v[8:11]
	s_waitcnt lgkmcnt(0)
	v_mfma_f32_16x16x32_bf16 v[68:71], v[144:147], v[242:245], v[68:71]
	v_mfma_f32_16x16x32_bf16 v[76:79], v[148:151], v[242:245], v[76:79]
	v_mfma_f32_16x16x32_bf16 v[4:7], v[152:155], v[242:245], v[4:7]
	v_mfma_f32_16x16x32_bf16 v[12:15], v[156:159], v[242:245], v[12:15]
	global_load_dwordx4 v[144:147], v[248:249], off
	global_load_dwordx4 v[148:151], v[248:249], off offset:256
	global_load_dwordx4 v[152:155], v[250:251], off
	global_load_dwordx4 v[156:159], v[250:251], off offset:256
	s_waitcnt vmcnt(8)
	s_barrier
	s_add_i32 s8, s8, 4
	s_cmp_lt_u32 s8, 84
	s_cbranch_scc1 .Lg16_down_k
	s_mov_b32 s96, 0xac000
	s_add_i32 m0, vcc_lo, 16384
	v_lshl_add_u64 v[160:161], v[188:189], 0, s[96:97]
	global_load_lds_dwordx4 v[160:161], off
	global_load_lds_dwordx4 v[160:161], off offset:1024
	s_mov_b32 s96, 0xae000
	s_add_i32 m0, vcc_lo, 24576
	v_lshl_add_u64 v[160:161], v[188:189], 0, s[96:97]
	global_load_lds_dwordx4 v[160:161], off
	global_load_lds_dwordx4 v[160:161], off offset:1024
	ds_read_b128 v[196:199], v246 offset:0
	ds_read_b128 v[200:203], v246 offset:1024
	ds_read_b128 v[204:207], v246 offset:2048
	ds_read_b128 v[242:245], v246 offset:3072
	s_mov_b32 s96, 0x2b000
	v_lshl_add_u64 v[248:249], v[184:185], 0, s[96:97]
	v_lshl_add_u64 v[250:251], v[186:187], 0, s[96:97]
	s_waitcnt vmcnt(8) lgkmcnt(3)
	v_mfma_f32_16x16x32_bf16 v[112:115], v[128:131], v[196:199], v[112:115]
	v_mfma_f32_16x16x32_bf16 v[120:123], v[132:135], v[196:199], v[120:123]
	v_mfma_f32_16x16x32_bf16 v[48:51], v[136:139], v[196:199], v[48:51]
	v_mfma_f32_16x16x32_bf16 v[56:59], v[140:143], v[196:199], v[56:59]
	ds_read_b128 v[196:199], v246 offset:4096
	s_waitcnt lgkmcnt(3)
	v_mfma_f32_16x16x32_bf16 v[116:119], v[128:131], v[200:203], v[116:119]
	v_mfma_f32_16x16x32_bf16 v[124:127], v[132:135], v[200:203], v[124:127]
	v_mfma_f32_16x16x32_bf16 v[52:55], v[136:139], v[200:203], v[52:55]
	v_mfma_f32_16x16x32_bf16 v[60:63], v[140:143], v[200:203], v[60:63]
	ds_read_b128 v[200:203], v246 offset:5120
	s_waitcnt lgkmcnt(3)
	v_mfma_f32_16x16x32_bf16 v[96:99], v[128:131], v[204:207], v[96:99]
	v_mfma_f32_16x16x32_bf16 v[104:107], v[132:135], v[204:207], v[104:107]
	v_mfma_f32_16x16x32_bf16 v[32:35], v[136:139], v[204:207], v[32:35]
	v_mfma_f32_16x16x32_bf16 v[40:43], v[140:143], v[204:207], v[40:43]
	ds_read_b128 v[204:207], v246 offset:6144
	s_waitcnt lgkmcnt(3)
	v_mfma_f32_16x16x32_bf16 v[100:103], v[128:131], v[242:245], v[100:103]
	v_mfma_f32_16x16x32_bf16 v[108:111], v[132:135], v[242:245], v[108:111]
	v_mfma_f32_16x16x32_bf16 v[36:39], v[136:139], v[242:245], v[36:39]
	v_mfma_f32_16x16x32_bf16 v[44:47], v[140:143], v[242:245], v[44:47]
	ds_read_b128 v[242:245], v246 offset:7168
	s_waitcnt lgkmcnt(3)
	v_mfma_f32_16x16x32_bf16 v[80:83], v[128:131], v[196:199], v[80:83]
	v_mfma_f32_16x16x32_bf16 v[88:91], v[132:135], v[196:199], v[88:91]
	v_mfma_f32_16x16x32_bf16 v[16:19], v[136:139], v[196:199], v[16:19]
	v_mfma_f32_16x16x32_bf16 v[24:27], v[140:143], v[196:199], v[24:27]
	s_waitcnt lgkmcnt(2)
	v_mfma_f32_16x16x32_bf16 v[84:87], v[128:131], v[200:203], v[84:87]
	v_mfma_f32_16x16x32_bf16 v[92:95], v[132:135], v[200:203], v[92:95]
	v_mfma_f32_16x16x32_bf16 v[20:23], v[136:139], v[200:203], v[20:23]
	v_mfma_f32_16x16x32_bf16 v[28:31], v[140:143], v[200:203], v[28:31]
	s_waitcnt lgkmcnt(1)
	v_mfma_f32_16x16x32_bf16 v[64:67], v[128:131], v[204:207], v[64:67]
	v_mfma_f32_16x16x32_bf16 v[72:75], v[132:135], v[204:207], v[72:75]
	v_mfma_f32_16x16x32_bf16 v[0:3], v[136:139], v[204:207], v[0:3]
	v_mfma_f32_16x16x32_bf16 v[8:11], v[140:143], v[204:207], v[8:11]
	s_waitcnt lgkmcnt(0)
	v_mfma_f32_16x16x32_bf16 v[68:71], v[128:131], v[242:245], v[68:71]
	v_mfma_f32_16x16x32_bf16 v[76:79], v[132:135], v[242:245], v[76:79]
	v_mfma_f32_16x16x32_bf16 v[4:7], v[136:139], v[242:245], v[4:7]
	v_mfma_f32_16x16x32_bf16 v[12:15], v[140:143], v[242:245], v[12:15]
	global_load_dwordx4 v[128:131], v[248:249], off
	global_load_dwordx4 v[132:135], v[248:249], off offset:256
	global_load_dwordx4 v[136:139], v[250:251], off
	global_load_dwordx4 v[140:143], v[250:251], off offset:256
	ds_read_b128 v[196:199], v246 offset:8192
	ds_read_b128 v[200:203], v246 offset:9216
	ds_read_b128 v[204:207], v246 offset:10240
	ds_read_b128 v[242:245], v246 offset:11264
	s_mov_b32 s96, 0x2b800
	v_lshl_add_u64 v[248:249], v[184:185], 0, s[96:97]
	v_lshl_add_u64 v[250:251], v[186:187], 0, s[96:97]
	s_waitcnt vmcnt(8) lgkmcnt(3)
	v_mfma_f32_16x16x32_bf16 v[112:115], v[144:147], v[196:199], v[112:115]
	v_mfma_f32_16x16x32_bf16 v[120:123], v[148:151], v[196:199], v[120:123]
	v_mfma_f32_16x16x32_bf16 v[48:51], v[152:155], v[196:199], v[48:51]
	v_mfma_f32_16x16x32_bf16 v[56:59], v[156:159], v[196:199], v[56:59]
	ds_read_b128 v[196:199], v246 offset:12288
	s_waitcnt lgkmcnt(3)
	v_mfma_f32_16x16x32_bf16 v[116:119], v[144:147], v[200:203], v[116:119]
	v_mfma_f32_16x16x32_bf16 v[124:127], v[148:151], v[200:203], v[124:127]
	v_mfma_f32_16x16x32_bf16 v[52:55], v[152:155], v[200:203], v[52:55]
	v_mfma_f32_16x16x32_bf16 v[60:63], v[156:159], v[200:203], v[60:63]
	ds_read_b128 v[200:203], v246 offset:13312
	s_waitcnt lgkmcnt(3)
	v_mfma_f32_16x16x32_bf16 v[96:99], v[144:147], v[204:207], v[96:99]
	v_mfma_f32_16x16x32_bf16 v[104:107], v[148:151], v[204:207], v[104:107]
	v_mfma_f32_16x16x32_bf16 v[32:35], v[152:155], v[204:207], v[32:35]
	v_mfma_f32_16x16x32_bf16 v[40:43], v[156:159], v[204:207], v[40:43]
	ds_read_b128 v[204:207], v246 offset:14336
	s_waitcnt lgkmcnt(3)
	v_mfma_f32_16x16x32_bf16 v[100:103], v[144:147], v[242:245], v[100:103]
	v_mfma_f32_16x16x32_bf16 v[108:111], v[148:151], v[242:245], v[108:111]
	v_mfma_f32_16x16x32_bf16 v[36:39], v[152:155], v[242:245], v[36:39]
	v_mfma_f32_16x16x32_bf16 v[44:47], v[156:159], v[242:245], v[44:47]
	ds_read_b128 v[242:245], v246 offset:15360
	s_waitcnt lgkmcnt(3)
	v_mfma_f32_16x16x32_bf16 v[80:83], v[144:147], v[196:199], v[80:83]
	v_mfma_f32_16x16x32_bf16 v[88:91], v[148:151], v[196:199], v[88:91]
	v_mfma_f32_16x16x32_bf16 v[16:19], v[152:155], v[196:199], v[16:19]
	v_mfma_f32_16x16x32_bf16 v[24:27], v[156:159], v[196:199], v[24:27]
	s_waitcnt lgkmcnt(2)
	v_mfma_f32_16x16x32_bf16 v[84:87], v[144:147], v[200:203], v[84:87]
	v_mfma_f32_16x16x32_bf16 v[92:95], v[148:151], v[200:203], v[92:95]
	v_mfma_f32_16x16x32_bf16 v[20:23], v[152:155], v[200:203], v[20:23]
	v_mfma_f32_16x16x32_bf16 v[28:31], v[156:159], v[200:203], v[28:31]
	s_waitcnt lgkmcnt(1)
	v_mfma_f32_16x16x32_bf16 v[64:67], v[144:147], v[204:207], v[64:67]
	v_mfma_f32_16x16x32_bf16 v[72:75], v[148:151], v[204:207], v[72:75]
	v_mfma_f32_16x16x32_bf16 v[0:3], v[152:155], v[204:207], v[0:3]
	v_mfma_f32_16x16x32_bf16 v[8:11], v[156:159], v[204:207], v[8:11]
	s_waitcnt lgkmcnt(0)
	v_mfma_f32_16x16x32_bf16 v[68:71], v[144:147], v[242:245], v[68:71]
	v_mfma_f32_16x16x32_bf16 v[76:79], v[148:151], v[242:245], v[76:79]
	v_mfma_f32_16x16x32_bf16 v[4:7], v[152:155], v[242:245], v[4:7]
	v_mfma_f32_16x16x32_bf16 v[12:15], v[156:159], v[242:245], v[12:15]
	global_load_dwordx4 v[144:147], v[248:249], off
	global_load_dwordx4 v[148:151], v[248:249], off offset:256
	global_load_dwordx4 v[152:155], v[250:251], off
	global_load_dwordx4 v[156:159], v[250:251], off offset:256
	s_waitcnt vmcnt(8)
	s_barrier
	ds_read_b128 v[196:199], v246 offset:16384
	ds_read_b128 v[200:203], v246 offset:17408
	ds_read_b128 v[204:207], v246 offset:18432
	ds_read_b128 v[242:245], v246 offset:19456
	s_waitcnt vmcnt(4) lgkmcnt(3)
	v_mfma_f32_16x16x32_bf16 v[112:115], v[128:131], v[196:199], v[112:115]
	v_mfma_f32_16x16x32_bf16 v[120:123], v[132:135], v[196:199], v[120:123]
	v_mfma_f32_16x16x32_bf16 v[48:51], v[136:139], v[196:199], v[48:51]
	v_mfma_f32_16x16x32_bf16 v[56:59], v[140:143], v[196:199], v[56:59]
	ds_read_b128 v[196:199], v246 offset:20480
	s_waitcnt lgkmcnt(3)
	v_mfma_f32_16x16x32_bf16 v[116:119], v[128:131], v[200:203], v[116:119]
	v_mfma_f32_16x16x32_bf16 v[124:127], v[132:135], v[200:203], v[124:127]
	v_mfma_f32_16x16x32_bf16 v[52:55], v[136:139], v[200:203], v[52:55]
	v_mfma_f32_16x16x32_bf16 v[60:63], v[140:143], v[200:203], v[60:63]
	ds_read_b128 v[200:203], v246 offset:21504
	s_waitcnt lgkmcnt(3)
	v_mfma_f32_16x16x32_bf16 v[96:99], v[128:131], v[204:207], v[96:99]
	v_mfma_f32_16x16x32_bf16 v[104:107], v[132:135], v[204:207], v[104:107]
	v_mfma_f32_16x16x32_bf16 v[32:35], v[136:139], v[204:207], v[32:35]
	v_mfma_f32_16x16x32_bf16 v[40:43], v[140:143], v[204:207], v[40:43]
	ds_read_b128 v[204:207], v246 offset:22528
	s_waitcnt lgkmcnt(3)
	v_mfma_f32_16x16x32_bf16 v[100:103], v[128:131], v[242:245], v[100:103]
	v_mfma_f32_16x16x32_bf16 v[108:111], v[132:135], v[242:245], v[108:111]
	v_mfma_f32_16x16x32_bf16 v[36:39], v[136:139], v[242:245], v[36:39]
	v_mfma_f32_16x16x32_bf16 v[44:47], v[140:143], v[242:245], v[44:47]
	ds_read_b128 v[242:245], v246 offset:23552
	s_waitcnt lgkmcnt(3)
	v_mfma_f32_16x16x32_bf16 v[80:83], v[128:131], v[196:199], v[80:83]
	v_mfma_f32_16x16x32_bf16 v[88:91], v[132:135], v[196:199], v[88:91]
	v_mfma_f32_16x16x32_bf16 v[16:19], v[136:139], v[196:199], v[16:19]
	v_mfma_f32_16x16x32_bf16 v[24:27], v[140:143], v[196:199], v[24:27]
	s_waitcnt lgkmcnt(2)
	v_mfma_f32_16x16x32_bf16 v[84:87], v[128:131], v[200:203], v[84:87]
	v_mfma_f32_16x16x32_bf16 v[92:95], v[132:135], v[200:203], v[92:95]
	v_mfma_f32_16x16x32_bf16 v[20:23], v[136:139], v[200:203], v[20:23]
	v_mfma_f32_16x16x32_bf16 v[28:31], v[140:143], v[200:203], v[28:31]
	s_waitcnt lgkmcnt(1)
	v_mfma_f32_16x16x32_bf16 v[64:67], v[128:131], v[204:207], v[64:67]
	v_mfma_f32_16x16x32_bf16 v[72:75], v[132:135], v[204:207], v[72:75]
	v_mfma_f32_16x16x32_bf16 v[0:3], v[136:139], v[204:207], v[0:3]
	v_mfma_f32_16x16x32_bf16 v[8:11], v[140:143], v[204:207], v[8:11]
	s_waitcnt lgkmcnt(0)
	v_mfma_f32_16x16x32_bf16 v[68:71], v[128:131], v[242:245], v[68:71]
	v_mfma_f32_16x16x32_bf16 v[76:79], v[132:135], v[242:245], v[76:79]
	v_mfma_f32_16x16x32_bf16 v[4:7], v[136:139], v[242:245], v[4:7]
	v_mfma_f32_16x16x32_bf16 v[12:15], v[140:143], v[242:245], v[12:15]
	ds_read_b128 v[196:199], v246 offset:24576
	ds_read_b128 v[200:203], v246 offset:25600
	ds_read_b128 v[204:207], v246 offset:26624
	ds_read_b128 v[242:245], v246 offset:27648
	s_waitcnt vmcnt(0) lgkmcnt(3)
	v_mfma_f32_16x16x32_bf16 v[112:115], v[144:147], v[196:199], v[112:115]
	v_mfma_f32_16x16x32_bf16 v[120:123], v[148:151], v[196:199], v[120:123]
	v_mfma_f32_16x16x32_bf16 v[48:51], v[152:155], v[196:199], v[48:51]
	v_mfma_f32_16x16x32_bf16 v[56:59], v[156:159], v[196:199], v[56:59]
	ds_read_b128 v[196:199], v246 offset:28672
	s_waitcnt lgkmcnt(3)
	v_mfma_f32_16x16x32_bf16 v[116:119], v[144:147], v[200:203], v[116:119]
	v_mfma_f32_16x16x32_bf16 v[124:127], v[148:151], v[200:203], v[124:127]
	v_mfma_f32_16x16x32_bf16 v[52:55], v[152:155], v[200:203], v[52:55]
	v_mfma_f32_16x16x32_bf16 v[60:63], v[156:159], v[200:203], v[60:63]
	ds_read_b128 v[200:203], v246 offset:29696
	s_waitcnt lgkmcnt(3)
	v_mfma_f32_16x16x32_bf16 v[96:99], v[144:147], v[204:207], v[96:99]
	v_mfma_f32_16x16x32_bf16 v[104:107], v[148:151], v[204:207], v[104:107]
	v_mfma_f32_16x16x32_bf16 v[32:35], v[152:155], v[204:207], v[32:35]
	v_mfma_f32_16x16x32_bf16 v[40:43], v[156:159], v[204:207], v[40:43]
	ds_read_b128 v[204:207], v246 offset:30720
	s_waitcnt lgkmcnt(3)
	v_mfma_f32_16x16x32_bf16 v[100:103], v[144:147], v[242:245], v[100:103]
	v_mfma_f32_16x16x32_bf16 v[108:111], v[148:151], v[242:245], v[108:111]
	v_mfma_f32_16x16x32_bf16 v[36:39], v[152:155], v[242:245], v[36:39]
	v_mfma_f32_16x16x32_bf16 v[44:47], v[156:159], v[242:245], v[44:47]
	ds_read_b128 v[242:245], v246 offset:31744
	v_permlane16_swap_b32_e32 v112, v116
	v_permlane16_swap_b32_e32 v113, v117
	v_permlane16_swap_b32_e32 v114, v118
	v_permlane16_swap_b32_e32 v115, v119
	v_permlane16_swap_b32_e32 v120, v124
	v_permlane16_swap_b32_e32 v121, v125
	v_permlane16_swap_b32_e32 v122, v126
	v_permlane16_swap_b32_e32 v123, v127
	v_permlane16_swap_b32_e32 v48, v52
	v_permlane16_swap_b32_e32 v49, v53
	v_permlane16_swap_b32_e32 v50, v54
	v_permlane16_swap_b32_e32 v51, v55
	v_permlane16_swap_b32_e32 v56, v60
	v_permlane16_swap_b32_e32 v57, v61
	v_permlane16_swap_b32_e32 v58, v62
	v_permlane16_swap_b32_e32 v59, v63
	v_permlane32_swap_b32_e32 v112, v116
	v_permlane32_swap_b32_e32 v113, v117
	v_permlane32_swap_b32_e32 v114, v118
	v_permlane32_swap_b32_e32 v115, v119
	v_permlane32_swap_b32_e32 v120, v124
	v_permlane32_swap_b32_e32 v121, v125
	v_permlane32_swap_b32_e32 v122, v126
	v_permlane32_swap_b32_e32 v123, v127
	v_permlane32_swap_b32_e32 v48, v52
	v_permlane32_swap_b32_e32 v49, v53
	v_permlane32_swap_b32_e32 v50, v54
	v_permlane32_swap_b32_e32 v51, v55
	v_permlane32_swap_b32_e32 v56, v60
	v_permlane32_swap_b32_e32 v57, v61
	v_permlane32_swap_b32_e32 v58, v62
	v_permlane32_swap_b32_e32 v59, v63
	s_waitcnt lgkmcnt(3)
	v_mfma_f32_16x16x32_bf16 v[80:83], v[144:147], v[196:199], v[80:83]
	v_mfma_f32_16x16x32_bf16 v[88:91], v[148:151], v[196:199], v[88:91]
	v_mfma_f32_16x16x32_bf16 v[16:19], v[152:155], v[196:199], v[16:19]
	v_mfma_f32_16x16x32_bf16 v[24:27], v[156:159], v[196:199], v[24:27]
	s_waitcnt lgkmcnt(2)
	v_mfma_f32_16x16x32_bf16 v[84:87], v[144:147], v[200:203], v[84:87]
	v_mfma_f32_16x16x32_bf16 v[92:95], v[148:151], v[200:203], v[92:95]
	v_mfma_f32_16x16x32_bf16 v[20:23], v[152:155], v[200:203], v[20:23]
	v_mfma_f32_16x16x32_bf16 v[28:31], v[156:159], v[200:203], v[28:31]
	v_permlane16_swap_b32_e32 v96, v100
	v_permlane16_swap_b32_e32 v97, v101
	v_permlane16_swap_b32_e32 v98, v102
	v_permlane16_swap_b32_e32 v99, v103
	v_permlane16_swap_b32_e32 v104, v108
	v_permlane16_swap_b32_e32 v105, v109
	v_permlane16_swap_b32_e32 v106, v110
	v_permlane16_swap_b32_e32 v107, v111
	v_permlane16_swap_b32_e32 v32, v36
	v_permlane16_swap_b32_e32 v33, v37
	v_permlane16_swap_b32_e32 v34, v38
	v_permlane16_swap_b32_e32 v35, v39
	v_permlane16_swap_b32_e32 v40, v44
	v_permlane16_swap_b32_e32 v41, v45
	v_permlane16_swap_b32_e32 v42, v46
	v_permlane16_swap_b32_e32 v43, v47
	v_permlane32_swap_b32_e32 v96, v100
	v_permlane32_swap_b32_e32 v97, v101
	v_permlane32_swap_b32_e32 v98, v102
	v_permlane32_swap_b32_e32 v99, v103
	v_permlane32_swap_b32_e32 v104, v108
	v_permlane32_swap_b32_e32 v105, v109
	v_permlane32_swap_b32_e32 v106, v110
	v_permlane32_swap_b32_e32 v107, v111
	v_permlane32_swap_b32_e32 v32, v36
	v_permlane32_swap_b32_e32 v33, v37
	v_permlane32_swap_b32_e32 v34, v38
	v_permlane32_swap_b32_e32 v35, v39
	v_permlane32_swap_b32_e32 v40, v44
	v_permlane32_swap_b32_e32 v41, v45
	v_permlane32_swap_b32_e32 v42, v46
	v_permlane32_swap_b32_e32 v43, v47
	s_waitcnt lgkmcnt(1)
	v_mfma_f32_16x16x32_bf16 v[64:67], v[144:147], v[204:207], v[64:67]
	v_mfma_f32_16x16x32_bf16 v[72:75], v[148:151], v[204:207], v[72:75]
	v_mfma_f32_16x16x32_bf16 v[0:3], v[152:155], v[204:207], v[0:3]
	v_mfma_f32_16x16x32_bf16 v[8:11], v[156:159], v[204:207], v[8:11]
	s_waitcnt lgkmcnt(0)
	v_mfma_f32_16x16x32_bf16 v[68:71], v[144:147], v[242:245], v[68:71]
	v_mfma_f32_16x16x32_bf16 v[76:79], v[148:151], v[242:245], v[76:79]
	v_mfma_f32_16x16x32_bf16 v[4:7], v[152:155], v[242:245], v[4:7]
	v_mfma_f32_16x16x32_bf16 v[12:15], v[156:159], v[242:245], v[12:15]
	v_permlane16_swap_b32_e32 v80, v84
	v_permlane16_swap_b32_e32 v81, v85
	v_permlane16_swap_b32_e32 v82, v86
	v_permlane16_swap_b32_e32 v83, v87
	v_permlane16_swap_b32_e32 v88, v92
	v_permlane16_swap_b32_e32 v89, v93
	v_permlane16_swap_b32_e32 v90, v94
	v_permlane16_swap_b32_e32 v91, v95
	v_permlane16_swap_b32_e32 v16, v20
	v_permlane16_swap_b32_e32 v17, v21
	v_permlane16_swap_b32_e32 v18, v22
	v_permlane16_swap_b32_e32 v19, v23
	v_permlane16_swap_b32_e32 v24, v28
	v_permlane16_swap_b32_e32 v25, v29
	v_permlane16_swap_b32_e32 v26, v30
	v_permlane16_swap_b32_e32 v27, v31
	v_permlane32_swap_b32_e32 v80, v84
	v_permlane32_swap_b32_e32 v81, v85
	v_permlane32_swap_b32_e32 v82, v86
	v_permlane32_swap_b32_e32 v83, v87
	v_permlane32_swap_b32_e32 v88, v92
	v_permlane32_swap_b32_e32 v89, v93
	v_permlane32_swap_b32_e32 v90, v94
	v_permlane32_swap_b32_e32 v91, v95
	v_permlane32_swap_b32_e32 v16, v20
	v_permlane32_swap_b32_e32 v17, v21
	v_permlane32_swap_b32_e32 v18, v22
	v_permlane32_swap_b32_e32 v19, v23
	v_permlane32_swap_b32_e32 v24, v28
	v_permlane32_swap_b32_e32 v25, v29
	v_permlane32_swap_b32_e32 v26, v30
	v_permlane32_swap_b32_e32 v27, v31
	s_barrier
	s_nop 7
	v_permlane16_swap_b32_e32 v64, v68
	v_permlane16_swap_b32_e32 v65, v69
	v_permlane16_swap_b32_e32 v66, v70
	v_permlane16_swap_b32_e32 v67, v71
	v_permlane16_swap_b32_e32 v72, v76
	v_permlane16_swap_b32_e32 v73, v77
	v_permlane16_swap_b32_e32 v74, v78
	v_permlane16_swap_b32_e32 v75, v79
	v_permlane16_swap_b32_e32 v0, v4
	v_permlane16_swap_b32_e32 v1, v5
	v_permlane16_swap_b32_e32 v2, v6
	v_permlane16_swap_b32_e32 v3, v7
	v_permlane16_swap_b32_e32 v8, v12
	v_permlane16_swap_b32_e32 v9, v13
	v_permlane16_swap_b32_e32 v10, v14
	v_permlane16_swap_b32_e32 v11, v15
	v_permlane32_swap_b32_e32 v64, v68
	v_permlane32_swap_b32_e32 v65, v69
	v_permlane32_swap_b32_e32 v66, v70
	v_permlane32_swap_b32_e32 v67, v71
	v_permlane32_swap_b32_e32 v72, v76
	v_permlane32_swap_b32_e32 v73, v77
	v_permlane32_swap_b32_e32 v74, v78
	v_permlane32_swap_b32_e32 v75, v79
	v_permlane32_swap_b32_e32 v0, v4
	v_permlane32_swap_b32_e32 v1, v5
	v_permlane32_swap_b32_e32 v2, v6
	v_permlane32_swap_b32_e32 v3, v7
	v_permlane32_swap_b32_e32 v8, v12
	v_permlane32_swap_b32_e32 v9, v13
	v_permlane32_swap_b32_e32 v10, v14
	v_permlane32_swap_b32_e32 v11, v15
	s_waitcnt vmcnt(0)
	s_movk_i32 s8, 0x2400
	s_waitcnt vmcnt(0)
	v_and_b32_e32 v132, 0xffffffc0, v181
	v_mul_lo_u32 v129, v237, s8
	v_lshlrev_b32_e32 v130, 2, v238
	v_lshl_add_u32 v156, s7, 8, v132
	v_mul_u32_u24_e32 v132, 0x110, v183
	v_or_b32_e32 v131, v129, v130
	v_lshlrev_b32_e32 v132, 2, v132
	v_add_u32_e32 v131, v131, v132
	v_add3_u32 v132, v129, v132, v130
	v_readlane_b32 s8, v253, 36
	v_lshlrev_b32_e32 v128, 2, v181
	v_add_u32_e32 v133, 0x800, v131
	v_add_u32_e32 v134, 0x800, v132
	v_lshrrev_b32_e32 v155, 4, v239
	v_readlane_b32 s12, v253, 40
	v_readlane_b32 s13, v253, 41
	v_readlane_b32 s14, v253, 42
	v_readlane_b32 s15, v253, 43
	v_readlane_b32 s16, v253, 44
	v_readlane_b32 s17, v253, 45
	v_readlane_b32 s18, v253, 46
	v_readlane_b32 s19, v253, 47
	v_and_b32_e32 v128, 60, v128
	ds_write2_b32 v131, v112, v113 offset1:68
	ds_write2_b32 v132, v96, v97 offset0:32 offset1:100
	ds_write2_b32 v131, v114, v115 offset0:136 offset1:204
	ds_write2_b32 v132, v98, v99 offset0:168 offset1:236
	ds_write2_b32 v133, v116, v117 offset0:32 offset1:100
	ds_write2_b32 v134, v100, v101 offset0:64 offset1:132
	ds_write2_b32 v133, v118, v119 offset0:168 offset1:236
	v_or_b32_e32 v100, v156, v155
	v_readlane_b32 s20, v253, 48
	v_readlane_b32 s21, v253, 49
	v_readlane_b32 s22, v253, 50
	v_readlane_b32 s23, v253, 51
	s_mov_b64 s[12:13], s[16:17]
	v_lshl_or_b32 v144, v128, 2, v129
	v_lshl_or_b32 v128, s6, 7, v128
	s_movk_i32 s6, 0x110
	v_cmp_gt_i32_e32 vcc, s39, v100
	v_add_u32_e32 v96, 0xffff8000, v100
	v_ashrrev_i32_e32 v97, 31, v100
	s_mov_b64 s[14:15], s[18:19]
	v_mad_u32_u24 v130, v155, s6, v144
	v_cndmask_b32_e32 v97, 0, v97, vcc
	v_cndmask_b32_e32 v96, v96, v100, vcc
	v_mov_b32_e32 v144, s63
	v_mov_b32_e32 v145, s15
	v_mov_b32_e32 v146, s62
	v_mov_b32_e32 v147, s14
	v_min_i32_e32 v100, 0x8000, v100
	v_add_u32_e32 v135, 0xa00, v132
	v_add_u32_e32 v136, 0x1000, v131
	v_add_u32_e32 v137, 0x1000, v132
	v_add_u32_e32 v138, 0x1200, v131
	v_add_u32_e32 v139, 0x1200, v132
	v_add_u32_e32 v140, 0x1800, v131
	v_add_u32_e32 v141, 0x1800, v132
	v_add_u32_e32 v142, 0x1a00, v131
	v_add_u32_e32 v143, 0x1c00, v132
	v_ashrrev_i32_e32 v129, 31, v128
	v_cndmask_b32_e32 v99, v144, v145, vcc
	v_cndmask_b32_e32 v98, v146, v147, vcc
	v_lshlrev_b64 v[96:97], 12, v[96:97]
	v_ashrrev_i32_e32 v100, 12, v100
	ds_write2_b32 v135, v102, v103 offset0:72 offset1:140
	ds_write2_b32 v136, v120, v121 offset0:64 offset1:132
	ds_write2_b32 v137, v104, v105 offset0:96 offset1:164
	ds_write2_b32 v138, v122, v123 offset0:72 offset1:140
	ds_write2_b32 v139, v106, v107 offset0:104 offset1:172
	ds_write2_b32 v140, v124, v125 offset0:96 offset1:164
	ds_write2_b32 v141, v108, v109 offset0:128 offset1:196
	ds_write2_b32 v142, v126, v127 offset0:104 offset1:172
	ds_write2_b32 v143, v110, v111 offset0:8 offset1:76
	v_lshl_add_u64 v[98:99], v[98:99], 0, v[96:97]
	v_lshlrev_b64 v[96:97], 2, v[128:129]
	v_mul_hi_i32_i24_e32 v101, 0x6000, v100
	v_mul_i32_i24_e32 v100, 0x6000, v100
	s_waitcnt lgkmcnt(0)
	v_lshl_add_u64 v[98:99], v[98:99], 0, v[96:97]
	v_lshl_add_u64 v[100:101], s[0:1], 0, v[100:101]
	v_lshl_add_u64 v[100:101], v[100:101], 0, v[96:97]
	ds_read_b128 v[102:105], v130
	global_load_dwordx4 v[106:109], v[98:99], off
	global_load_dwordx4 v[110:113], v[100:101], off
	v_or_b32_e32 v148, 4, v155
	v_or_b32_e32 v149, 8, v155
	v_or_b32_e32 v150, 12, v155
	v_or_b32_e32 v151, 16, v155
	v_or_b32_e32 v152, 20, v155
	v_or_b32_e32 v153, 24, v155
	v_or_b32_e32 v154, 28, v155
	v_or_b32_e32 v157, v156, v154
	v_readlane_b32 s6, v254, 11
	s_add_i32 s2, s2, s6
	s_cmp_lt_i32 s2, s26
	v_readlane_b32 s9, v253, 37
	v_readlane_b32 s10, v253, 38
	v_readlane_b32 s11, v253, 39
	s_mov_b64 s[16:17], s[20:21]
	s_mov_b64 s[18:19], s[22:23]
	s_waitcnt vmcnt(0) lgkmcnt(0)
	v_pk_fma_f32 v[102:103], v[102:103], v[110:111], v[106:107]
	v_pk_fma_f32 v[104:105], v[104:105], v[112:113], v[108:109]
	v_or_b32_e32 v106, v156, v148
	global_store_dwordx4 v[98:99], v[102:105], off
	v_cmp_gt_i32_e32 vcc, s39, v106
	s_nop 0
	v_ashrrev_i32_e32 v102, 31, v106
	v_add_u32_e32 v104, 0xffff8000, v106
	v_cndmask_b32_e32 v103, 0, v102, vcc
	v_cndmask_b32_e32 v102, v104, v106, vcc
	v_cndmask_b32_e32 v105, v144, v145, vcc
	v_cndmask_b32_e32 v104, v146, v147, vcc
	v_lshlrev_b64 v[102:103], 12, v[102:103]
	v_lshl_add_u64 v[102:103], v[104:105], 0, v[102:103]
	v_min_i32_e32 v104, 0x8000, v106
	v_ashrrev_i32_e32 v104, 12, v104
	v_mul_hi_i32_i24_e32 v105, 0x6000, v104
	v_mul_i32_i24_e32 v104, 0x6000, v104
	v_lshl_add_u64 v[102:103], v[102:103], 0, v[96:97]
	v_lshl_add_u64 v[104:105], s[0:1], 0, v[104:105]
	v_lshl_add_u64 v[104:105], v[104:105], 0, v[96:97]
	ds_read_b128 v[106:109], v130 offset:1088
	global_load_dwordx4 v[110:113], v[102:103], off
	global_load_dwordx4 v[114:117], v[104:105], off
	s_waitcnt vmcnt(0) lgkmcnt(0)
	v_pk_fma_f32 v[106:107], v[106:107], v[114:115], v[110:111]
	v_pk_fma_f32 v[108:109], v[108:109], v[116:117], v[112:113]
	v_or_b32_e32 v110, v156, v149
	global_store_dwordx4 v[102:103], v[106:109], off
	v_cmp_gt_i32_e32 vcc, s39, v110
	s_nop 0
	v_ashrrev_i32_e32 v106, 31, v110
	v_add_u32_e32 v108, 0xffff8000, v110
	v_cndmask_b32_e32 v107, 0, v106, vcc
	v_cndmask_b32_e32 v106, v108, v110, vcc
	v_cndmask_b32_e32 v109, v144, v145, vcc
	v_cndmask_b32_e32 v108, v146, v147, vcc
	v_lshlrev_b64 v[106:107], 12, v[106:107]
	v_lshl_add_u64 v[106:107], v[108:109], 0, v[106:107]
	v_min_i32_e32 v108, 0x8000, v110
	v_ashrrev_i32_e32 v108, 12, v108
	v_mul_hi_i32_i24_e32 v109, 0x6000, v108
	v_mul_i32_i24_e32 v108, 0x6000, v108
	v_lshl_add_u64 v[106:107], v[106:107], 0, v[96:97]
	v_lshl_add_u64 v[108:109], s[0:1], 0, v[108:109]
	v_lshl_add_u64 v[108:109], v[108:109], 0, v[96:97]
	ds_read_b128 v[110:113], v130 offset:2176
	global_load_dwordx4 v[114:117], v[106:107], off
	global_load_dwordx4 v[118:121], v[108:109], off
	s_waitcnt vmcnt(0) lgkmcnt(0)
	v_pk_fma_f32 v[110:111], v[110:111], v[118:119], v[114:115]
	v_pk_fma_f32 v[112:113], v[112:113], v[120:121], v[116:117]
	v_or_b32_e32 v114, v156, v150
	global_store_dwordx4 v[106:107], v[110:113], off
	v_cmp_gt_i32_e32 vcc, s39, v114
	s_nop 0
	v_ashrrev_i32_e32 v110, 31, v114
	v_add_u32_e32 v112, 0xffff8000, v114
	v_cndmask_b32_e32 v111, 0, v110, vcc
	v_cndmask_b32_e32 v110, v112, v114, vcc
	v_cndmask_b32_e32 v113, v144, v145, vcc
	v_cndmask_b32_e32 v112, v146, v147, vcc
	v_lshlrev_b64 v[110:111], 12, v[110:111]
	v_lshl_add_u64 v[110:111], v[112:113], 0, v[110:111]
	v_min_i32_e32 v112, 0x8000, v114
	v_ashrrev_i32_e32 v112, 12, v112
	v_mul_hi_i32_i24_e32 v113, 0x6000, v112
	v_mul_i32_i24_e32 v112, 0x6000, v112
	v_lshl_add_u64 v[110:111], v[110:111], 0, v[96:97]
	v_lshl_add_u64 v[112:113], s[0:1], 0, v[112:113]
	v_lshl_add_u64 v[112:113], v[112:113], 0, v[96:97]
	ds_read_b128 v[114:117], v130 offset:3264
	global_load_dwordx4 v[118:121], v[110:111], off
	global_load_dwordx4 v[122:125], v[112:113], off
	s_waitcnt vmcnt(0) lgkmcnt(0)
	v_pk_fma_f32 v[114:115], v[114:115], v[122:123], v[118:119]
	v_pk_fma_f32 v[116:117], v[116:117], v[124:125], v[120:121]
	v_or_b32_e32 v118, v156, v151
	global_store_dwordx4 v[110:111], v[114:117], off
	v_cmp_gt_i32_e32 vcc, s39, v118
	s_nop 0
	v_ashrrev_i32_e32 v114, 31, v118
	v_add_u32_e32 v116, 0xffff8000, v118
	v_cndmask_b32_e32 v115, 0, v114, vcc
	v_cndmask_b32_e32 v114, v116, v118, vcc
	v_cndmask_b32_e32 v117, v144, v145, vcc
	v_cndmask_b32_e32 v116, v146, v147, vcc
	v_lshlrev_b64 v[114:115], 12, v[114:115]
	v_lshl_add_u64 v[114:115], v[116:117], 0, v[114:115]
	v_min_i32_e32 v116, 0x8000, v118
	v_ashrrev_i32_e32 v116, 12, v116
	v_mul_hi_i32_i24_e32 v117, 0x6000, v116
	v_mul_i32_i24_e32 v116, 0x6000, v116
	v_lshl_add_u64 v[114:115], v[114:115], 0, v[96:97]
	v_lshl_add_u64 v[116:117], s[0:1], 0, v[116:117]
	v_lshl_add_u64 v[116:117], v[116:117], 0, v[96:97]
	ds_read_b128 v[118:121], v130 offset:4352
	global_load_dwordx4 v[122:125], v[114:115], off
	global_load_dwordx4 v[126:129], v[116:117], off
	s_waitcnt vmcnt(0) lgkmcnt(0)
	v_pk_fma_f32 v[118:119], v[118:119], v[126:127], v[122:123]
	v_pk_fma_f32 v[120:121], v[120:121], v[128:129], v[124:125]
	v_or_b32_e32 v122, v156, v152
	global_store_dwordx4 v[114:115], v[118:121], off
	v_cmp_gt_i32_e32 vcc, s39, v122
	s_nop 0
	v_ashrrev_i32_e32 v118, 31, v122
	v_add_u32_e32 v120, 0xffff8000, v122
	v_cndmask_b32_e32 v119, 0, v118, vcc
	v_cndmask_b32_e32 v118, v120, v122, vcc
	v_cndmask_b32_e32 v121, v144, v145, vcc
	v_cndmask_b32_e32 v120, v146, v147, vcc
	v_lshlrev_b64 v[118:119], 12, v[118:119]
	v_lshl_add_u64 v[118:119], v[120:121], 0, v[118:119]
	v_min_i32_e32 v120, 0x8000, v122
	v_ashrrev_i32_e32 v120, 12, v120
	v_mul_hi_i32_i24_e32 v121, 0x6000, v120
	v_mul_i32_i24_e32 v120, 0x6000, v120
	v_lshl_add_u64 v[118:119], v[118:119], 0, v[96:97]
	v_lshl_add_u64 v[120:121], s[0:1], 0, v[120:121]
	v_lshl_add_u64 v[120:121], v[120:121], 0, v[96:97]
	ds_read_b128 v[122:125], v130 offset:5440
	global_load_dwordx4 v[126:129], v[118:119], off
	global_load_dwordx4 v[158:161], v[120:121], off
	s_waitcnt vmcnt(0) lgkmcnt(0)
	v_pk_fma_f32 v[122:123], v[122:123], v[158:159], v[126:127]
	v_pk_fma_f32 v[124:125], v[124:125], v[160:161], v[128:129]
	v_or_b32_e32 v126, v156, v153
	global_store_dwordx4 v[118:119], v[122:125], off
	v_cmp_gt_i32_e32 vcc, s39, v126
	s_nop 0
	v_ashrrev_i32_e32 v122, 31, v126
	v_add_u32_e32 v124, 0xffff8000, v126
	v_cndmask_b32_e32 v123, 0, v122, vcc
	v_cndmask_b32_e32 v122, v124, v126, vcc
	v_cndmask_b32_e32 v125, v144, v145, vcc
	v_cndmask_b32_e32 v124, v146, v147, vcc
	v_lshlrev_b64 v[122:123], 12, v[122:123]
	v_lshl_add_u64 v[122:123], v[124:125], 0, v[122:123]
	v_min_i32_e32 v124, 0x8000, v126
	v_ashrrev_i32_e32 v124, 12, v124
	v_mul_hi_i32_i24_e32 v125, 0x6000, v124
	v_mul_i32_i24_e32 v124, 0x6000, v124
	v_lshl_add_u64 v[122:123], v[122:123], 0, v[96:97]
	v_lshl_add_u64 v[124:125], s[0:1], 0, v[124:125]
	v_lshl_add_u64 v[124:125], v[124:125], 0, v[96:97]
	ds_read_b128 v[126:129], v130 offset:6528
	global_load_dwordx4 v[158:161], v[122:123], off
	global_load_dwordx4 v[162:165], v[124:125], off
	v_cmp_gt_i32_e32 vcc, s39, v157
	s_waitcnt vmcnt(0) lgkmcnt(0)
	v_pk_fma_f32 v[126:127], v[126:127], v[162:163], v[158:159]
	v_pk_fma_f32 v[128:129], v[128:129], v[164:165], v[160:161]
	global_store_dwordx4 v[122:123], v[126:129], off
	ds_read_b128 v[158:161], v130 offset:7616
	s_nop 0
	v_ashrrev_i32_e32 v126, 31, v157
	v_add_u32_e32 v128, 0xffff8000, v157
	v_cndmask_b32_e32 v127, 0, v126, vcc
	v_cndmask_b32_e32 v126, v128, v157, vcc
	v_cndmask_b32_e32 v129, v144, v145, vcc
	v_cndmask_b32_e32 v128, v146, v147, vcc
	v_lshlrev_b64 v[126:127], 12, v[126:127]
	v_lshl_add_u64 v[126:127], v[128:129], 0, v[126:127]
	v_min_i32_e32 v128, 0x8000, v157
	v_ashrrev_i32_e32 v128, 12, v128
	v_mul_hi_i32_i24_e32 v129, 0x6000, v128
	v_mul_i32_i24_e32 v128, 0x6000, v128
	v_lshl_add_u64 v[126:127], v[126:127], 0, v[96:97]
	v_lshl_add_u64 v[128:129], s[0:1], 0, v[128:129]
	v_lshl_add_u64 v[128:129], v[128:129], 0, v[96:97]
	global_load_dwordx4 v[162:165], v[126:127], off
	global_load_dwordx4 v[166:169], v[128:129], off
	s_waitcnt vmcnt(0) lgkmcnt(0)
	v_pk_fma_f32 v[158:159], v[158:159], v[166:167], v[162:163]
	v_pk_fma_f32 v[160:161], v[160:161], v[168:169], v[164:165]
	global_store_dwordx4 v[126:127], v[158:161], off
	s_waitcnt lgkmcnt(0)
	ds_write2_b32 v131, v80, v81 offset1:68
	ds_write2_b32 v132, v64, v65 offset0:32 offset1:100
	ds_write2_b32 v131, v82, v83 offset0:136 offset1:204
	ds_write2_b32 v132, v66, v67 offset0:168 offset1:236
	ds_write2_b32 v133, v84, v85 offset0:32 offset1:100
	ds_write2_b32 v134, v68, v69 offset0:64 offset1:132
	ds_write2_b32 v133, v86, v87 offset0:168 offset1:236
	ds_write2_b32 v135, v70, v71 offset0:72 offset1:140
	ds_write2_b32 v136, v88, v89 offset0:64 offset1:132
	ds_write2_b32 v137, v72, v73 offset0:96 offset1:164
	ds_write2_b32 v138, v90, v91 offset0:72 offset1:140
	ds_write2_b32 v139, v74, v75 offset0:104 offset1:172
	ds_write2_b32 v140, v92, v93 offset0:96 offset1:164
	ds_write2_b32 v141, v76, v77 offset0:128 offset1:196
	ds_write2_b32 v142, v94, v95 offset0:104 offset1:172
	ds_write2_b32 v143, v78, v79 offset0:8 offset1:76
	s_waitcnt lgkmcnt(0)
	ds_read_b128 v[64:67], v130
	global_load_dwordx4 v[68:71], v[98:99], off offset:256
	global_load_dwordx4 v[72:75], v[100:101], off offset:256
	s_waitcnt vmcnt(0) lgkmcnt(0)
	v_pk_fma_f32 v[64:65], v[64:65], v[72:73], v[68:69]
	v_pk_fma_f32 v[66:67], v[66:67], v[74:75], v[70:71]
	global_store_dwordx4 v[98:99], v[64:67], off offset:256
	ds_read_b128 v[64:67], v130 offset:1088
	global_load_dwordx4 v[68:71], v[102:103], off offset:256
	global_load_dwordx4 v[72:75], v[104:105], off offset:256
	s_waitcnt vmcnt(0) lgkmcnt(0)
	v_pk_fma_f32 v[64:65], v[64:65], v[72:73], v[68:69]
	v_pk_fma_f32 v[66:67], v[66:67], v[74:75], v[70:71]
	global_store_dwordx4 v[102:103], v[64:67], off offset:256
	ds_read_b128 v[64:67], v130 offset:2176
	global_load_dwordx4 v[68:71], v[106:107], off offset:256
	global_load_dwordx4 v[72:75], v[108:109], off offset:256
	s_waitcnt vmcnt(0) lgkmcnt(0)
	v_pk_fma_f32 v[64:65], v[64:65], v[72:73], v[68:69]
	v_pk_fma_f32 v[66:67], v[66:67], v[74:75], v[70:71]
	global_store_dwordx4 v[106:107], v[64:67], off offset:256
	ds_read_b128 v[64:67], v130 offset:3264
	global_load_dwordx4 v[68:71], v[110:111], off offset:256
	global_load_dwordx4 v[72:75], v[112:113], off offset:256
	s_waitcnt vmcnt(0) lgkmcnt(0)
	v_pk_fma_f32 v[64:65], v[64:65], v[72:73], v[68:69]
	v_pk_fma_f32 v[66:67], v[66:67], v[74:75], v[70:71]
	global_store_dwordx4 v[110:111], v[64:67], off offset:256
	ds_read_b128 v[64:67], v130 offset:4352
	global_load_dwordx4 v[68:71], v[114:115], off offset:256
	global_load_dwordx4 v[72:75], v[116:117], off offset:256
	s_waitcnt vmcnt(0) lgkmcnt(0)
	v_pk_fma_f32 v[64:65], v[64:65], v[72:73], v[68:69]
	v_pk_fma_f32 v[66:67], v[66:67], v[74:75], v[70:71]
	global_store_dwordx4 v[114:115], v[64:67], off offset:256
	ds_read_b128 v[64:67], v130 offset:5440
	global_load_dwordx4 v[68:71], v[118:119], off offset:256
	global_load_dwordx4 v[72:75], v[120:121], off offset:256
	s_waitcnt vmcnt(0) lgkmcnt(0)
	v_pk_fma_f32 v[64:65], v[64:65], v[72:73], v[68:69]
	v_pk_fma_f32 v[66:67], v[66:67], v[74:75], v[70:71]
	global_store_dwordx4 v[118:119], v[64:67], off offset:256
	ds_read_b128 v[64:67], v130 offset:6528
	global_load_dwordx4 v[68:71], v[122:123], off offset:256
	global_load_dwordx4 v[72:75], v[124:125], off offset:256
	s_waitcnt vmcnt(0) lgkmcnt(0)
	v_pk_fma_f32 v[64:65], v[64:65], v[72:73], v[68:69]
	v_pk_fma_f32 v[66:67], v[66:67], v[74:75], v[70:71]
	global_store_dwordx4 v[122:123], v[64:67], off offset:256
	ds_read_b128 v[64:67], v130 offset:7616
	global_load_dwordx4 v[68:71], v[126:127], off offset:256
	global_load_dwordx4 v[72:75], v[128:129], off offset:256
	s_waitcnt vmcnt(0) lgkmcnt(0)
	v_pk_fma_f32 v[64:65], v[64:65], v[72:73], v[68:69]
	v_pk_fma_f32 v[66:67], v[66:67], v[74:75], v[70:71]
	global_store_dwordx4 v[126:127], v[64:67], off offset:256
	s_waitcnt lgkmcnt(0)
	ds_write2_b32 v131, v48, v49 offset1:68
	ds_write2_b32 v132, v32, v33 offset0:32 offset1:100
	ds_write2_b32 v131, v50, v51 offset0:136 offset1:204
	ds_write2_b32 v132, v34, v35 offset0:168 offset1:236
	ds_write2_b32 v133, v52, v53 offset0:32 offset1:100
	ds_write2_b32 v134, v36, v37 offset0:64 offset1:132
	ds_write2_b32 v133, v54, v55 offset0:168 offset1:236
	ds_write2_b32 v135, v38, v39 offset0:72 offset1:140
	ds_write2_b32 v136, v56, v57 offset0:64 offset1:132
	ds_write2_b32 v137, v40, v41 offset0:96 offset1:164
	ds_write2_b32 v138, v58, v59 offset0:72 offset1:140
	ds_write2_b32 v139, v42, v43 offset0:104 offset1:172
	ds_write2_b32 v140, v60, v61 offset0:96 offset1:164
	ds_write2_b32 v141, v44, v45 offset0:128 offset1:196
	ds_write2_b32 v142, v62, v63 offset0:104 offset1:172
	ds_write2_b32 v143, v46, v47 offset0:8 offset1:76
	v_or_b32_e32 v64, 32, v156
	v_or_b32_e32 v36, v64, v155
	v_cmp_gt_i32_e32 vcc, s39, v36
	v_ashrrev_i32_e32 v32, 31, v36
	v_add_u32_e32 v34, 0xffff8000, v36
	v_cndmask_b32_e32 v33, 0, v32, vcc
	v_cndmask_b32_e32 v32, v34, v36, vcc
	v_cndmask_b32_e32 v35, v144, v145, vcc
	v_cndmask_b32_e32 v34, v146, v147, vcc
	v_lshlrev_b64 v[32:33], 12, v[32:33]
	v_lshl_add_u64 v[32:33], v[34:35], 0, v[32:33]
	v_min_i32_e32 v34, 0x8000, v36
	v_ashrrev_i32_e32 v34, 12, v34
	v_mul_hi_i32_i24_e32 v35, 0x6000, v34
	v_mul_i32_i24_e32 v34, 0x6000, v34
	s_waitcnt lgkmcnt(0)
	v_lshl_add_u64 v[32:33], v[32:33], 0, v[96:97]
	v_lshl_add_u64 v[34:35], s[0:1], 0, v[34:35]
	v_lshl_add_u64 v[34:35], v[34:35], 0, v[96:97]
	ds_read_b128 v[36:39], v130
	global_load_dwordx4 v[40:43], v[32:33], off
	global_load_dwordx4 v[44:47], v[34:35], off
	s_waitcnt vmcnt(0) lgkmcnt(0)
	v_pk_fma_f32 v[36:37], v[36:37], v[44:45], v[40:41]
	v_pk_fma_f32 v[38:39], v[38:39], v[46:47], v[42:43]
	v_or_b32_e32 v40, v64, v148
	global_store_dwordx4 v[32:33], v[36:39], off
	v_cmp_gt_i32_e32 vcc, s39, v40
	s_nop 0
	v_ashrrev_i32_e32 v36, 31, v40
	v_add_u32_e32 v38, 0xffff8000, v40
	v_cndmask_b32_e32 v37, 0, v36, vcc
	v_cndmask_b32_e32 v36, v38, v40, vcc
	v_cndmask_b32_e32 v39, v144, v145, vcc
	v_cndmask_b32_e32 v38, v146, v147, vcc
	v_lshlrev_b64 v[36:37], 12, v[36:37]
	v_lshl_add_u64 v[36:37], v[38:39], 0, v[36:37]
	v_min_i32_e32 v38, 0x8000, v40
	v_ashrrev_i32_e32 v38, 12, v38
	v_mul_hi_i32_i24_e32 v39, 0x6000, v38
	v_mul_i32_i24_e32 v38, 0x6000, v38
	v_lshl_add_u64 v[36:37], v[36:37], 0, v[96:97]
	v_lshl_add_u64 v[38:39], s[0:1], 0, v[38:39]
	v_lshl_add_u64 v[38:39], v[38:39], 0, v[96:97]
	ds_read_b128 v[40:43], v130 offset:1088
	global_load_dwordx4 v[44:47], v[36:37], off
	global_load_dwordx4 v[48:51], v[38:39], off
	s_waitcnt vmcnt(0) lgkmcnt(0)
	v_pk_fma_f32 v[40:41], v[40:41], v[48:49], v[44:45]
	v_pk_fma_f32 v[42:43], v[42:43], v[50:51], v[46:47]
	v_or_b32_e32 v44, v64, v149
	global_store_dwordx4 v[36:37], v[40:43], off
	v_cmp_gt_i32_e32 vcc, s39, v44
	s_nop 0
	v_ashrrev_i32_e32 v40, 31, v44
	v_add_u32_e32 v42, 0xffff8000, v44
	v_cndmask_b32_e32 v41, 0, v40, vcc
	v_cndmask_b32_e32 v40, v42, v44, vcc
	v_cndmask_b32_e32 v43, v144, v145, vcc
	v_cndmask_b32_e32 v42, v146, v147, vcc
	v_lshlrev_b64 v[40:41], 12, v[40:41]
	v_lshl_add_u64 v[40:41], v[42:43], 0, v[40:41]
	v_min_i32_e32 v42, 0x8000, v44
	v_ashrrev_i32_e32 v42, 12, v42
	v_mul_hi_i32_i24_e32 v43, 0x6000, v42
	v_mul_i32_i24_e32 v42, 0x6000, v42
	v_lshl_add_u64 v[40:41], v[40:41], 0, v[96:97]
	v_lshl_add_u64 v[42:43], s[0:1], 0, v[42:43]
	v_lshl_add_u64 v[42:43], v[42:43], 0, v[96:97]
	ds_read_b128 v[44:47], v130 offset:2176
	global_load_dwordx4 v[48:51], v[40:41], off
	global_load_dwordx4 v[52:55], v[42:43], off
	s_waitcnt vmcnt(0) lgkmcnt(0)
	v_pk_fma_f32 v[44:45], v[44:45], v[52:53], v[48:49]
	v_pk_fma_f32 v[46:47], v[46:47], v[54:55], v[50:51]
	v_or_b32_e32 v48, v64, v150
	global_store_dwordx4 v[40:41], v[44:47], off
	v_cmp_gt_i32_e32 vcc, s39, v48
	s_nop 0
	v_ashrrev_i32_e32 v44, 31, v48
	v_add_u32_e32 v46, 0xffff8000, v48
	v_cndmask_b32_e32 v45, 0, v44, vcc
	v_cndmask_b32_e32 v44, v46, v48, vcc
	v_cndmask_b32_e32 v47, v144, v145, vcc
	v_cndmask_b32_e32 v46, v146, v147, vcc
	v_lshlrev_b64 v[44:45], 12, v[44:45]
	v_lshl_add_u64 v[44:45], v[46:47], 0, v[44:45]
	v_min_i32_e32 v46, 0x8000, v48
	v_ashrrev_i32_e32 v46, 12, v46
	v_mul_hi_i32_i24_e32 v47, 0x6000, v46
	v_mul_i32_i24_e32 v46, 0x6000, v46
	v_lshl_add_u64 v[44:45], v[44:45], 0, v[96:97]
	v_lshl_add_u64 v[46:47], s[0:1], 0, v[46:47]
	v_lshl_add_u64 v[46:47], v[46:47], 0, v[96:97]
	ds_read_b128 v[48:51], v130 offset:3264
	global_load_dwordx4 v[52:55], v[44:45], off
	global_load_dwordx4 v[56:59], v[46:47], off
	s_waitcnt vmcnt(0) lgkmcnt(0)
	v_pk_fma_f32 v[48:49], v[48:49], v[56:57], v[52:53]
	v_pk_fma_f32 v[50:51], v[50:51], v[58:59], v[54:55]
	v_or_b32_e32 v52, v64, v151
	global_store_dwordx4 v[44:45], v[48:51], off
	v_cmp_gt_i32_e32 vcc, s39, v52
	s_nop 0
	v_ashrrev_i32_e32 v48, 31, v52
	v_add_u32_e32 v50, 0xffff8000, v52
	v_cndmask_b32_e32 v49, 0, v48, vcc
	v_cndmask_b32_e32 v48, v50, v52, vcc
	v_cndmask_b32_e32 v51, v144, v145, vcc
	v_cndmask_b32_e32 v50, v146, v147, vcc
	v_lshlrev_b64 v[48:49], 12, v[48:49]
	v_lshl_add_u64 v[48:49], v[50:51], 0, v[48:49]
	v_min_i32_e32 v50, 0x8000, v52
	v_ashrrev_i32_e32 v50, 12, v50
	v_mul_hi_i32_i24_e32 v51, 0x6000, v50
	v_mul_i32_i24_e32 v50, 0x6000, v50
	v_lshl_add_u64 v[48:49], v[48:49], 0, v[96:97]
	v_lshl_add_u64 v[50:51], s[0:1], 0, v[50:51]
	v_lshl_add_u64 v[50:51], v[50:51], 0, v[96:97]
	ds_read_b128 v[52:55], v130 offset:4352
	global_load_dwordx4 v[56:59], v[48:49], off
	global_load_dwordx4 v[60:63], v[50:51], off
	s_waitcnt vmcnt(0) lgkmcnt(0)
	v_pk_fma_f32 v[52:53], v[52:53], v[60:61], v[56:57]
	v_pk_fma_f32 v[54:55], v[54:55], v[62:63], v[58:59]
	v_or_b32_e32 v56, v64, v152
	global_store_dwordx4 v[48:49], v[52:55], off
	v_cmp_gt_i32_e32 vcc, s39, v56
	s_nop 0
	v_ashrrev_i32_e32 v52, 31, v56
	v_add_u32_e32 v54, 0xffff8000, v56
	v_cndmask_b32_e32 v53, 0, v52, vcc
	v_cndmask_b32_e32 v52, v54, v56, vcc
	v_cndmask_b32_e32 v55, v144, v145, vcc
	v_cndmask_b32_e32 v54, v146, v147, vcc
	v_lshlrev_b64 v[52:53], 12, v[52:53]
	v_lshl_add_u64 v[52:53], v[54:55], 0, v[52:53]
	v_min_i32_e32 v54, 0x8000, v56
	v_ashrrev_i32_e32 v54, 12, v54
	v_mul_hi_i32_i24_e32 v55, 0x6000, v54
	v_mul_i32_i24_e32 v54, 0x6000, v54
	v_lshl_add_u64 v[52:53], v[52:53], 0, v[96:97]
	v_lshl_add_u64 v[54:55], s[0:1], 0, v[54:55]
	v_lshl_add_u64 v[54:55], v[54:55], 0, v[96:97]
	ds_read_b128 v[56:59], v130 offset:5440
	global_load_dwordx4 v[60:63], v[52:53], off
	global_load_dwordx4 v[66:69], v[54:55], off
	s_waitcnt vmcnt(0) lgkmcnt(0)
	v_pk_fma_f32 v[56:57], v[56:57], v[66:67], v[60:61]
	v_pk_fma_f32 v[58:59], v[58:59], v[68:69], v[62:63]
	v_or_b32_e32 v60, v64, v153
	global_store_dwordx4 v[52:53], v[56:59], off
	v_cmp_gt_i32_e32 vcc, s39, v60
	v_or_b32_e32 v64, v64, v154
	v_ashrrev_i32_e32 v56, 31, v60
	v_add_u32_e32 v58, 0xffff8000, v60
	v_cndmask_b32_e32 v57, 0, v56, vcc
	v_cndmask_b32_e32 v56, v58, v60, vcc
	v_cndmask_b32_e32 v59, v144, v145, vcc
	v_cndmask_b32_e32 v58, v146, v147, vcc
	v_lshlrev_b64 v[56:57], 12, v[56:57]
	v_lshl_add_u64 v[56:57], v[58:59], 0, v[56:57]
	v_min_i32_e32 v58, 0x8000, v60
	v_ashrrev_i32_e32 v58, 12, v58
	v_mul_hi_i32_i24_e32 v59, 0x6000, v58
	v_mul_i32_i24_e32 v58, 0x6000, v58
	v_lshl_add_u64 v[56:57], v[56:57], 0, v[96:97]
	v_lshl_add_u64 v[58:59], s[0:1], 0, v[58:59]
	v_lshl_add_u64 v[58:59], v[58:59], 0, v[96:97]
	ds_read_b128 v[60:63], v130 offset:6528
	global_load_dwordx4 v[66:69], v[56:57], off
	global_load_dwordx4 v[70:73], v[58:59], off
	v_cmp_gt_i32_e32 vcc, s39, v64
	s_waitcnt vmcnt(0) lgkmcnt(0)
	v_pk_fma_f32 v[60:61], v[60:61], v[70:71], v[66:67]
	v_pk_fma_f32 v[62:63], v[62:63], v[72:73], v[68:69]
	global_store_dwordx4 v[56:57], v[60:63], off
	s_nop 1
	v_ashrrev_i32_e32 v60, 31, v64
	v_add_u32_e32 v62, 0xffff8000, v64
	v_cndmask_b32_e32 v61, 0, v60, vcc
	v_cndmask_b32_e32 v60, v62, v64, vcc
	v_cndmask_b32_e32 v63, v144, v145, vcc
	v_cndmask_b32_e32 v62, v146, v147, vcc
	v_lshlrev_b64 v[60:61], 12, v[60:61]
	v_lshl_add_u64 v[60:61], v[62:63], 0, v[60:61]
	v_min_i32_e32 v62, 0x8000, v64
	v_ashrrev_i32_e32 v62, 12, v62
	v_mul_hi_i32_i24_e32 v63, 0x6000, v62
	v_mul_i32_i24_e32 v62, 0x6000, v62
	v_lshl_add_u64 v[60:61], v[60:61], 0, v[96:97]
	v_lshl_add_u64 v[62:63], s[0:1], 0, v[62:63]
	v_lshl_add_u64 v[62:63], v[62:63], 0, v[96:97]
	ds_read_b128 v[64:67], v130 offset:7616
	global_load_dwordx4 v[68:71], v[60:61], off
	global_load_dwordx4 v[72:75], v[62:63], off
	s_waitcnt vmcnt(0) lgkmcnt(0)
	v_pk_fma_f32 v[64:65], v[64:65], v[72:73], v[68:69]
	v_pk_fma_f32 v[66:67], v[66:67], v[74:75], v[70:71]
	global_store_dwordx4 v[60:61], v[64:67], off
	s_waitcnt lgkmcnt(0)
	ds_write2_b32 v131, v16, v17 offset1:68
	ds_write2_b32 v132, v0, v1 offset0:32 offset1:100
	ds_write2_b32 v131, v18, v19 offset0:136 offset1:204
	ds_write2_b32 v132, v2, v3 offset0:168 offset1:236
	ds_write2_b32 v133, v20, v21 offset0:32 offset1:100
	ds_write2_b32 v134, v4, v5 offset0:64 offset1:132
	ds_write2_b32 v133, v22, v23 offset0:168 offset1:236
	ds_write2_b32 v135, v6, v7 offset0:72 offset1:140
	ds_write2_b32 v136, v24, v25 offset0:64 offset1:132
	ds_write2_b32 v137, v8, v9 offset0:96 offset1:164
	ds_write2_b32 v138, v26, v27 offset0:72 offset1:140
	ds_write2_b32 v139, v10, v11 offset0:104 offset1:172
	ds_write2_b32 v140, v28, v29 offset0:96 offset1:164
	ds_write2_b32 v141, v12, v13 offset0:128 offset1:196
	ds_write2_b32 v142, v30, v31 offset0:104 offset1:172
	ds_write2_b32 v143, v14, v15 offset0:8 offset1:76
	s_waitcnt lgkmcnt(0)
	ds_read_b128 v[0:3], v130
	global_load_dwordx4 v[4:7], v[32:33], off offset:256
	global_load_dwordx4 v[8:11], v[34:35], off offset:256
	s_waitcnt vmcnt(0) lgkmcnt(0)
	v_pk_fma_f32 v[0:1], v[0:1], v[8:9], v[4:5]
	v_pk_fma_f32 v[2:3], v[2:3], v[10:11], v[6:7]
	global_store_dwordx4 v[32:33], v[0:3], off offset:256
	ds_read_b128 v[0:3], v130 offset:1088
	global_load_dwordx4 v[4:7], v[36:37], off offset:256
	global_load_dwordx4 v[8:11], v[38:39], off offset:256
	s_waitcnt vmcnt(0) lgkmcnt(0)
	v_pk_fma_f32 v[0:1], v[0:1], v[8:9], v[4:5]
	v_pk_fma_f32 v[2:3], v[2:3], v[10:11], v[6:7]
	global_store_dwordx4 v[36:37], v[0:3], off offset:256
	ds_read_b128 v[0:3], v130 offset:2176
	global_load_dwordx4 v[4:7], v[40:41], off offset:256
	global_load_dwordx4 v[8:11], v[42:43], off offset:256
	s_waitcnt vmcnt(0) lgkmcnt(0)
	v_pk_fma_f32 v[0:1], v[0:1], v[8:9], v[4:5]
	v_pk_fma_f32 v[2:3], v[2:3], v[10:11], v[6:7]
	global_store_dwordx4 v[40:41], v[0:3], off offset:256
	ds_read_b128 v[0:3], v130 offset:3264
	global_load_dwordx4 v[4:7], v[44:45], off offset:256
	global_load_dwordx4 v[8:11], v[46:47], off offset:256
	s_waitcnt vmcnt(0) lgkmcnt(0)
	v_pk_fma_f32 v[0:1], v[0:1], v[8:9], v[4:5]
	v_pk_fma_f32 v[2:3], v[2:3], v[10:11], v[6:7]
	global_store_dwordx4 v[44:45], v[0:3], off offset:256
	ds_read_b128 v[0:3], v130 offset:4352
	global_load_dwordx4 v[4:7], v[48:49], off offset:256
	global_load_dwordx4 v[8:11], v[50:51], off offset:256
	s_waitcnt vmcnt(0) lgkmcnt(0)
	v_pk_fma_f32 v[0:1], v[0:1], v[8:9], v[4:5]
	v_pk_fma_f32 v[2:3], v[2:3], v[10:11], v[6:7]
	global_store_dwordx4 v[48:49], v[0:3], off offset:256
	ds_read_b128 v[0:3], v130 offset:5440
	global_load_dwordx4 v[4:7], v[52:53], off offset:256
	global_load_dwordx4 v[8:11], v[54:55], off offset:256
	s_waitcnt vmcnt(0) lgkmcnt(0)
	v_pk_fma_f32 v[0:1], v[0:1], v[8:9], v[4:5]
	v_pk_fma_f32 v[2:3], v[2:3], v[10:11], v[6:7]
	global_store_dwordx4 v[52:53], v[0:3], off offset:256
	ds_read_b128 v[0:3], v130 offset:6528
	global_load_dwordx4 v[4:7], v[56:57], off offset:256
	global_load_dwordx4 v[8:11], v[58:59], off offset:256
	s_waitcnt vmcnt(0) lgkmcnt(0)
	v_pk_fma_f32 v[0:1], v[0:1], v[8:9], v[4:5]
	v_pk_fma_f32 v[2:3], v[2:3], v[10:11], v[6:7]
	global_store_dwordx4 v[56:57], v[0:3], off offset:256
	ds_read_b128 v[0:3], v130 offset:7616
	global_load_dwordx4 v[4:7], v[60:61], off offset:256
	global_load_dwordx4 v[8:11], v[62:63], off offset:256
	s_waitcnt vmcnt(0) lgkmcnt(0)
	v_pk_fma_f32 v[0:1], v[0:1], v[8:9], v[4:5]
	v_pk_fma_f32 v[2:3], v[2:3], v[10:11], v[6:7]
	global_store_dwordx4 v[60:61], v[0:3], off offset:256
	s_waitcnt lgkmcnt(0)
	s_barrier
	s_cbranch_scc1 .LBB0_1086
